# de-serialised gate loads in mem-attn and diff-attn unit epilogues (prefetch into dead VGPRs, counted vmcnt)
# speedup vs baseline: 1.0137x; 1.0137x over previous
; #define SBAR() __builtin_amdgcn_sched_barrier(0)
; #define PK4(P, BASE, OUT) do { u32x4 w = {cvtpk(P[BASE + 0], P[BASE + 1]), cvtpk(P[BASE + 2], P[BASE + 3]), cvtpk(P[BASE + 4], P[BASE + 5]), cvtpk(P[BASE + 6], P[BASE + 7])}; \
;     OUT = *reinterpret_cast<bf16x8*>(&w); } while (0)
; __device__ __forceinline__ void exp_half(f32x16& p) {
; #pragma unroll
;     for (int r = 0; r < 16; ++r) p[r] = __builtin_amdgcn_exp2f(p[r]);
; }
; __device__ __forceinline__ void pack_p(const f32x16& p0, const f32x16& p1, float& l_reg, bf16x8& pa0, bf16x8& pa1, bf16x8& pa2, bf16x8& pa3) {
;     float ps = 0;
; #pragma unroll
;     for (int r = 0; r < 16; ++r) ps += p0[r];
; #pragma unroll
;     for (int r = 0; r < 16; ++r) ps += p1[r];
;     l_reg += ps;
;     ...
;     PK4(p0, 0, pa0); PK4(p0, 8, pa1); PK4(p1, 0, pa2); PK4(p1, 8, pa3);
;     ...
; }
; template <int ND0> __device__ __forceinline__ void qkt(f32x16& p0, f32x16& p1, const char* Ks, const bf16x8* qr, int r32, int hi, int colB0) {
; #pragma unroll
;     for (int d0 = 0; d0 < ND0; ++d0) { const int cb = colB0 + (d0 * 16 + hi * 8) * 2;
;         const bf16x8 b0 = *reinterpret_cast<const bf16x8*>(Ks + KSWZ(r32, cb));
;         const bf16x8 b1 = *reinterpret_cast<const bf16x8*>(Ks + KSWZ(32 + r32, cb));
;         p0 = __builtin_amdgcn_mfma_f32_32x32x16_bf16(b0, qr[d0], p0, 0, 0, 0);
;         p1 = __builtin_amdgcn_mfma_f32_32x32x16_bf16(b1, qr[d0], p1, 0, 0, 0); }
; }
; __device__ __forceinline__ void mem_unit(const MemArgs& A, int unit, char* lds, int wv) {
;     ...
;     for (int t = 0; t < 4; ++t) {
;         f32x16 p0, p1; bf16x8 pa0, pa1, pa2, pa3;
; #pragma unroll
;         for (int r = 0; r < 16; ++r) { p0[r] = nM2; p1[r] = nM2; }
;         qkt<8>(p0, p1, K_lds + t * SHM_K, qr, r32, hi, 0);
;         exp_half(p0); exp_half(p1); pack_p(p0, p1, l_reg, pa0, pa1, pa2, pa3); SBAR();
;         pv_d0(o, vb0 + t * SHM_V, pa0, pa1, pa2, pa3);
.LBB0_200:
	v_add_u32_e32 v84, s2, v156
	v_add_u32_e32 v80, 0x10000, v84
	v_add_u32_e32 v84, 0x12000, v84
	ds_read_b128 v[80:83], v80
	ds_read_b128 v[158:161], v84
	v_add_u32_e32 v157, s2, v155
	s_waitcnt lgkmcnt(1)
	v_mfma_f32_32x32x16_bf16 v[96:111], v[80:83], v[112:115], v[64:79]
	s_waitcnt lgkmcnt(0)
	v_mfma_f32_32x32x16_bf16 v[80:95], v[158:161], v[112:115], v[64:79]
	v_add_u32_e32 v158, 0x10000, v157
	ds_read_b128 v[158:161], v158
	v_add_u32_e32 v157, 0x12000, v157
	ds_read_b128 v[162:165], v157
	v_add_u32_e32 v157, s2, v154
	s_waitcnt lgkmcnt(1)
	v_mfma_f32_32x32x16_bf16 v[96:111], v[158:161], v[116:119], v[96:111]
	v_add_u32_e32 v158, 0x10000, v157
	ds_read_b128 v[158:161], v158
	v_add_u32_e32 v157, 0x12000, v157
	s_waitcnt lgkmcnt(1)
	v_mfma_f32_32x32x16_bf16 v[80:95], v[162:165], v[116:119], v[80:95]
	ds_read_b128 v[162:165], v157
	v_add_u32_e32 v157, s2, v153
	s_waitcnt lgkmcnt(1)
	v_mfma_f32_32x32x16_bf16 v[96:111], v[158:161], v[120:123], v[96:111]
	v_add_u32_e32 v158, 0x10000, v157
	ds_read_b128 v[158:161], v158
	v_add_u32_e32 v157, 0x12000, v157
	s_waitcnt lgkmcnt(1)
	v_mfma_f32_32x32x16_bf16 v[80:95], v[162:165], v[120:123], v[80:95]
	ds_read_b128 v[162:165], v157
	v_add_u32_e32 v157, s2, v152
	s_waitcnt lgkmcnt(1)
	v_mfma_f32_32x32x16_bf16 v[96:111], v[158:161], v[124:127], v[96:111]
	v_add_u32_e32 v158, 0x10000, v157
	ds_read_b128 v[158:161], v158
	v_add_u32_e32 v157, 0x12000, v157
	s_waitcnt lgkmcnt(1)
	v_mfma_f32_32x32x16_bf16 v[80:95], v[162:165], v[124:127], v[80:95]
	ds_read_b128 v[162:165], v157
	v_add_u32_e32 v157, s2, v151
	s_waitcnt lgkmcnt(1)
	v_mfma_f32_32x32x16_bf16 v[96:111], v[158:161], v[128:131], v[96:111]
	v_add_u32_e32 v158, 0x10000, v157
	ds_read_b128 v[158:161], v158
	v_add_u32_e32 v157, 0x12000, v157
	s_waitcnt lgkmcnt(1)
	v_mfma_f32_32x32x16_bf16 v[80:95], v[162:165], v[128:131], v[80:95]
	ds_read_b128 v[162:165], v157
	v_add_u32_e32 v157, s2, v150
	s_waitcnt lgkmcnt(1)
	v_mfma_f32_32x32x16_bf16 v[96:111], v[158:161], v[132:135], v[96:111]
	v_add_u32_e32 v158, 0x10000, v157
	ds_read_b128 v[158:161], v158
	v_add_u32_e32 v157, 0x12000, v157
	s_waitcnt lgkmcnt(1)
	v_mfma_f32_32x32x16_bf16 v[80:95], v[162:165], v[132:135], v[80:95]
	ds_read_b128 v[162:165], v157
	v_add_u32_e32 v157, s2, v149
	s_waitcnt lgkmcnt(1)
	v_mfma_f32_32x32x16_bf16 v[96:111], v[158:161], v[136:139], v[96:111]
	v_add_u32_e32 v158, 0x10000, v157
	ds_read_b128 v[158:161], v158
	v_add_u32_e32 v157, 0x12000, v157
	s_waitcnt lgkmcnt(1)
	v_mfma_f32_32x32x16_bf16 v[80:95], v[162:165], v[136:139], v[80:95]
	ds_read_b128 v[162:165], v157
	s_waitcnt lgkmcnt(1)
	v_mfma_f32_32x32x16_bf16 v[96:111], v[158:161], v[140:143], v[96:111]
	s_waitcnt lgkmcnt(0)
	v_mfma_f32_32x32x16_bf16 v[80:95], v[162:165], v[140:143], v[80:95]
	s_nop 9
	v_exp_f32_e32 v96, v96
	v_exp_f32_e32 v97, v97
	v_exp_f32_e32 v98, v98
	v_exp_f32_e32 v99, v99
	v_exp_f32_e32 v100, v100
	v_exp_f32_e32 v101, v101
	v_exp_f32_e32 v102, v102
	v_exp_f32_e32 v157, v80
	v_add_f32_e32 v80, 0, v96
	v_add_f32_e32 v80, v97, v80
	v_add_f32_e32 v80, v98, v80
	v_exp_f32_e32 v103, v103
	v_add_f32_e32 v80, v99, v80
	v_exp_f32_e32 v104, v104
	v_add_f32_e32 v80, v100, v80
	v_exp_f32_e32 v105, v105
	v_add_f32_e32 v80, v101, v80
	v_exp_f32_e32 v106, v106
	v_add_f32_e32 v80, v102, v80
	v_exp_f32_e32 v107, v107
	v_add_f32_e32 v80, v103, v80
	v_exp_f32_e32 v108, v108
	v_add_f32_e32 v80, v104, v80
	v_exp_f32_e32 v109, v109
	v_add_f32_e32 v80, v105, v80
	v_exp_f32_e32 v110, v110
	v_add_f32_e32 v80, v106, v80
	v_exp_f32_e32 v111, v111
	v_add_f32_e32 v80, v107, v80
	v_add_f32_e32 v80, v108, v80
	v_exp_f32_e32 v158, v81
	v_add_f32_e32 v80, v109, v80
	v_exp_f32_e32 v159, v82
	v_add_f32_e32 v80, v110, v80
	v_exp_f32_e32 v160, v83
	v_add_f32_e32 v80, v111, v80
	v_exp_f32_e32 v161, v84
	v_add_f32_e32 v80, v157, v80
	v_exp_f32_e32 v162, v85
	v_add_f32_e32 v80, v158, v80
	v_exp_f32_e32 v163, v86
	v_add_f32_e32 v80, v159, v80
	v_exp_f32_e32 v164, v87
	v_add_f32_e32 v80, v160, v80
	v_exp_f32_e32 v165, v88
	v_add_f32_e32 v80, v161, v80
	v_exp_f32_e32 v166, v89
	v_add_f32_e32 v80, v162, v80
	v_exp_f32_e32 v167, v90
	v_add_f32_e32 v80, v163, v80
	v_exp_f32_e32 v168, v91
	v_add_f32_e32 v80, v164, v80
	v_exp_f32_e32 v169, v92
	v_add_f32_e32 v80, v165, v80
	v_exp_f32_e32 v170, v93
	v_add_f32_e32 v80, v166, v80
	v_exp_f32_e32 v171, v94
	v_add_f32_e32 v80, v167, v80
	v_exp_f32_e32 v95, v95
	v_add_f32_e32 v80, v168, v80
	v_add_f32_e32 v80, v169, v80
	v_add_f32_e32 v80, v170, v80
	v_add_f32_e32 v80, v171, v80
	v_add_f32_e32 v80, v95, v80
	v_add_f32_e32 v148, v148, v80
	v_cvt_pk_bf16_f32 v80, v96, v97
	v_cvt_pk_bf16_f32 v81, v98, v99
	v_cvt_pk_bf16_f32 v82, v100, v101
	v_cvt_pk_bf16_f32 v83, v102, v103
	v_cvt_pk_bf16_f32 v84, v104, v105
	v_cvt_pk_bf16_f32 v85, v106, v107
	v_cvt_pk_bf16_f32 v86, v108, v109
	v_cvt_pk_bf16_f32 v87, v110, v111
	v_cvt_pk_bf16_f32 v88, v157, v158
	v_cvt_pk_bf16_f32 v89, v159, v160
	v_cvt_pk_bf16_f32 v90, v161, v162
	v_cvt_pk_bf16_f32 v91, v163, v164
	v_cvt_pk_bf16_f32 v92, v165, v166
	v_cvt_pk_bf16_f32 v93, v167, v168
	v_cvt_pk_bf16_f32 v94, v169, v170
	v_cvt_pk_bf16_f32 v95, v171, v95
	v_add_u32_e32 v157, s2, v147
	s_setprio 1
	ds_read_b64_tr_b16 v[96:97], v157 offset:0
	ds_read_b64_tr_b16 v[98:99], v157 offset:0x800
	ds_read_b64_tr_b16 v[100:101], v157 offset:0x200
	ds_read_b64_tr_b16 v[102:103], v157 offset:0xa00
	ds_read_b64_tr_b16 v[104:105], v157 offset:0x400
	ds_read_b64_tr_b16 v[106:107], v157 offset:0xc00
	ds_read_b64_tr_b16 v[108:109], v157 offset:0x600
	ds_read_b64_tr_b16 v[110:111], v157 offset:0xe00
	s_waitcnt lgkmcnt(6)
	s_nop 0
	v_mfma_f32_32x32x16_bf16 v[48:63], v[80:83], v[96:99], v[48:63]
	s_waitcnt lgkmcnt(4)
; #define SBAR() __builtin_amdgcn_sched_barrier(0)
; __device__ __forceinline__ int crow(int r, int hi) { return (r & 3) + 8 * (r >> 2) + 4 * hi; }
; __device__ __forceinline__ float bf2f(unsigned short h) { return __uint_as_float(((unsigned)h) << 16); }
; __device__ __forceinline__ float silu(float x) { return x / (1.0f + __expf(-x)); }
; template <int KS> __device__ __forceinline__ void pv_ks(f32x16* o, int vb, bf16x8 pa) {
;     const s16x4 l0 = tr_read<v_rd_off(0, KS, 0)>(vb), h0 = tr_read<v_rd_off(0, KS, 1)>(vb), l1 = tr_read<v_rd_off(1, KS, 0)>(vb), h1 = tr_read<v_rd_off(1, KS, 1)>(vb);
;     const s16x4 l2 = tr_read<v_rd_off(2, KS, 0)>(vb), h2 = tr_read<v_rd_off(2, KS, 1)>(vb), l3 = tr_read<v_rd_off(3, KS, 0)>(vb), h3 = tr_read<v_rd_off(3, KS, 1)>(vb);
;     ...
;     asm volatile("s_waitcnt lgkmcnt(6)" ::: "memory"); SBAR();
;     o[0] = __builtin_amdgcn_mfma_f32_32x32x16_bf16(pa, PK(l0, h0), o[0], 0, 0, 0);
;     asm volatile("s_waitcnt lgkmcnt(4)" ::: "memory"); SBAR();
;     o[1] = __builtin_amdgcn_mfma_f32_32x32x16_bf16(pa, PK(l1, h1), o[1], 0, 0, 0);
;     asm volatile("s_waitcnt lgkmcnt(2)" ::: "memory"); SBAR();
;     o[2] = __builtin_amdgcn_mfma_f32_32x32x16_bf16(pa, PK(l2, h2), o[2], 0, 0, 0);
;     asm volatile("s_waitcnt lgkmcnt(0)" ::: "memory"); SBAR();
;     o[3] = __builtin_amdgcn_mfma_f32_32x32x16_bf16(pa, PK(l3, h3), o[3], 0, 0, 0);
;     ...
; }
; __device__ __forceinline__ void mem_unit(const MemArgs& A, int unit, char* lds, int wv) {
;     ...
;     { auto rr = __builtin_amdgcn_permlane32_swap(__float_as_uint(l_reg), __float_as_uint(l_reg), false, false);
;       l_reg = __uint_as_float(rr[0]) + __uint_as_float(rr[1]); }
;     if (hi == 0) wsl[r32] = l_reg;
;     asm volatile("s_waitcnt lgkmcnt(0)" ::: "memory");
; #pragma unroll
;     for (int r = 0; r < 16; ++r) { const int rr_ = crow(r, hi); const float rl = 1.0f / wsl[rr_];
;         const bf16* gp = A.proj + (grow0 + rr_) * INC + C_MG + hm * 128 + r32; bf16* yp = A.y + (grow0 + rr_) * DM + Y_M + hm * 128 + r32;
; #pragma unroll
;         for (int d0 = 0; d0 < 4; ++d0) { const float g = bf2f(gp[d0 * 32]); const float val = o[d0][r] * rl * silu(g);
	v_mfma_f32_32x32x16_bf16 v[32:47], v[80:83], v[100:103], v[32:47]
	s_waitcnt lgkmcnt(2)
	v_mfma_f32_32x32x16_bf16 v[16:31], v[80:83], v[104:107], v[16:31]
	s_waitcnt lgkmcnt(0)
	v_mfma_f32_32x32x16_bf16 v[0:15], v[80:83], v[108:111], v[0:15]
	ds_read_b64_tr_b16 v[80:81], v157 offset:0x1000
	ds_read_b64_tr_b16 v[82:83], v157 offset:0x1800
	ds_read_b64_tr_b16 v[96:97], v157 offset:0x1200
	ds_read_b64_tr_b16 v[98:99], v157 offset:0x1a00
	ds_read_b64_tr_b16 v[100:101], v157 offset:0x1400
	ds_read_b64_tr_b16 v[102:103], v157 offset:0x1c00
	ds_read_b64_tr_b16 v[104:105], v157 offset:0x1600
	ds_read_b64_tr_b16 v[106:107], v157 offset:0x1e00
	s_waitcnt lgkmcnt(6)
	s_nop 0
	v_mfma_f32_32x32x16_bf16 v[48:63], v[84:87], v[80:83], v[48:63]
	s_waitcnt lgkmcnt(4)
	v_mfma_f32_32x32x16_bf16 v[32:47], v[84:87], v[96:99], v[32:47]
	s_waitcnt lgkmcnt(2)
	v_mfma_f32_32x32x16_bf16 v[16:31], v[84:87], v[100:103], v[16:31]
	s_waitcnt lgkmcnt(0)
	ds_read_b64_tr_b16 v[80:81], v157 offset:0x2000
	ds_read_b64_tr_b16 v[82:83], v157 offset:0x2800
	v_mfma_f32_32x32x16_bf16 v[0:15], v[84:87], v[104:107], v[0:15]
	ds_read_b64_tr_b16 v[84:85], v157 offset:0x2200
	ds_read_b64_tr_b16 v[86:87], v157 offset:0x2a00
	ds_read_b64_tr_b16 v[96:97], v157 offset:0x2400
	ds_read_b64_tr_b16 v[98:99], v157 offset:0x2c00
	ds_read_b64_tr_b16 v[100:101], v157 offset:0x2600
	ds_read_b64_tr_b16 v[102:103], v157 offset:0x2e00
	s_waitcnt lgkmcnt(6)
	v_mfma_f32_32x32x16_bf16 v[48:63], v[88:91], v[80:83], v[48:63]
	s_waitcnt lgkmcnt(4)
	v_mfma_f32_32x32x16_bf16 v[32:47], v[88:91], v[84:87], v[32:47]
	s_waitcnt lgkmcnt(2)
	v_mfma_f32_32x32x16_bf16 v[16:31], v[88:91], v[96:99], v[16:31]
	s_waitcnt lgkmcnt(0)
	ds_read_b64_tr_b16 v[80:81], v157 offset:0x3000
	ds_read_b64_tr_b16 v[82:83], v157 offset:0x3800
	ds_read_b64_tr_b16 v[84:85], v157 offset:0x3200
	v_mfma_f32_32x32x16_bf16 v[0:15], v[88:91], v[100:103], v[0:15]
	ds_read_b64_tr_b16 v[86:87], v157 offset:0x3a00
	ds_read_b64_tr_b16 v[88:89], v157 offset:0x3400
	ds_read_b64_tr_b16 v[90:91], v157 offset:0x3c00
	ds_read_b64_tr_b16 v[96:97], v157 offset:0x3600
	ds_read_b64_tr_b16 v[98:99], v157 offset:0x3e00
	s_waitcnt lgkmcnt(6)
	v_mfma_f32_32x32x16_bf16 v[48:63], v[92:95], v[80:83], v[48:63]
	s_waitcnt lgkmcnt(4)
	v_mfma_f32_32x32x16_bf16 v[32:47], v[92:95], v[84:87], v[32:47]
	s_waitcnt lgkmcnt(2)
	v_mfma_f32_32x32x16_bf16 v[16:31], v[92:95], v[88:91], v[16:31]
	s_waitcnt lgkmcnt(0)
	v_mfma_f32_32x32x16_bf16 v[0:15], v[92:95], v[96:99], v[0:15]
	s_setprio 0
	s_addk_i32 s2, 0x4000
	s_cmp_lg_u32 s2, 0x10000
	s_cbranch_scc1 .LBB0_200
	s_and_b32 s1, s1, 0x3fffffc0
	s_lshl_b32 s1, s1, 2
	s_add_i32 s1, s1, 0
	v_mov_b32_e32 v64, v148
	s_add_i32 s1, s1, 0x20000
	s_nop 0
	v_permlane32_swap_b32_e32 v148, v64
	v_cmp_gt_u32_e32 vcc, 32, v145
	s_and_saveexec_b64 s[6:7], vcc
	v_add_f32_e32 v64, v148, v64
	v_lshl_add_u32 v65, v144, 2, s1
	ds_write_b32 v65, v64
	s_or_b64 exec, exec, s[6:7]
	s_waitcnt lgkmcnt(0)
	v_lshl_add_u32 v72, v146, 4, s1
	ds_read_b128 v[64:67], v72
	s_lshl_b32 s84, s0, 1
	v_lshlrev_b32_e32 v176, 1, v144
	s_waitcnt lgkmcnt(0)
	v_div_scale_f32 v68, s[6:7], v64, v64, 1.0
	v_rcp_f32_e32 v69, v68
	s_nop 0
	v_fma_f32 v70, -v68, v69, 1.0
	v_fmac_f32_e32 v69, v70, v69
	v_div_scale_f32 v70, vcc, 1.0, v64, 1.0
	v_mul_f32_e32 v71, v70, v69
	v_fma_f32 v73, -v68, v71, v70
	v_fmac_f32_e32 v71, v73, v69
	v_fma_f32 v68, -v68, v71, v70
	v_div_fmas_f32 v68, v68, v69, v71
	v_div_fixup_f32 v64, v68, v64, 1.0
	v_lshl_or_b32 v68, v146, 2, s8
	v_mul_u32_u24_e32 v161, 0x3800, v68
	v_add_u32_e32 v161, s84, v161
	v_lshl_add_u32 v161, v144, 1, v161
	v_add_u32_e32 v161, 0x3400, v161
	global_load_ushort v84, v161, s[80:81]
	global_load_ushort v85, v161, s[80:81] offset:64
	global_load_ushort v86, v161, s[80:81] offset:128
	global_load_ushort v87, v161, s[80:81] offset:192
	v_add_u32_e32 v163, 0x3800, v161
	global_load_ushort v88, v163, s[80:81]
	global_load_ushort v89, v163, s[80:81] offset:64
	global_load_ushort v90, v163, s[80:81] offset:128
	global_load_ushort v91, v163, s[80:81] offset:192
	v_add_u32_e32 v162, 0x7000, v161
	global_load_ushort v92, v162, s[80:81]
	global_load_ushort v93, v162, s[80:81] offset:64
	global_load_ushort v94, v162, s[80:81] offset:128
	global_load_ushort v95, v162, s[80:81] offset:192
	v_add_u32_e32 v163, 0xa800, v161
	global_load_ushort v96, v163, s[80:81]
	global_load_ushort v97, v163, s[80:81] offset:64
	global_load_ushort v98, v163, s[80:81] offset:128
	global_load_ushort v99, v163, s[80:81] offset:192
	v_add_u32_e32 v162, 0x1c000, v161
	global_load_ushort v100, v162, s[80:81]
	global_load_ushort v101, v162, s[80:81] offset:64
	global_load_ushort v102, v162, s[80:81] offset:128
	global_load_ushort v103, v162, s[80:81] offset:192
	v_add_u32_e32 v163, 0x1f800, v161
	global_load_ushort v104, v163, s[80:81]
	global_load_ushort v105, v163, s[80:81] offset:64
	global_load_ushort v106, v163, s[80:81] offset:128
	global_load_ushort v107, v163, s[80:81] offset:192
	v_add_u32_e32 v162, 0x23000, v161
	global_load_ushort v108, v162, s[80:81]
	global_load_ushort v109, v162, s[80:81] offset:64
	global_load_ushort v110, v162, s[80:81] offset:128
	global_load_ushort v111, v162, s[80:81] offset:192
	v_add_u32_e32 v163, 0x26800, v161
	global_load_ushort v157, v163, s[80:81]
	global_load_ushort v158, v163, s[80:81] offset:64
	global_load_ushort v159, v163, s[80:81] offset:128
	global_load_ushort v160, v163, s[80:81] offset:192
	v_mov_b64_e32 v[70:71], s[80:81]
	v_mad_u64_u32 v[74:75], s[6:7], v68, s33, v[70:71]
	s_mul_i32 s6, s3, 0x3800
	s_nop 0
	v_add_u32_e32 v75, s6, v75
	v_lshl_add_u64 v[74:75], v[74:75], 0, s[84:85]
	v_mov_b32_e32 v69, s3
	v_lshl_add_u64 v[74:75], v[74:75], 0, v[176:177]
	s_mov_b64 s[2:3], 0x3400
	v_lshl_add_u64 v[76:77], v[74:75], 0, s[2:3]
	v_add_co_u32_e32 v74, vcc, s63, v74
	v_lshlrev_b64 v[78:79], 12, v[68:69]
	s_nop 0
	v_addc_co_u32_e32 v75, vcc, 0, v75, vcc
	s_waitcnt vmcnt(28)
; __device__ __forceinline__ int crow(int r, int hi) { return (r & 3) + 8 * (r >> 2) + 4 * hi; }
; __device__ __forceinline__ unsigned cvtpk(float lo, float hi) { f32x2_t v = {lo, hi}; bf16x2_t b = __builtin_convertvector(v, bf16x2_t); return __builtin_bit_cast(unsigned, b); }
; __device__ __forceinline__ float bf2f(unsigned short h) { return __uint_as_float(((unsigned)h) << 16); }
; __device__ __forceinline__ float silu(float x) { return x / (1.0f + __expf(-x)); }
; __device__ __forceinline__ void mem_unit(const MemArgs& A, int unit, char* lds, int wv) {
;     ...
;     for (int r = 0; r < 16; ++r) { const int rr_ = crow(r, hi); const float rl = 1.0f / wsl[rr_];
;         const bf16* gp = A.proj + (grow0 + rr_) * INC + C_MG + hm * 128 + r32; bf16* yp = A.y + (grow0 + rr_) * DM + Y_M + hm * 128 + r32;
; #pragma unroll
;         for (int d0 = 0; d0 < 4; ++d0) { const float g = bf2f(gp[d0 * 32]); const float val = o[d0][r] * rl * silu(g);
;             yp[d0 * 32] = (bf16)(cvtpk(val, val) & 0xffffu); } }
	v_mov_b32_e32 v73, v84
	v_lshl_add_u64 v[78:79], s[82:83], 0, v[78:79]
	v_mul_f32_e32 v48, v48, v64
	v_lshl_add_u64 v[78:79], v[78:79], 0, s[84:85]
	v_lshl_add_u64 v[78:79], v[78:79], 0, v[176:177]
	v_mul_f32_e32 v32, v32, v64
	v_mul_f32_e32 v16, v16, v64
	v_mul_f32_e32 v0, v0, v64
	s_nop 0
	v_lshlrev_b32_e32 v73, 16, v73
	v_mul_f32_e32 v74, 0xbfb8aa3b, v73
	v_exp_f32_e32 v74, v74
	s_nop 0
	v_add_f32_e32 v74, 1.0, v74
	v_div_scale_f32 v75, s[0:1], v74, v74, v73
	v_rcp_f32_e32 v80, v75
	s_nop 0
	v_fma_f32 v81, -v75, v80, 1.0
	v_fmac_f32_e32 v80, v81, v80
	v_div_scale_f32 v81, vcc, v73, v74, v73
	v_mul_f32_e32 v82, v81, v80
	v_fma_f32 v83, -v75, v82, v81
	v_fmac_f32_e32 v82, v83, v80
	v_fma_f32 v75, -v75, v82, v81
	v_div_fmas_f32 v75, v75, v80, v82
	v_div_fixup_f32 v73, v75, v74, v73
	v_mul_f32_e32 v48, v48, v73
	v_cvt_pk_bf16_f32 v48, v48, s0
	global_store_short v[78:79], v48, off offset:3072
	s_waitcnt vmcnt(28)
	v_mov_b32_e32 v48, v85
	s_nop 0
	v_lshlrev_b32_e32 v48, 16, v48
	v_mul_f32_e32 v73, 0xbfb8aa3b, v48
	v_exp_f32_e32 v73, v73
	s_nop 0
	v_add_f32_e32 v73, 1.0, v73
	v_div_scale_f32 v74, s[0:1], v73, v73, v48
	v_rcp_f32_e32 v75, v74
	s_nop 0
	v_fma_f32 v80, -v74, v75, 1.0
	v_fmac_f32_e32 v75, v80, v75
	v_div_scale_f32 v80, vcc, v48, v73, v48
	v_mul_f32_e32 v81, v80, v75
	v_fma_f32 v82, -v74, v81, v80
	v_fmac_f32_e32 v81, v82, v75
	v_fma_f32 v74, -v74, v81, v80
	v_div_fmas_f32 v74, v74, v75, v81
	v_div_fixup_f32 v48, v74, v73, v48
	v_mul_f32_e32 v32, v32, v48
	v_cvt_pk_bf16_f32 v32, v32, s0
	global_store_short v[78:79], v32, off offset:3136
	s_waitcnt vmcnt(28)
	v_mov_b32_e32 v32, v86
	s_nop 0
	v_lshlrev_b32_e32 v32, 16, v32
	v_mul_f32_e32 v48, 0xbfb8aa3b, v32
	v_exp_f32_e32 v48, v48
	s_nop 0
	v_add_f32_e32 v48, 1.0, v48
	v_div_scale_f32 v73, s[0:1], v48, v48, v32
	v_rcp_f32_e32 v74, v73
	s_nop 0
	v_fma_f32 v75, -v73, v74, 1.0
	v_fmac_f32_e32 v74, v75, v74
	v_div_scale_f32 v75, vcc, v32, v48, v32
	v_mul_f32_e32 v80, v75, v74
	v_fma_f32 v81, -v73, v80, v75
	v_fmac_f32_e32 v80, v81, v74
	v_fma_f32 v73, -v73, v80, v75
	v_div_fmas_f32 v73, v73, v74, v80
	v_div_fixup_f32 v32, v73, v48, v32
	v_mul_f32_e32 v16, v16, v32
	v_cvt_pk_bf16_f32 v16, v16, s0
	global_store_short v[78:79], v16, off offset:3200
	s_waitcnt vmcnt(28)
	v_mov_b32_e32 v16, v87
	s_nop 0
	v_lshlrev_b32_e32 v16, 16, v16
	v_mul_f32_e32 v32, 0xbfb8aa3b, v16
	v_exp_f32_e32 v32, v32
	s_nop 0
	v_add_f32_e32 v32, 1.0, v32
	v_div_scale_f32 v48, s[0:1], v32, v32, v16
	v_rcp_f32_e32 v64, v48
	s_nop 0
	v_fma_f32 v73, -v48, v64, 1.0
	v_fmac_f32_e32 v64, v73, v64
	v_div_scale_f32 v73, vcc, v16, v32, v16
	v_mul_f32_e32 v74, v73, v64
	v_fma_f32 v75, -v48, v74, v73
	v_fmac_f32_e32 v74, v75, v64
	v_fma_f32 v48, -v48, v74, v73
	v_div_fmas_f32 v48, v48, v64, v74
	v_div_fixup_f32 v16, v48, v32, v16
	v_mul_f32_e32 v0, v0, v16
	v_cvt_pk_bf16_f32 v0, v0, s0
	global_store_short v[78:79], v0, off offset:3264
	v_div_scale_f32 v0, s[0:1], v65, v65, 1.0
	v_rcp_f32_e32 v16, v0
	s_nop 0
	v_fma_f32 v32, -v0, v16, 1.0
	v_fmac_f32_e32 v16, v32, v16
	v_div_scale_f32 v32, vcc, 1.0, v65, 1.0
	v_mul_f32_e32 v48, v32, v16
	v_fma_f32 v64, -v0, v48, v32
	v_fmac_f32_e32 v48, v64, v16
	v_or_b32_e32 v64, 1, v68
	v_mad_u64_u32 v[74:75], s[0:1], v64, s33, v[70:71]
	v_add_u32_e32 v75, s6, v75
	v_lshl_add_u64 v[74:75], v[74:75], 0, s[84:85]
	v_fma_f32 v0, -v0, v48, v32
	v_lshl_add_u64 v[74:75], v[74:75], 0, v[176:177]
	v_div_fmas_f32 v0, v0, v16, v48
	v_lshl_add_u64 v[76:77], v[74:75], 0, s[2:3]
	v_add_co_u32_e32 v74, vcc, s63, v74
	v_div_fixup_f32 v0, v0, v65, 1.0
	s_nop 0
	v_addc_co_u32_e32 v75, vcc, 0, v75, vcc
	s_waitcnt vmcnt(28)
	v_mov_b32_e32 v16, v88
	v_mul_f32_e32 v32, v49, v0
	v_mov_b32_e32 v65, v69
	v_lshlrev_b64 v[64:65], 12, v[64:65]
	v_lshl_add_u64 v[64:65], s[82:83], 0, v[64:65]
	v_lshl_add_u64 v[64:65], v[64:65], 0, s[84:85]
	v_lshl_add_u64 v[64:65], v[64:65], 0, v[176:177]
	v_mul_f32_e32 v17, v17, v0
	s_nop 0
	v_lshlrev_b32_e32 v16, 16, v16
	v_mul_f32_e32 v48, 0xbfb8aa3b, v16
	v_exp_f32_e32 v48, v48
	s_nop 0
	v_add_f32_e32 v48, 1.0, v48
	v_div_scale_f32 v49, s[0:1], v48, v48, v16
	v_rcp_f32_e32 v73, v49
	s_nop 0
	v_fma_f32 v74, -v49, v73, 1.0
	v_fmac_f32_e32 v73, v74, v73
	v_div_scale_f32 v74, vcc, v16, v48, v16
	v_mul_f32_e32 v75, v74, v73
	v_fma_f32 v78, -v49, v75, v74
	v_fmac_f32_e32 v75, v78, v73
	v_fma_f32 v49, -v49, v75, v74
	v_div_fmas_f32 v49, v49, v73, v75
	v_div_fixup_f32 v16, v49, v48, v16
	v_mul_f32_e32 v16, v32, v16
	v_cvt_pk_bf16_f32 v16, v16, s0
	global_store_short v[64:65], v16, off offset:3072
	s_waitcnt vmcnt(28)
	v_mov_b32_e32 v16, v89
	v_mul_f32_e32 v32, v33, v0
	v_mul_f32_e32 v0, v1, v0
	s_nop 0
	v_lshlrev_b32_e32 v16, 16, v16
	v_mul_f32_e32 v33, 0xbfb8aa3b, v16
	v_exp_f32_e32 v33, v33
	s_nop 0
	v_add_f32_e32 v33, 1.0, v33
	v_div_scale_f32 v48, s[0:1], v33, v33, v16
	v_rcp_f32_e32 v49, v48
	s_nop 0
	v_fma_f32 v73, -v48, v49, 1.0
	v_fmac_f32_e32 v49, v73, v49
	v_div_scale_f32 v73, vcc, v16, v33, v16
	v_mul_f32_e32 v74, v73, v49
	v_fma_f32 v75, -v48, v74, v73
	v_fmac_f32_e32 v74, v75, v49
	v_fma_f32 v48, -v48, v74, v73
	v_div_fmas_f32 v48, v48, v49, v74
	v_div_fixup_f32 v16, v48, v33, v16
	v_mul_f32_e32 v16, v32, v16
	v_cvt_pk_bf16_f32 v16, v16, s0
	global_store_short v[64:65], v16, off offset:3136
	s_waitcnt vmcnt(28)
	v_mov_b32_e32 v16, v90
	s_nop 0
	v_lshlrev_b32_e32 v16, 16, v16
	v_mul_f32_e32 v32, 0xbfb8aa3b, v16
	v_exp_f32_e32 v32, v32
	s_nop 0
	v_add_f32_e32 v32, 1.0, v32
	v_div_scale_f32 v33, s[0:1], v32, v32, v16
	v_rcp_f32_e32 v48, v33
	s_nop 0
	v_fma_f32 v49, -v33, v48, 1.0
	v_fmac_f32_e32 v48, v49, v48
	v_div_scale_f32 v49, vcc, v16, v32, v16
	v_mul_f32_e32 v73, v49, v48
	v_fma_f32 v74, -v33, v73, v49
	v_fmac_f32_e32 v73, v74, v48
	v_fma_f32 v33, -v33, v73, v49
	v_div_fmas_f32 v33, v33, v48, v73
	v_div_fixup_f32 v16, v33, v32, v16
	v_mul_f32_e32 v16, v17, v16
	v_cvt_pk_bf16_f32 v16, v16, s0
	global_store_short v[64:65], v16, off offset:3200
	s_waitcnt vmcnt(28)
; __device__ __forceinline__ int crow(int r, int hi) { return (r & 3) + 8 * (r >> 2) + 4 * hi; }
; __device__ __forceinline__ unsigned cvtpk(float lo, float hi) { f32x2_t v = {lo, hi}; bf16x2_t b = __builtin_convertvector(v, bf16x2_t); return __builtin_bit_cast(unsigned, b); }
; __device__ __forceinline__ float bf2f(unsigned short h) { return __uint_as_float(((unsigned)h) << 16); }
; __device__ __forceinline__ float silu(float x) { return x / (1.0f + __expf(-x)); }
; __device__ __forceinline__ void mem_unit(const MemArgs& A, int unit, char* lds, int wv) {
;     ...
;     for (int r = 0; r < 16; ++r) { const int rr_ = crow(r, hi); const float rl = 1.0f / wsl[rr_];
;         const bf16* gp = A.proj + (grow0 + rr_) * INC + C_MG + hm * 128 + r32; bf16* yp = A.y + (grow0 + rr_) * DM + Y_M + hm * 128 + r32;
; #pragma unroll
;         for (int d0 = 0; d0 < 4; ++d0) { const float g = bf2f(gp[d0 * 32]); const float val = o[d0][r] * rl * silu(g);
;             yp[d0 * 32] = (bf16)(cvtpk(val, val) & 0xffffu); } }
	v_mov_b32_e32 v16, v91
	s_nop 0
	v_lshlrev_b32_e32 v16, 16, v16
	v_mul_f32_e32 v1, 0xbfb8aa3b, v16
	v_exp_f32_e32 v1, v1
	s_nop 0
	v_add_f32_e32 v1, 1.0, v1
	v_div_scale_f32 v17, s[0:1], v1, v1, v16
	v_rcp_f32_e32 v32, v17
	s_nop 0
	v_fma_f32 v33, -v17, v32, 1.0
	v_fmac_f32_e32 v32, v33, v32
	v_div_scale_f32 v33, vcc, v16, v1, v16
	v_mul_f32_e32 v48, v33, v32
	v_fma_f32 v49, -v17, v48, v33
	v_fmac_f32_e32 v48, v49, v32
	v_fma_f32 v17, -v17, v48, v33
	v_div_fmas_f32 v17, v17, v32, v48
	v_div_fixup_f32 v1, v17, v1, v16
	v_mul_f32_e32 v0, v0, v1
	v_cvt_pk_bf16_f32 v0, v0, s0
	global_store_short v[64:65], v0, off offset:3264
	v_div_scale_f32 v0, s[0:1], v66, v66, 1.0
	v_rcp_f32_e32 v1, v0
	s_nop 0
	v_fma_f32 v16, -v0, v1, 1.0
	v_fmac_f32_e32 v1, v16, v1
	v_div_scale_f32 v16, vcc, 1.0, v66, 1.0
	v_mul_f32_e32 v17, v16, v1
	v_fma_f32 v32, -v0, v17, v16
	v_fmac_f32_e32 v17, v32, v1
	v_fma_f32 v0, -v0, v17, v16
	v_div_fmas_f32 v0, v0, v1, v17
	v_div_fixup_f32 v48, v0, v66, 1.0
	v_or_b32_e32 v0, 2, v68
	v_mad_u64_u32 v[16:17], s[0:1], v0, s33, v[70:71]
	v_add_u32_e32 v17, s6, v17
	v_lshl_add_u64 v[16:17], v[16:17], 0, s[84:85]
	v_lshl_add_u64 v[16:17], v[16:17], 0, v[176:177]
	v_lshl_add_u64 v[32:33], v[16:17], 0, s[2:3]
	v_add_co_u32_e32 v16, vcc, s63, v16
	v_mov_b32_e32 v1, v69
	s_nop 0
	v_addc_co_u32_e32 v17, vcc, 0, v17, vcc
	s_waitcnt vmcnt(28)
	v_mov_b32_e32 v16, v92
	v_mul_f32_e32 v17, v50, v48
	v_lshlrev_b64 v[0:1], 12, v[0:1]
	v_lshl_add_u64 v[0:1], s[82:83], 0, v[0:1]
	v_lshl_add_u64 v[0:1], v[0:1], 0, s[84:85]
	v_lshl_add_u64 v[0:1], v[0:1], 0, v[176:177]
	v_mul_f32_e32 v2, v2, v48
	s_nop 0
	v_lshlrev_b32_e32 v16, 16, v16
	v_mul_f32_e32 v49, 0xbfb8aa3b, v16
	v_exp_f32_e32 v49, v49
	s_nop 0
	v_add_f32_e32 v49, 1.0, v49
	v_div_scale_f32 v50, s[0:1], v49, v49, v16
	v_rcp_f32_e32 v64, v50
	s_nop 0
	v_fma_f32 v65, -v50, v64, 1.0
	v_fmac_f32_e32 v64, v65, v64
	v_div_scale_f32 v65, vcc, v16, v49, v16
	v_mul_f32_e32 v66, v65, v64
	v_fma_f32 v73, -v50, v66, v65
	v_fmac_f32_e32 v66, v73, v64
	v_fma_f32 v50, -v50, v66, v65
	v_div_fmas_f32 v50, v50, v64, v66
	v_div_fixup_f32 v16, v50, v49, v16
	v_mul_f32_e32 v16, v17, v16
	v_cvt_pk_bf16_f32 v16, v16, s0
	global_store_short v[0:1], v16, off offset:3072
	s_waitcnt vmcnt(28)
	v_mov_b32_e32 v16, v93
	v_mul_f32_e32 v17, v34, v48
	s_nop 0
	v_lshlrev_b32_e32 v16, 16, v16
	v_mul_f32_e32 v34, 0xbfb8aa3b, v16
	v_exp_f32_e32 v34, v34
	s_nop 0
	v_add_f32_e32 v34, 1.0, v34
	v_div_scale_f32 v49, s[0:1], v34, v34, v16
	v_rcp_f32_e32 v50, v49
	s_nop 0
	v_fma_f32 v64, -v49, v50, 1.0
	v_fmac_f32_e32 v50, v64, v50
	v_div_scale_f32 v64, vcc, v16, v34, v16
	v_mul_f32_e32 v65, v64, v50
	v_fma_f32 v66, -v49, v65, v64
	v_fmac_f32_e32 v65, v66, v50
	v_fma_f32 v49, -v49, v65, v64
	v_div_fmas_f32 v49, v49, v50, v65
	v_div_fixup_f32 v16, v49, v34, v16
	v_mul_f32_e32 v16, v17, v16
	v_cvt_pk_bf16_f32 v16, v16, s0
	global_store_short v[0:1], v16, off offset:3136
	s_waitcnt vmcnt(28)
	v_mov_b32_e32 v16, v94
	v_mul_f32_e32 v17, v18, v48
	s_nop 0
	v_lshlrev_b32_e32 v16, 16, v16
	v_mul_f32_e32 v18, 0xbfb8aa3b, v16
	v_exp_f32_e32 v18, v18
	s_nop 0
	v_add_f32_e32 v18, 1.0, v18
	v_div_scale_f32 v34, s[0:1], v18, v18, v16
	v_rcp_f32_e32 v49, v34
	s_nop 0
	v_fma_f32 v50, -v34, v49, 1.0
	v_fmac_f32_e32 v49, v50, v49
	v_div_scale_f32 v50, vcc, v16, v18, v16
	v_mul_f32_e32 v64, v50, v49
	v_fma_f32 v65, -v34, v64, v50
	v_fmac_f32_e32 v64, v65, v49
	v_fma_f32 v34, -v34, v64, v50
	v_div_fmas_f32 v34, v34, v49, v64
	v_div_fixup_f32 v16, v34, v18, v16
	v_mul_f32_e32 v16, v17, v16
	v_cvt_pk_bf16_f32 v16, v16, s0
	global_store_short v[0:1], v16, off offset:3200
	s_waitcnt vmcnt(28)
	v_mov_b32_e32 v16, v95
	s_nop 0
	v_lshlrev_b32_e32 v16, 16, v16
	v_mul_f32_e32 v17, 0xbfb8aa3b, v16
	v_exp_f32_e32 v17, v17
	s_nop 0
	v_add_f32_e32 v17, 1.0, v17
	v_div_scale_f32 v18, s[0:1], v17, v17, v16
	v_rcp_f32_e32 v32, v18
	s_nop 0
	v_fma_f32 v33, -v18, v32, 1.0
	v_fmac_f32_e32 v32, v33, v32
	v_div_scale_f32 v33, vcc, v16, v17, v16
	v_mul_f32_e32 v34, v33, v32
	v_fma_f32 v48, -v18, v34, v33
	v_fmac_f32_e32 v34, v48, v32
	v_fma_f32 v18, -v18, v34, v33
	v_div_fmas_f32 v18, v18, v32, v34
	v_div_fixup_f32 v16, v18, v17, v16
	v_mul_f32_e32 v2, v2, v16
	v_cvt_pk_bf16_f32 v2, v2, s0
	global_store_short v[0:1], v2, off offset:3264
	v_div_scale_f32 v0, s[0:1], v67, v67, 1.0
	v_rcp_f32_e32 v1, v0
	s_nop 0
	v_fma_f32 v2, -v0, v1, 1.0
	v_fmac_f32_e32 v1, v2, v1
	v_div_scale_f32 v2, vcc, 1.0, v67, 1.0
	v_mul_f32_e32 v16, v2, v1
	v_fma_f32 v17, -v0, v16, v2
	v_fmac_f32_e32 v16, v17, v1
	v_fma_f32 v0, -v0, v16, v2
	v_div_fmas_f32 v0, v0, v1, v16
	v_div_fixup_f32 v2, v0, v67, 1.0
	v_or_b32_e32 v0, 3, v68
	v_mad_u64_u32 v[16:17], s[0:1], v0, s33, v[70:71]
	v_add_u32_e32 v17, s6, v17
	v_lshl_add_u64 v[16:17], v[16:17], 0, s[84:85]
	v_lshl_add_u64 v[16:17], v[16:17], 0, v[176:177]
	v_lshl_add_u64 v[32:33], v[16:17], 0, s[2:3]
	v_add_co_u32_e32 v16, vcc, s63, v16
	v_mov_b32_e32 v1, v69
	s_nop 0
	v_addc_co_u32_e32 v17, vcc, 0, v17, vcc
	s_waitcnt vmcnt(28)
	v_mov_b32_e32 v16, v96
	v_mul_f32_e32 v17, v51, v2
	v_lshlrev_b64 v[0:1], 12, v[0:1]
	v_lshl_add_u64 v[0:1], s[82:83], 0, v[0:1]
	v_lshl_add_u64 v[0:1], v[0:1], 0, s[84:85]
	v_lshl_add_u64 v[0:1], v[0:1], 0, v[176:177]
	s_nop 0
	v_lshlrev_b32_e32 v16, 16, v16
	v_mul_f32_e32 v18, 0xbfb8aa3b, v16
	v_exp_f32_e32 v18, v18
	s_nop 0
	v_add_f32_e32 v18, 1.0, v18
	v_div_scale_f32 v34, s[0:1], v18, v18, v16
	v_rcp_f32_e32 v48, v34
	s_nop 0
	v_fma_f32 v49, -v34, v48, 1.0
	v_fmac_f32_e32 v48, v49, v48
	v_div_scale_f32 v49, vcc, v16, v18, v16
	v_mul_f32_e32 v50, v49, v48
	v_fma_f32 v51, -v34, v50, v49
	v_fmac_f32_e32 v50, v51, v48
	v_fma_f32 v34, -v34, v50, v49
	v_div_fmas_f32 v34, v34, v48, v50
	v_div_fixup_f32 v16, v34, v18, v16
	v_mul_f32_e32 v16, v17, v16
	v_cvt_pk_bf16_f32 v16, v16, s0
	global_store_short v[0:1], v16, off offset:3072
	s_waitcnt vmcnt(28)
; __device__ __forceinline__ int crow(int r, int hi) { return (r & 3) + 8 * (r >> 2) + 4 * hi; }
; __device__ __forceinline__ unsigned cvtpk(float lo, float hi) { f32x2_t v = {lo, hi}; bf16x2_t b = __builtin_convertvector(v, bf16x2_t); return __builtin_bit_cast(unsigned, b); }
; __device__ __forceinline__ float bf2f(unsigned short h) { return __uint_as_float(((unsigned)h) << 16); }
; __device__ __forceinline__ float silu(float x) { return x / (1.0f + __expf(-x)); }
; __device__ __forceinline__ void mem_unit(const MemArgs& A, int unit, char* lds, int wv) {
;     ...
;     for (int r = 0; r < 16; ++r) { const int rr_ = crow(r, hi); const float rl = 1.0f / wsl[rr_];
;         const bf16* gp = A.proj + (grow0 + rr_) * INC + C_MG + hm * 128 + r32; bf16* yp = A.y + (grow0 + rr_) * DM + Y_M + hm * 128 + r32;
; #pragma unroll
;         for (int d0 = 0; d0 < 4; ++d0) { const float g = bf2f(gp[d0 * 32]); const float val = o[d0][r] * rl * silu(g);
;             yp[d0 * 32] = (bf16)(cvtpk(val, val) & 0xffffu); } }
	v_mov_b32_e32 v16, v97
	v_mul_f32_e32 v17, v35, v2
	s_nop 0
	v_lshlrev_b32_e32 v16, 16, v16
	v_mul_f32_e32 v18, 0xbfb8aa3b, v16
	v_exp_f32_e32 v18, v18
	s_nop 0
	v_add_f32_e32 v18, 1.0, v18
	v_div_scale_f32 v34, s[0:1], v18, v18, v16
	v_rcp_f32_e32 v35, v34
	s_nop 0
	v_fma_f32 v48, -v34, v35, 1.0
	v_fmac_f32_e32 v35, v48, v35
	v_div_scale_f32 v48, vcc, v16, v18, v16
	v_mul_f32_e32 v49, v48, v35
	v_fma_f32 v50, -v34, v49, v48
	v_fmac_f32_e32 v49, v50, v35
	v_fma_f32 v34, -v34, v49, v48
	v_div_fmas_f32 v34, v34, v35, v49
	v_div_fixup_f32 v16, v34, v18, v16
	v_mul_f32_e32 v16, v17, v16
	v_cvt_pk_bf16_f32 v16, v16, s0
	global_store_short v[0:1], v16, off offset:3136
	s_waitcnt vmcnt(28)
	v_mov_b32_e32 v16, v98
	v_mul_f32_e32 v17, v19, v2
	v_mul_f32_e32 v2, v3, v2
	s_nop 0
	v_lshlrev_b32_e32 v16, 16, v16
	v_mul_f32_e32 v18, 0xbfb8aa3b, v16
	v_exp_f32_e32 v18, v18
	s_nop 0
	v_add_f32_e32 v18, 1.0, v18
	v_div_scale_f32 v19, s[0:1], v18, v18, v16
	v_rcp_f32_e32 v34, v19
	s_nop 0
	v_fma_f32 v35, -v19, v34, 1.0
	v_fmac_f32_e32 v34, v35, v34
	v_div_scale_f32 v35, vcc, v16, v18, v16
	v_mul_f32_e32 v48, v35, v34
	v_fma_f32 v49, -v19, v48, v35
	v_fmac_f32_e32 v48, v49, v34
	v_fma_f32 v19, -v19, v48, v35
	v_div_fmas_f32 v19, v19, v34, v48
	v_div_fixup_f32 v16, v19, v18, v16
	v_mul_f32_e32 v16, v17, v16
	v_cvt_pk_bf16_f32 v16, v16, s0
	global_store_short v[0:1], v16, off offset:3200
	s_waitcnt vmcnt(28)
	v_mov_b32_e32 v16, v99
	s_nop 0
	v_lshlrev_b32_e32 v16, 16, v16
	v_mul_f32_e32 v3, 0xbfb8aa3b, v16
	v_exp_f32_e32 v3, v3
	s_nop 0
	v_add_f32_e32 v3, 1.0, v3
	v_div_scale_f32 v17, s[0:1], v3, v3, v16
	v_rcp_f32_e32 v18, v17
	s_nop 0
	v_fma_f32 v19, -v17, v18, 1.0
	v_fmac_f32_e32 v18, v19, v18
	v_div_scale_f32 v19, vcc, v16, v3, v16
	v_mul_f32_e32 v32, v19, v18
	v_fma_f32 v33, -v17, v32, v19
	v_fmac_f32_e32 v32, v33, v18
	v_fma_f32 v17, -v17, v32, v19
	v_div_fmas_f32 v17, v17, v18, v32
	v_div_fixup_f32 v3, v17, v3, v16
	v_mul_f32_e32 v2, v2, v3
	v_cvt_pk_bf16_f32 v2, v2, s0
	global_store_short v[0:1], v2, off offset:3264
	ds_read_b128 v[0:3], v72 offset:32
	s_waitcnt lgkmcnt(0)
	v_div_scale_f32 v16, s[0:1], v0, v0, 1.0
	v_rcp_f32_e32 v17, v16
	s_nop 0
	v_fma_f32 v18, -v16, v17, 1.0
	v_fmac_f32_e32 v17, v18, v17
	v_div_scale_f32 v18, vcc, 1.0, v0, 1.0
	v_mul_f32_e32 v19, v18, v17
	v_fma_f32 v32, -v16, v19, v18
	v_fmac_f32_e32 v19, v32, v17
	v_fma_f32 v16, -v16, v19, v18
	v_div_fmas_f32 v16, v16, v17, v19
	v_div_fixup_f32 v0, v16, v0, 1.0
	v_or_b32_e32 v16, 8, v68
	v_mad_u64_u32 v[18:19], s[0:1], v16, s33, v[70:71]
	v_add_u32_e32 v19, s6, v19
	v_lshl_add_u64 v[18:19], v[18:19], 0, s[84:85]
	v_lshl_add_u64 v[32:33], v[18:19], 0, v[176:177]
	v_lshl_add_u64 v[18:19], v[32:33], 0, s[2:3]
	v_add_co_u32_e32 v32, vcc, s63, v32
	v_mov_b32_e32 v17, v69
	s_nop 0
	v_addc_co_u32_e32 v33, vcc, 0, v33, vcc
	s_waitcnt vmcnt(28)
	v_mov_b32_e32 v32, v100
	v_lshlrev_b64 v[16:17], 12, v[16:17]
	v_lshl_add_u64 v[16:17], s[82:83], 0, v[16:17]
	v_mul_f32_e32 v33, v52, v0
	v_lshl_add_u64 v[16:17], v[16:17], 0, s[84:85]
	v_lshl_add_u64 v[16:17], v[16:17], 0, v[176:177]
	v_mul_f32_e32 v20, v20, v0
	s_nop 0
	v_lshlrev_b32_e32 v32, 16, v32
	v_mul_f32_e32 v34, 0xbfb8aa3b, v32
	v_exp_f32_e32 v34, v34
	s_nop 0
	v_add_f32_e32 v34, 1.0, v34
	v_div_scale_f32 v35, s[0:1], v34, v34, v32
	v_rcp_f32_e32 v48, v35
	s_nop 0
	v_fma_f32 v49, -v35, v48, 1.0
	v_fmac_f32_e32 v48, v49, v48
	v_div_scale_f32 v49, vcc, v32, v34, v32
	v_mul_f32_e32 v50, v49, v48
	v_fma_f32 v51, -v35, v50, v49
	v_fmac_f32_e32 v50, v51, v48
	v_fma_f32 v35, -v35, v50, v49
	v_div_fmas_f32 v35, v35, v48, v50
	v_div_fixup_f32 v32, v35, v34, v32
	v_mul_f32_e32 v32, v33, v32
	v_cvt_pk_bf16_f32 v32, v32, s0
	global_store_short v[16:17], v32, off offset:3072
	s_waitcnt vmcnt(28)
	v_mov_b32_e32 v32, v101
	v_mul_f32_e32 v33, v36, v0
	v_mul_f32_e32 v0, v4, v0
	s_nop 0
	v_lshlrev_b32_e32 v32, 16, v32
	v_mul_f32_e32 v34, 0xbfb8aa3b, v32
	v_exp_f32_e32 v34, v34
	s_nop 0
	v_add_f32_e32 v34, 1.0, v34
	v_div_scale_f32 v35, s[0:1], v34, v34, v32
	v_rcp_f32_e32 v36, v35
	s_nop 0
	v_fma_f32 v48, -v35, v36, 1.0
	v_fmac_f32_e32 v36, v48, v36
	v_div_scale_f32 v48, vcc, v32, v34, v32
	v_mul_f32_e32 v49, v48, v36
	v_fma_f32 v50, -v35, v49, v48
	v_fmac_f32_e32 v49, v50, v36
	v_fma_f32 v35, -v35, v49, v48
	v_div_fmas_f32 v35, v35, v36, v49
	v_div_fixup_f32 v32, v35, v34, v32
	v_mul_f32_e32 v32, v33, v32
	v_cvt_pk_bf16_f32 v32, v32, s0
	global_store_short v[16:17], v32, off offset:3136
	s_waitcnt vmcnt(28)
	v_mov_b32_e32 v32, v102
	s_nop 0
	v_lshlrev_b32_e32 v32, 16, v32
	s_waitcnt vmcnt(28)
	v_mov_b32_e32 v18, v103
	v_mul_f32_e32 v33, 0xbfb8aa3b, v32
	v_exp_f32_e32 v33, v33
	s_nop 0
	v_lshlrev_b32_e32 v18, 16, v18
	v_add_f32_e32 v33, 1.0, v33
	v_div_scale_f32 v34, s[0:1], v33, v33, v32
	v_rcp_f32_e32 v35, v34
	v_mul_f32_e32 v4, 0xbfb8aa3b, v18
	v_exp_f32_e32 v4, v4
	v_fma_f32 v36, -v34, v35, 1.0
	v_fmac_f32_e32 v35, v36, v35
	v_div_scale_f32 v36, vcc, v32, v33, v32
	v_mul_f32_e32 v48, v36, v35
	v_fma_f32 v49, -v34, v48, v36
	v_fmac_f32_e32 v48, v49, v35
	v_fma_f32 v34, -v34, v48, v36
	v_div_fmas_f32 v34, v34, v35, v48
	v_div_fixup_f32 v32, v34, v33, v32
	v_mul_f32_e32 v20, v20, v32
	v_add_f32_e32 v4, 1.0, v4
	v_cvt_pk_bf16_f32 v20, v20, s0
	v_div_scale_f32 v19, s[0:1], v4, v4, v18
	global_store_short v[16:17], v20, off offset:3200
	v_rcp_f32_e32 v20, v19
	s_nop 0
	v_fma_f32 v32, -v19, v20, 1.0
	v_fmac_f32_e32 v20, v32, v20
	v_div_scale_f32 v32, vcc, v18, v4, v18
	v_mul_f32_e32 v33, v32, v20
	v_fma_f32 v34, -v19, v33, v32
	v_fmac_f32_e32 v33, v34, v20
	v_fma_f32 v19, -v19, v33, v32
	v_div_fmas_f32 v19, v19, v20, v33
	v_div_fixup_f32 v4, v19, v4, v18
	v_mul_f32_e32 v0, v0, v4
	v_cvt_pk_bf16_f32 v0, v0, s0
	global_store_short v[16:17], v0, off offset:3264
	v_div_scale_f32 v0, s[0:1], v1, v1, 1.0
	v_rcp_f32_e32 v4, v0
	s_nop 0
	v_fma_f32 v16, -v0, v4, 1.0
	v_fmac_f32_e32 v4, v16, v4
	v_div_scale_f32 v16, vcc, 1.0, v1, 1.0
	v_mul_f32_e32 v17, v16, v4
	v_fma_f32 v18, -v0, v17, v16
	v_fmac_f32_e32 v17, v18, v4
	v_fma_f32 v0, -v0, v17, v16
	v_div_fmas_f32 v0, v0, v4, v17
	v_div_fixup_f32 v4, v0, v1, 1.0
	v_or_b32_e32 v0, 9, v68
	v_mad_u64_u32 v[16:17], s[0:1], v0, s33, v[70:71]
	v_add_u32_e32 v17, s6, v17
	v_lshl_add_u64 v[16:17], v[16:17], 0, s[84:85]
	v_lshl_add_u64 v[18:19], v[16:17], 0, v[176:177]
	v_lshl_add_u64 v[16:17], v[18:19], 0, s[2:3]
	v_add_co_u32_e32 v18, vcc, s63, v18
	v_mov_b32_e32 v1, v69
	s_nop 0
	v_addc_co_u32_e32 v19, vcc, 0, v19, vcc
	s_waitcnt vmcnt(28)
; __device__ __forceinline__ int crow(int r, int hi) { return (r & 3) + 8 * (r >> 2) + 4 * hi; }
; __device__ __forceinline__ unsigned cvtpk(float lo, float hi) { f32x2_t v = {lo, hi}; bf16x2_t b = __builtin_convertvector(v, bf16x2_t); return __builtin_bit_cast(unsigned, b); }
; __device__ __forceinline__ float bf2f(unsigned short h) { return __uint_as_float(((unsigned)h) << 16); }
; __device__ __forceinline__ float silu(float x) { return x / (1.0f + __expf(-x)); }
; __device__ __forceinline__ void mem_unit(const MemArgs& A, int unit, char* lds, int wv) {
;     ...
;     for (int r = 0; r < 16; ++r) { const int rr_ = crow(r, hi); const float rl = 1.0f / wsl[rr_];
;         const bf16* gp = A.proj + (grow0 + rr_) * INC + C_MG + hm * 128 + r32; bf16* yp = A.y + (grow0 + rr_) * DM + Y_M + hm * 128 + r32;
; #pragma unroll
;         for (int d0 = 0; d0 < 4; ++d0) { const float g = bf2f(gp[d0 * 32]); const float val = o[d0][r] * rl * silu(g);
;             yp[d0 * 32] = (bf16)(cvtpk(val, val) & 0xffffu); } }
	v_mov_b32_e32 v18, v104
	v_lshlrev_b64 v[0:1], 12, v[0:1]
	v_lshl_add_u64 v[0:1], s[82:83], 0, v[0:1]
	v_mul_f32_e32 v19, v53, v4
	v_lshl_add_u64 v[0:1], v[0:1], 0, s[84:85]
	v_lshl_add_u64 v[0:1], v[0:1], 0, v[176:177]
	s_nop 0
	v_lshlrev_b32_e32 v18, 16, v18
	v_mul_f32_e32 v20, 0xbfb8aa3b, v18
	v_exp_f32_e32 v20, v20
	s_nop 0
	v_add_f32_e32 v20, 1.0, v20
	v_div_scale_f32 v32, s[0:1], v20, v20, v18
	v_rcp_f32_e32 v33, v32
	s_nop 0
	v_fma_f32 v34, -v32, v33, 1.0
	v_fmac_f32_e32 v33, v34, v33
	v_div_scale_f32 v34, vcc, v18, v20, v18
	v_mul_f32_e32 v35, v34, v33
	v_fma_f32 v36, -v32, v35, v34
	v_fmac_f32_e32 v35, v36, v33
	v_fma_f32 v32, -v32, v35, v34
	v_div_fmas_f32 v32, v32, v33, v35
	v_div_fixup_f32 v18, v32, v20, v18
	v_mul_f32_e32 v18, v19, v18
	v_cvt_pk_bf16_f32 v18, v18, s0
	global_store_short v[0:1], v18, off offset:3072
	s_waitcnt vmcnt(28)
	v_mov_b32_e32 v18, v105
	v_mul_f32_e32 v19, v37, v4
	s_nop 0
	v_lshlrev_b32_e32 v18, 16, v18
	v_mul_f32_e32 v20, 0xbfb8aa3b, v18
	v_exp_f32_e32 v20, v20
	s_nop 0
	v_add_f32_e32 v20, 1.0, v20
	v_div_scale_f32 v32, s[0:1], v20, v20, v18
	v_rcp_f32_e32 v33, v32
	s_nop 0
	v_fma_f32 v34, -v32, v33, 1.0
	v_fmac_f32_e32 v33, v34, v33
	v_div_scale_f32 v34, vcc, v18, v20, v18
	v_mul_f32_e32 v35, v34, v33
	v_fma_f32 v36, -v32, v35, v34
	v_fmac_f32_e32 v35, v36, v33
	v_fma_f32 v32, -v32, v35, v34
	v_div_fmas_f32 v32, v32, v33, v35
	v_div_fixup_f32 v18, v32, v20, v18
	v_mul_f32_e32 v18, v19, v18
	v_cvt_pk_bf16_f32 v18, v18, s0
	global_store_short v[0:1], v18, off offset:3136
	s_waitcnt vmcnt(28)
	v_mov_b32_e32 v18, v106
	v_mul_f32_e32 v19, v21, v4
	s_waitcnt vmcnt(28)
	v_mov_b32_e32 v16, v107
	v_mul_f32_e32 v4, v5, v4
	s_nop 0
	v_lshlrev_b32_e32 v18, 16, v18
	v_mul_f32_e32 v20, 0xbfb8aa3b, v18
	v_exp_f32_e32 v20, v20
	s_nop 0
	v_lshlrev_b32_e32 v16, 16, v16
	v_mul_f32_e32 v5, 0xbfb8aa3b, v16
	v_exp_f32_e32 v5, v5
	v_add_f32_e32 v20, 1.0, v20
	v_div_scale_f32 v21, s[0:1], v20, v20, v18
	v_rcp_f32_e32 v32, v21
	v_add_f32_e32 v5, 1.0, v5
	v_fma_f32 v33, -v21, v32, 1.0
	v_fmac_f32_e32 v32, v33, v32
	v_div_scale_f32 v33, vcc, v18, v20, v18
	v_mul_f32_e32 v34, v33, v32
	v_fma_f32 v35, -v21, v34, v33
	v_fmac_f32_e32 v34, v35, v32
	v_fma_f32 v21, -v21, v34, v33
	v_div_fmas_f32 v21, v21, v32, v34
	v_div_fixup_f32 v18, v21, v20, v18
	v_mul_f32_e32 v18, v19, v18
	v_cvt_pk_bf16_f32 v18, v18, s0
	v_div_scale_f32 v17, s[0:1], v5, v5, v16
	global_store_short v[0:1], v18, off offset:3200
	v_rcp_f32_e32 v18, v17
	s_nop 0
	v_fma_f32 v19, -v17, v18, 1.0
	v_fmac_f32_e32 v18, v19, v18
	v_div_scale_f32 v19, vcc, v16, v5, v16
	v_mul_f32_e32 v20, v19, v18
	v_fma_f32 v21, -v17, v20, v19
	v_fmac_f32_e32 v20, v21, v18
	v_fma_f32 v17, -v17, v20, v19
	v_div_fmas_f32 v17, v17, v18, v20
	v_div_fixup_f32 v5, v17, v5, v16
	v_mul_f32_e32 v4, v4, v5
	v_cvt_pk_bf16_f32 v4, v4, s0
	global_store_short v[0:1], v4, off offset:3264
	v_div_scale_f32 v0, s[0:1], v2, v2, 1.0
	v_rcp_f32_e32 v1, v0
	s_nop 0
	v_fma_f32 v4, -v0, v1, 1.0
	v_fmac_f32_e32 v1, v4, v1
	v_div_scale_f32 v4, vcc, 1.0, v2, 1.0
	v_mul_f32_e32 v5, v4, v1
	v_fma_f32 v16, -v0, v5, v4
	v_fmac_f32_e32 v5, v16, v1
	v_fma_f32 v0, -v0, v5, v4
	v_div_fmas_f32 v0, v0, v1, v5
	v_div_fixup_f32 v2, v0, v2, 1.0
	v_or_b32_e32 v0, 10, v68
	v_mad_u64_u32 v[4:5], s[0:1], v0, s33, v[70:71]
	v_add_u32_e32 v5, s6, v5
	v_lshl_add_u64 v[4:5], v[4:5], 0, s[84:85]
	v_lshl_add_u64 v[16:17], v[4:5], 0, v[176:177]
	v_lshl_add_u64 v[4:5], v[16:17], 0, s[2:3]
	v_add_co_u32_e32 v16, vcc, s63, v16
	v_mov_b32_e32 v1, v69
	s_nop 0
	v_addc_co_u32_e32 v17, vcc, 0, v17, vcc
	s_waitcnt vmcnt(28)
	v_mov_b32_e32 v16, v108
	v_lshlrev_b64 v[0:1], 12, v[0:1]
	v_lshl_add_u64 v[0:1], s[82:83], 0, v[0:1]
	v_mul_f32_e32 v17, v54, v2
	v_lshl_add_u64 v[0:1], v[0:1], 0, s[84:85]
	v_lshl_add_u64 v[0:1], v[0:1], 0, v[176:177]
	s_nop 0
	v_lshlrev_b32_e32 v16, 16, v16
	v_mul_f32_e32 v18, 0xbfb8aa3b, v16
	v_exp_f32_e32 v18, v18
	s_nop 0
	v_add_f32_e32 v18, 1.0, v18
	v_div_scale_f32 v19, s[0:1], v18, v18, v16
	v_rcp_f32_e32 v20, v19
	s_nop 0
	v_fma_f32 v21, -v19, v20, 1.0
	v_fmac_f32_e32 v20, v21, v20
	v_div_scale_f32 v21, vcc, v16, v18, v16
	v_mul_f32_e32 v32, v21, v20
	v_fma_f32 v33, -v19, v32, v21
	v_fmac_f32_e32 v32, v33, v20
	v_fma_f32 v19, -v19, v32, v21
	v_div_fmas_f32 v19, v19, v20, v32
	v_div_fixup_f32 v16, v19, v18, v16
	v_mul_f32_e32 v16, v17, v16
	v_cvt_pk_bf16_f32 v16, v16, s0
	global_store_short v[0:1], v16, off offset:3072
	s_waitcnt vmcnt(28)
	v_mov_b32_e32 v16, v109
	v_mul_f32_e32 v17, v38, v2
	s_nop 0
	v_lshlrev_b32_e32 v16, 16, v16
	v_mul_f32_e32 v18, 0xbfb8aa3b, v16
	v_exp_f32_e32 v18, v18
	s_nop 0
	v_add_f32_e32 v18, 1.0, v18
	v_div_scale_f32 v19, s[0:1], v18, v18, v16
	v_rcp_f32_e32 v20, v19
	s_nop 0
	v_fma_f32 v21, -v19, v20, 1.0
	v_fmac_f32_e32 v20, v21, v20
	v_div_scale_f32 v21, vcc, v16, v18, v16
	v_mul_f32_e32 v32, v21, v20
	v_fma_f32 v33, -v19, v32, v21
	v_fmac_f32_e32 v32, v33, v20
	v_fma_f32 v19, -v19, v32, v21
	v_div_fmas_f32 v19, v19, v20, v32
	v_div_fixup_f32 v16, v19, v18, v16
	v_mul_f32_e32 v16, v17, v16
	v_cvt_pk_bf16_f32 v16, v16, s0
	global_store_short v[0:1], v16, off offset:3136
	s_waitcnt vmcnt(28)
	v_mov_b32_e32 v16, v110
	v_mul_f32_e32 v17, v22, v2
	s_waitcnt vmcnt(28)
; __device__ __forceinline__ int crow(int r, int hi) { return (r & 3) + 8 * (r >> 2) + 4 * hi; }
; __device__ __forceinline__ unsigned cvtpk(float lo, float hi) { f32x2_t v = {lo, hi}; bf16x2_t b = __builtin_convertvector(v, bf16x2_t); return __builtin_bit_cast(unsigned, b); }
; __device__ __forceinline__ float bf2f(unsigned short h) { return __uint_as_float(((unsigned)h) << 16); }
; __device__ __forceinline__ float silu(float x) { return x / (1.0f + __expf(-x)); }
; __device__ __forceinline__ void mem_unit(const MemArgs& A, int unit, char* lds, int wv) {
;     ...
;     for (int r = 0; r < 16; ++r) { const int rr_ = crow(r, hi); const float rl = 1.0f / wsl[rr_];
;         const bf16* gp = A.proj + (grow0 + rr_) * INC + C_MG + hm * 128 + r32; bf16* yp = A.y + (grow0 + rr_) * DM + Y_M + hm * 128 + r32;
; #pragma unroll
;         for (int d0 = 0; d0 < 4; ++d0) { const float g = bf2f(gp[d0 * 32]); const float val = o[d0][r] * rl * silu(g);
;             yp[d0 * 32] = (bf16)(cvtpk(val, val) & 0xffffu); } }
	v_mov_b32_e32 v4, v111
	v_mul_f32_e32 v2, v6, v2
	s_nop 0
	v_lshlrev_b32_e32 v16, 16, v16
	v_mul_f32_e32 v18, 0xbfb8aa3b, v16
	v_exp_f32_e32 v18, v18
	s_nop 0
	v_lshlrev_b32_e32 v4, 16, v4
	v_mul_f32_e32 v5, 0xbfb8aa3b, v4
	v_exp_f32_e32 v5, v5
	v_add_f32_e32 v18, 1.0, v18
	v_div_scale_f32 v19, s[0:1], v18, v18, v16
	v_rcp_f32_e32 v20, v19
	v_add_f32_e32 v5, 1.0, v5
	v_fma_f32 v21, -v19, v20, 1.0
	v_fmac_f32_e32 v20, v21, v20
	v_div_scale_f32 v21, vcc, v16, v18, v16
	v_mul_f32_e32 v22, v21, v20
	v_fma_f32 v32, -v19, v22, v21
	v_fmac_f32_e32 v22, v32, v20
	v_fma_f32 v19, -v19, v22, v21
	v_div_fmas_f32 v19, v19, v20, v22
	v_div_fixup_f32 v16, v19, v18, v16
	v_mul_f32_e32 v16, v17, v16
	v_cvt_pk_bf16_f32 v16, v16, s0
	v_div_scale_f32 v6, s[0:1], v5, v5, v4
	global_store_short v[0:1], v16, off offset:3200
	v_rcp_f32_e32 v16, v6
	s_nop 0
	v_fma_f32 v17, -v6, v16, 1.0
	v_fmac_f32_e32 v16, v17, v16
	v_div_scale_f32 v17, vcc, v4, v5, v4
	v_mul_f32_e32 v18, v17, v16
	v_fma_f32 v19, -v6, v18, v17
	v_fmac_f32_e32 v18, v19, v16
	v_fma_f32 v6, -v6, v18, v17
	v_div_fmas_f32 v6, v6, v16, v18
	v_div_fixup_f32 v4, v6, v5, v4
	v_mul_f32_e32 v2, v2, v4
	v_cvt_pk_bf16_f32 v2, v2, s0
	global_store_short v[0:1], v2, off offset:3264
	v_div_scale_f32 v0, s[0:1], v3, v3, 1.0
	v_rcp_f32_e32 v1, v0
	s_nop 0
	v_fma_f32 v2, -v0, v1, 1.0
	v_fmac_f32_e32 v1, v2, v1
	v_div_scale_f32 v2, vcc, 1.0, v3, 1.0
	v_mul_f32_e32 v4, v2, v1
	v_fma_f32 v5, -v0, v4, v2
	v_fmac_f32_e32 v4, v5, v1
	v_fma_f32 v0, -v0, v4, v2
	v_div_fmas_f32 v0, v0, v1, v4
	v_div_fixup_f32 v4, v0, v3, 1.0
	v_or_b32_e32 v0, 11, v68
	v_mad_u64_u32 v[2:3], s[0:1], v0, s33, v[70:71]
	v_add_u32_e32 v3, s6, v3
	v_lshl_add_u64 v[2:3], v[2:3], 0, s[84:85]
	v_lshl_add_u64 v[16:17], v[2:3], 0, v[176:177]
	v_lshl_add_u64 v[2:3], v[16:17], 0, s[2:3]
	v_add_co_u32_e32 v16, vcc, s63, v16
	v_mov_b32_e32 v1, v69
	s_nop 0
	v_addc_co_u32_e32 v17, vcc, 0, v17, vcc
	s_waitcnt vmcnt(28)
	v_mov_b32_e32 v5, v157
	v_lshlrev_b64 v[0:1], 12, v[0:1]
	v_lshl_add_u64 v[0:1], s[82:83], 0, v[0:1]
	v_mul_f32_e32 v6, v55, v4
	v_lshl_add_u64 v[0:1], v[0:1], 0, s[84:85]
	v_lshl_add_u64 v[0:1], v[0:1], 0, v[176:177]
	s_nop 0
	v_lshlrev_b32_e32 v5, 16, v5
	v_mul_f32_e32 v16, 0xbfb8aa3b, v5
	v_exp_f32_e32 v16, v16
	s_nop 0
	v_add_f32_e32 v16, 1.0, v16
	v_div_scale_f32 v17, s[0:1], v16, v16, v5
	v_rcp_f32_e32 v18, v17
	s_nop 0
	v_fma_f32 v19, -v17, v18, 1.0
	v_fmac_f32_e32 v18, v19, v18
	v_div_scale_f32 v19, vcc, v5, v16, v5
	v_mul_f32_e32 v20, v19, v18
	v_fma_f32 v21, -v17, v20, v19
	v_fmac_f32_e32 v20, v21, v18
	v_fma_f32 v17, -v17, v20, v19
	v_div_fmas_f32 v17, v17, v18, v20
	v_div_fixup_f32 v5, v17, v16, v5
	v_mul_f32_e32 v5, v6, v5
	v_cvt_pk_bf16_f32 v5, v5, s0
	global_store_short v[0:1], v5, off offset:3072
	s_waitcnt vmcnt(28)
	v_mov_b32_e32 v5, v158
	v_mul_f32_e32 v6, v39, v4
	s_nop 0
	v_lshlrev_b32_e32 v5, 16, v5
	v_mul_f32_e32 v16, 0xbfb8aa3b, v5
	v_exp_f32_e32 v16, v16
	s_nop 0
	v_add_f32_e32 v16, 1.0, v16
	v_div_scale_f32 v17, s[0:1], v16, v16, v5
	v_rcp_f32_e32 v18, v17
	s_nop 0
	v_fma_f32 v19, -v17, v18, 1.0
	v_fmac_f32_e32 v18, v19, v18
	v_div_scale_f32 v19, vcc, v5, v16, v5
	v_mul_f32_e32 v20, v19, v18
	v_fma_f32 v21, -v17, v20, v19
	v_fmac_f32_e32 v20, v21, v18
	v_fma_f32 v17, -v17, v20, v19
	v_div_fmas_f32 v17, v17, v18, v20
	v_div_fixup_f32 v5, v17, v16, v5
	v_mul_f32_e32 v5, v6, v5
	v_cvt_pk_bf16_f32 v5, v5, s0
	global_store_short v[0:1], v5, off offset:3136
	s_waitcnt vmcnt(28)
	v_mov_b32_e32 v5, v159
	v_mul_f32_e32 v6, v23, v4
	s_waitcnt vmcnt(28)
	v_mov_b32_e32 v2, v160
	v_mul_f32_e32 v3, v7, v4
	s_nop 0
	v_lshlrev_b32_e32 v5, 16, v5
	v_mul_f32_e32 v16, 0xbfb8aa3b, v5
	v_exp_f32_e32 v16, v16
	s_nop 0
	v_lshlrev_b32_e32 v2, 16, v2
	v_mul_f32_e32 v4, 0xbfb8aa3b, v2
	v_exp_f32_e32 v4, v4
	v_add_f32_e32 v16, 1.0, v16
	v_div_scale_f32 v17, s[0:1], v16, v16, v5
	v_rcp_f32_e32 v18, v17
	v_add_f32_e32 v4, 1.0, v4
	v_fma_f32 v19, -v17, v18, 1.0
	v_fmac_f32_e32 v18, v19, v18
	v_div_scale_f32 v19, vcc, v5, v16, v5
	v_mul_f32_e32 v20, v19, v18
	v_fma_f32 v21, -v17, v20, v19
	v_fmac_f32_e32 v20, v21, v18
	v_fma_f32 v17, -v17, v20, v19
	v_div_fmas_f32 v17, v17, v18, v20
	v_div_fixup_f32 v5, v17, v16, v5
	v_mul_f32_e32 v5, v6, v5
	v_cvt_pk_bf16_f32 v5, v5, s0
	global_store_short v[0:1], v5, off offset:3200
	v_div_scale_f32 v5, s[0:1], v4, v4, v2
	v_rcp_f32_e32 v6, v5
	s_nop 0
	v_fma_f32 v7, -v5, v6, 1.0
	v_fmac_f32_e32 v6, v7, v6
	v_div_scale_f32 v7, vcc, v2, v4, v2
	v_mul_f32_e32 v16, v7, v6
	v_fma_f32 v17, -v5, v16, v7
	v_fmac_f32_e32 v16, v17, v6
	v_fma_f32 v5, -v5, v16, v7
	v_div_fmas_f32 v5, v5, v6, v16
	v_div_fixup_f32 v2, v5, v4, v2
	v_mul_f32_e32 v2, v3, v2
	v_cvt_pk_bf16_f32 v2, v2, s0
	global_store_short v[0:1], v2, off offset:3264
	s_waitcnt vmcnt(16)
; __device__ __forceinline__ int crow(int r, int hi) { return (r & 3) + 8 * (r >> 2) + 4 * hi; }
; __device__ __forceinline__ unsigned cvtpk(float lo, float hi) { f32x2_t v = {lo, hi}; bf16x2_t b = __builtin_convertvector(v, bf16x2_t); return __builtin_bit_cast(unsigned, b); }
; __device__ __forceinline__ float bf2f(unsigned short h) { return __uint_as_float(((unsigned)h) << 16); }
; __device__ __forceinline__ float silu(float x) { return x / (1.0f + __expf(-x)); }
; __device__ __forceinline__ void mem_unit(const MemArgs& A, int unit, char* lds, int wv) {
;     ...
;     for (int r = 0; r < 16; ++r) { const int rr_ = crow(r, hi); const float rl = 1.0f / wsl[rr_];
;         const bf16* gp = A.proj + (grow0 + rr_) * INC + C_MG + hm * 128 + r32; bf16* yp = A.y + (grow0 + rr_) * DM + Y_M + hm * 128 + r32;
; #pragma unroll
;         for (int d0 = 0; d0 < 4; ++d0) { const float g = bf2f(gp[d0 * 32]); const float val = o[d0][r] * rl * silu(g);
;             yp[d0 * 32] = (bf16)(cvtpk(val, val) & 0xffffu); } }
	v_add_u32_e32 v162, 0x38000, v161
	global_load_ushort v84, v162, s[80:81]
	global_load_ushort v85, v162, s[80:81] offset:64
	global_load_ushort v86, v162, s[80:81] offset:128
	global_load_ushort v87, v162, s[80:81] offset:192
	v_add_u32_e32 v163, 0x3b800, v161
	global_load_ushort v88, v163, s[80:81]
	global_load_ushort v89, v163, s[80:81] offset:64
	global_load_ushort v90, v163, s[80:81] offset:128
	global_load_ushort v91, v163, s[80:81] offset:192
	v_add_u32_e32 v162, 0x3f000, v161
	global_load_ushort v92, v162, s[80:81]
	global_load_ushort v93, v162, s[80:81] offset:64
	global_load_ushort v94, v162, s[80:81] offset:128
	global_load_ushort v95, v162, s[80:81] offset:192
	v_add_u32_e32 v163, 0x42800, v161
	global_load_ushort v96, v163, s[80:81]
	global_load_ushort v97, v163, s[80:81] offset:64
	global_load_ushort v98, v163, s[80:81] offset:128
	global_load_ushort v99, v163, s[80:81] offset:192
	v_add_u32_e32 v162, 0x54000, v161
	global_load_ushort v100, v162, s[80:81]
	global_load_ushort v101, v162, s[80:81] offset:64
	global_load_ushort v102, v162, s[80:81] offset:128
	global_load_ushort v103, v162, s[80:81] offset:192
	v_add_u32_e32 v163, 0x57800, v161
	global_load_ushort v104, v163, s[80:81]
	global_load_ushort v105, v163, s[80:81] offset:64
	global_load_ushort v106, v163, s[80:81] offset:128
	global_load_ushort v107, v163, s[80:81] offset:192
	v_add_u32_e32 v162, 0x5b000, v161
	global_load_ushort v108, v162, s[80:81]
	global_load_ushort v109, v162, s[80:81] offset:64
	global_load_ushort v110, v162, s[80:81] offset:128
	global_load_ushort v111, v162, s[80:81] offset:192
	v_add_u32_e32 v163, 0x5e800, v161
	global_load_ushort v157, v163, s[80:81]
	global_load_ushort v158, v163, s[80:81] offset:64
	global_load_ushort v159, v163, s[80:81] offset:128
	global_load_ushort v160, v163, s[80:81] offset:192
	ds_read_b128 v[0:3], v72 offset:64
	s_waitcnt lgkmcnt(0)
	v_div_scale_f32 v4, s[0:1], v0, v0, 1.0
	v_rcp_f32_e32 v5, v4
	s_nop 0
	v_fma_f32 v6, -v4, v5, 1.0
	v_fmac_f32_e32 v5, v6, v5
	v_div_scale_f32 v6, vcc, 1.0, v0, 1.0
	v_mul_f32_e32 v7, v6, v5
	v_fma_f32 v16, -v4, v7, v6
	v_fmac_f32_e32 v7, v16, v5
	v_fma_f32 v4, -v4, v7, v6
	v_div_fmas_f32 v4, v4, v5, v7
	v_div_fixup_f32 v0, v4, v0, 1.0
	v_or_b32_e32 v4, 16, v68
	v_mad_u64_u32 v[6:7], s[0:1], v4, s33, v[70:71]
	v_add_u32_e32 v7, s6, v7
	v_lshl_add_u64 v[6:7], v[6:7], 0, s[84:85]
	v_lshl_add_u64 v[16:17], v[6:7], 0, v[176:177]
	v_lshl_add_u64 v[6:7], v[16:17], 0, s[2:3]
	v_add_co_u32_e32 v16, vcc, s63, v16
	v_mov_b32_e32 v5, v69
	s_nop 0
	v_addc_co_u32_e32 v17, vcc, 0, v17, vcc
	s_waitcnt vmcnt(28)
	v_mov_b32_e32 v16, v84
	v_lshlrev_b64 v[4:5], 12, v[4:5]
	v_lshl_add_u64 v[4:5], s[82:83], 0, v[4:5]
	v_mul_f32_e32 v17, v56, v0
	v_lshl_add_u64 v[4:5], v[4:5], 0, s[84:85]
	v_lshl_add_u64 v[4:5], v[4:5], 0, v[176:177]
	s_nop 0
	v_lshlrev_b32_e32 v16, 16, v16
	v_mul_f32_e32 v18, 0xbfb8aa3b, v16
	v_exp_f32_e32 v18, v18
	s_nop 0
	v_add_f32_e32 v18, 1.0, v18
	v_div_scale_f32 v19, s[0:1], v18, v18, v16
	v_rcp_f32_e32 v20, v19
	s_nop 0
	v_fma_f32 v21, -v19, v20, 1.0
	v_fmac_f32_e32 v20, v21, v20
	v_div_scale_f32 v21, vcc, v16, v18, v16
	v_mul_f32_e32 v22, v21, v20
	v_fma_f32 v23, -v19, v22, v21
	v_fmac_f32_e32 v22, v23, v20
	v_fma_f32 v19, -v19, v22, v21
	v_div_fmas_f32 v19, v19, v20, v22
	v_div_fixup_f32 v16, v19, v18, v16
	v_mul_f32_e32 v16, v17, v16
	v_cvt_pk_bf16_f32 v16, v16, s0
	global_store_short v[4:5], v16, off offset:3072
	s_waitcnt vmcnt(28)
	v_mov_b32_e32 v16, v85
	v_mul_f32_e32 v17, v40, v0
	s_nop 0
	v_lshlrev_b32_e32 v16, 16, v16
	v_mul_f32_e32 v18, 0xbfb8aa3b, v16
	v_exp_f32_e32 v18, v18
	s_nop 0
	v_add_f32_e32 v18, 1.0, v18
	v_div_scale_f32 v19, s[0:1], v18, v18, v16
	v_rcp_f32_e32 v20, v19
	s_nop 0
	v_fma_f32 v21, -v19, v20, 1.0
	v_fmac_f32_e32 v20, v21, v20
	v_div_scale_f32 v21, vcc, v16, v18, v16
	v_mul_f32_e32 v22, v21, v20
	v_fma_f32 v23, -v19, v22, v21
	v_fmac_f32_e32 v22, v23, v20
	v_fma_f32 v19, -v19, v22, v21
	v_div_fmas_f32 v19, v19, v20, v22
	v_div_fixup_f32 v16, v19, v18, v16
	v_mul_f32_e32 v16, v17, v16
	v_cvt_pk_bf16_f32 v16, v16, s0
	global_store_short v[4:5], v16, off offset:3136
	s_waitcnt vmcnt(28)
	v_mov_b32_e32 v16, v86
	v_mul_f32_e32 v17, v24, v0
	s_waitcnt vmcnt(28)
	v_mov_b32_e32 v6, v87
	v_mul_f32_e32 v0, v8, v0
	s_nop 0
	v_lshlrev_b32_e32 v16, 16, v16
	v_mul_f32_e32 v18, 0xbfb8aa3b, v16
	v_exp_f32_e32 v18, v18
	s_nop 0
	v_lshlrev_b32_e32 v6, 16, v6
	v_mul_f32_e32 v7, 0xbfb8aa3b, v6
	v_exp_f32_e32 v7, v7
	v_add_f32_e32 v18, 1.0, v18
	v_div_scale_f32 v19, s[0:1], v18, v18, v16
	v_rcp_f32_e32 v20, v19
	v_add_f32_e32 v7, 1.0, v7
	v_fma_f32 v21, -v19, v20, 1.0
	v_fmac_f32_e32 v20, v21, v20
	v_div_scale_f32 v21, vcc, v16, v18, v16
	v_mul_f32_e32 v22, v21, v20
	v_fma_f32 v23, -v19, v22, v21
	v_fmac_f32_e32 v22, v23, v20
	v_fma_f32 v19, -v19, v22, v21
	v_div_fmas_f32 v19, v19, v20, v22
	v_div_fixup_f32 v16, v19, v18, v16
	v_mul_f32_e32 v16, v17, v16
	v_cvt_pk_bf16_f32 v16, v16, s0
	v_div_scale_f32 v8, s[0:1], v7, v7, v6
	global_store_short v[4:5], v16, off offset:3200
	v_rcp_f32_e32 v16, v8
	s_nop 0
	v_fma_f32 v17, -v8, v16, 1.0
	v_fmac_f32_e32 v16, v17, v16
	v_div_scale_f32 v17, vcc, v6, v7, v6
	v_mul_f32_e32 v18, v17, v16
	v_fma_f32 v19, -v8, v18, v17
	v_fmac_f32_e32 v18, v19, v16
	v_fma_f32 v8, -v8, v18, v17
	v_div_fmas_f32 v8, v8, v16, v18
	v_div_fixup_f32 v6, v8, v7, v6
	v_mul_f32_e32 v0, v0, v6
	v_cvt_pk_bf16_f32 v0, v0, s0
	global_store_short v[4:5], v0, off offset:3264
	v_div_scale_f32 v0, s[0:1], v1, v1, 1.0
	v_rcp_f32_e32 v4, v0
	s_nop 0
	v_fma_f32 v5, -v0, v4, 1.0
	v_fmac_f32_e32 v4, v5, v4
	v_div_scale_f32 v5, vcc, 1.0, v1, 1.0
	v_mul_f32_e32 v6, v5, v4
	v_fma_f32 v7, -v0, v6, v5
	v_fmac_f32_e32 v6, v7, v4
	v_fma_f32 v0, -v0, v6, v5
	v_div_fmas_f32 v0, v0, v4, v6
	v_div_fixup_f32 v8, v0, v1, 1.0
	v_or_b32_e32 v0, 17, v68
	v_mad_u64_u32 v[4:5], s[0:1], v0, s33, v[70:71]
	v_add_u32_e32 v5, s6, v5
	v_lshl_add_u64 v[4:5], v[4:5], 0, s[84:85]
	v_lshl_add_u64 v[4:5], v[4:5], 0, v[176:177]
	v_lshl_add_u64 v[6:7], v[4:5], 0, s[2:3]
	v_add_co_u32_e32 v4, vcc, s63, v4
	v_mov_b32_e32 v1, v69
	s_nop 0
	v_addc_co_u32_e32 v5, vcc, 0, v5, vcc
	s_waitcnt vmcnt(28)
; __device__ __forceinline__ int crow(int r, int hi) { return (r & 3) + 8 * (r >> 2) + 4 * hi; }
; __device__ __forceinline__ unsigned cvtpk(float lo, float hi) { f32x2_t v = {lo, hi}; bf16x2_t b = __builtin_convertvector(v, bf16x2_t); return __builtin_bit_cast(unsigned, b); }
; __device__ __forceinline__ float bf2f(unsigned short h) { return __uint_as_float(((unsigned)h) << 16); }
; __device__ __forceinline__ float silu(float x) { return x / (1.0f + __expf(-x)); }
; __device__ __forceinline__ void mem_unit(const MemArgs& A, int unit, char* lds, int wv) {
;     ...
;     for (int r = 0; r < 16; ++r) { const int rr_ = crow(r, hi); const float rl = 1.0f / wsl[rr_];
;         const bf16* gp = A.proj + (grow0 + rr_) * INC + C_MG + hm * 128 + r32; bf16* yp = A.y + (grow0 + rr_) * DM + Y_M + hm * 128 + r32;
; #pragma unroll
;         for (int d0 = 0; d0 < 4; ++d0) { const float g = bf2f(gp[d0 * 32]); const float val = o[d0][r] * rl * silu(g);
;             yp[d0 * 32] = (bf16)(cvtpk(val, val) & 0xffffu); } }
	v_mov_b32_e32 v4, v88
	v_lshlrev_b64 v[0:1], 12, v[0:1]
	v_lshl_add_u64 v[0:1], s[82:83], 0, v[0:1]
	v_mul_f32_e32 v5, v57, v8
	v_lshl_add_u64 v[0:1], v[0:1], 0, s[84:85]
	v_lshl_add_u64 v[0:1], v[0:1], 0, v[176:177]
	s_nop 0
	v_lshlrev_b32_e32 v4, 16, v4
	v_mul_f32_e32 v16, 0xbfb8aa3b, v4
	v_exp_f32_e32 v16, v16
	s_nop 0
	v_add_f32_e32 v16, 1.0, v16
	v_div_scale_f32 v17, s[0:1], v16, v16, v4
	v_rcp_f32_e32 v18, v17
	s_nop 0
	v_fma_f32 v19, -v17, v18, 1.0
	v_fmac_f32_e32 v18, v19, v18
	v_div_scale_f32 v19, vcc, v4, v16, v4
	v_mul_f32_e32 v20, v19, v18
	v_fma_f32 v21, -v17, v20, v19
	v_fmac_f32_e32 v20, v21, v18
	v_fma_f32 v17, -v17, v20, v19
	v_div_fmas_f32 v17, v17, v18, v20
	v_div_fixup_f32 v4, v17, v16, v4
	v_mul_f32_e32 v4, v5, v4
	v_cvt_pk_bf16_f32 v4, v4, s0
	global_store_short v[0:1], v4, off offset:3072
	s_waitcnt vmcnt(28)
	v_mov_b32_e32 v4, v89
	v_mul_f32_e32 v5, v41, v8
	s_nop 0
	v_lshlrev_b32_e32 v4, 16, v4
	v_mul_f32_e32 v16, 0xbfb8aa3b, v4
	v_exp_f32_e32 v16, v16
	s_nop 0
	v_add_f32_e32 v16, 1.0, v16
	v_div_scale_f32 v17, s[0:1], v16, v16, v4
	v_rcp_f32_e32 v18, v17
	s_nop 0
	v_fma_f32 v19, -v17, v18, 1.0
	v_fmac_f32_e32 v18, v19, v18
	v_div_scale_f32 v19, vcc, v4, v16, v4
	v_mul_f32_e32 v20, v19, v18
	v_fma_f32 v21, -v17, v20, v19
	v_fmac_f32_e32 v20, v21, v18
	v_fma_f32 v17, -v17, v20, v19
	v_div_fmas_f32 v17, v17, v18, v20
	v_div_fixup_f32 v4, v17, v16, v4
	v_mul_f32_e32 v4, v5, v4
	v_cvt_pk_bf16_f32 v4, v4, s0
	global_store_short v[0:1], v4, off offset:3136
	s_waitcnt vmcnt(28)
	v_mov_b32_e32 v4, v90
	v_mul_f32_e32 v5, v25, v8
	s_nop 0
	v_lshlrev_b32_e32 v4, 16, v4
	v_mul_f32_e32 v16, 0xbfb8aa3b, v4
	v_exp_f32_e32 v16, v16
	s_nop 0
	v_add_f32_e32 v16, 1.0, v16
	v_div_scale_f32 v17, s[0:1], v16, v16, v4
	v_rcp_f32_e32 v18, v17
	s_nop 0
	v_fma_f32 v19, -v17, v18, 1.0
	v_fmac_f32_e32 v18, v19, v18
	v_div_scale_f32 v19, vcc, v4, v16, v4
	v_mul_f32_e32 v20, v19, v18
	v_fma_f32 v21, -v17, v20, v19
	v_fmac_f32_e32 v20, v21, v18
	v_fma_f32 v17, -v17, v20, v19
	v_div_fmas_f32 v17, v17, v18, v20
	v_div_fixup_f32 v4, v17, v16, v4
	v_mul_f32_e32 v4, v5, v4
	v_cvt_pk_bf16_f32 v4, v4, s0
	global_store_short v[0:1], v4, off offset:3200
	s_waitcnt vmcnt(28)
	v_mov_b32_e32 v4, v91
	v_mul_f32_e32 v5, v9, v8
	s_nop 0
	v_lshlrev_b32_e32 v4, 16, v4
	v_mul_f32_e32 v6, 0xbfb8aa3b, v4
	v_exp_f32_e32 v6, v6
	s_nop 0
	v_add_f32_e32 v6, 1.0, v6
	v_div_scale_f32 v7, s[0:1], v6, v6, v4
	v_rcp_f32_e32 v8, v7
	s_nop 0
	v_fma_f32 v9, -v7, v8, 1.0
	v_fmac_f32_e32 v8, v9, v8
	v_div_scale_f32 v9, vcc, v4, v6, v4
	v_mul_f32_e32 v16, v9, v8
	v_fma_f32 v17, -v7, v16, v9
	v_fmac_f32_e32 v16, v17, v8
	v_fma_f32 v7, -v7, v16, v9
	v_div_fmas_f32 v7, v7, v8, v16
	v_div_fixup_f32 v4, v7, v6, v4
	v_mul_f32_e32 v4, v5, v4
	v_cvt_pk_bf16_f32 v4, v4, s0
	global_store_short v[0:1], v4, off offset:3264
	v_div_scale_f32 v0, s[0:1], v2, v2, 1.0
	v_rcp_f32_e32 v1, v0
	s_nop 0
	v_fma_f32 v4, -v0, v1, 1.0
	v_fmac_f32_e32 v1, v4, v1
	v_div_scale_f32 v4, vcc, 1.0, v2, 1.0
	v_mul_f32_e32 v5, v4, v1
	v_fma_f32 v6, -v0, v5, v4
	v_fmac_f32_e32 v5, v6, v1
	v_fma_f32 v0, -v0, v5, v4
	v_div_fmas_f32 v0, v0, v1, v5
	v_div_fixup_f32 v2, v0, v2, 1.0
	v_or_b32_e32 v0, 18, v68
	v_mad_u64_u32 v[4:5], s[0:1], v0, s33, v[70:71]
	v_add_u32_e32 v5, s6, v5
	v_lshl_add_u64 v[4:5], v[4:5], 0, s[84:85]
	v_lshl_add_u64 v[4:5], v[4:5], 0, v[176:177]
	v_lshl_add_u64 v[6:7], v[4:5], 0, s[2:3]
	v_add_co_u32_e32 v4, vcc, s63, v4
	v_mov_b32_e32 v1, v69
	s_nop 0
	v_addc_co_u32_e32 v5, vcc, 0, v5, vcc
	s_waitcnt vmcnt(28)
	v_mov_b32_e32 v4, v92
	v_lshlrev_b64 v[0:1], 12, v[0:1]
	v_lshl_add_u64 v[0:1], s[82:83], 0, v[0:1]
	v_mul_f32_e32 v5, v58, v2
	v_lshl_add_u64 v[0:1], v[0:1], 0, s[84:85]
	v_lshl_add_u64 v[0:1], v[0:1], 0, v[176:177]
	s_nop 0
	v_lshlrev_b32_e32 v4, 16, v4
	v_mul_f32_e32 v8, 0xbfb8aa3b, v4
	v_exp_f32_e32 v8, v8
	s_nop 0
	v_add_f32_e32 v8, 1.0, v8
	v_div_scale_f32 v9, s[0:1], v8, v8, v4
	v_rcp_f32_e32 v16, v9
	s_nop 0
	v_fma_f32 v17, -v9, v16, 1.0
	v_fmac_f32_e32 v16, v17, v16
	v_div_scale_f32 v17, vcc, v4, v8, v4
	v_mul_f32_e32 v18, v17, v16
	v_fma_f32 v19, -v9, v18, v17
	v_fmac_f32_e32 v18, v19, v16
	v_fma_f32 v9, -v9, v18, v17
	v_div_fmas_f32 v9, v9, v16, v18
	v_div_fixup_f32 v4, v9, v8, v4
	v_mul_f32_e32 v4, v5, v4
	v_cvt_pk_bf16_f32 v4, v4, s0
	global_store_short v[0:1], v4, off offset:3072
	s_waitcnt vmcnt(28)
	v_mov_b32_e32 v4, v93
	v_mul_f32_e32 v5, v42, v2
	s_nop 0
	v_lshlrev_b32_e32 v4, 16, v4
	v_mul_f32_e32 v8, 0xbfb8aa3b, v4
	v_exp_f32_e32 v8, v8
	s_nop 0
	v_add_f32_e32 v8, 1.0, v8
	v_div_scale_f32 v9, s[0:1], v8, v8, v4
	v_rcp_f32_e32 v16, v9
	s_nop 0
	v_fma_f32 v17, -v9, v16, 1.0
	v_fmac_f32_e32 v16, v17, v16
	v_div_scale_f32 v17, vcc, v4, v8, v4
	v_mul_f32_e32 v18, v17, v16
	v_fma_f32 v19, -v9, v18, v17
	v_fmac_f32_e32 v18, v19, v16
	v_fma_f32 v9, -v9, v18, v17
	v_div_fmas_f32 v9, v9, v16, v18
	v_div_fixup_f32 v4, v9, v8, v4
	v_mul_f32_e32 v4, v5, v4
	v_cvt_pk_bf16_f32 v4, v4, s0
	global_store_short v[0:1], v4, off offset:3136
	s_waitcnt vmcnt(28)
	v_mov_b32_e32 v4, v94
	v_mul_f32_e32 v5, v26, v2
	v_mul_f32_e32 v2, v10, v2
	s_nop 0
	v_lshlrev_b32_e32 v4, 16, v4
	v_mul_f32_e32 v8, 0xbfb8aa3b, v4
	v_exp_f32_e32 v8, v8
	s_nop 0
	v_add_f32_e32 v8, 1.0, v8
	v_div_scale_f32 v9, s[0:1], v8, v8, v4
	v_rcp_f32_e32 v16, v9
	s_nop 0
	v_fma_f32 v17, -v9, v16, 1.0
	v_fmac_f32_e32 v16, v17, v16
	v_div_scale_f32 v17, vcc, v4, v8, v4
	v_mul_f32_e32 v18, v17, v16
	v_fma_f32 v19, -v9, v18, v17
	v_fmac_f32_e32 v18, v19, v16
	v_fma_f32 v9, -v9, v18, v17
	v_div_fmas_f32 v9, v9, v16, v18
	v_div_fixup_f32 v4, v9, v8, v4
	v_mul_f32_e32 v4, v5, v4
	v_cvt_pk_bf16_f32 v4, v4, s0
	global_store_short v[0:1], v4, off offset:3200
	s_waitcnt vmcnt(28)
; __device__ __forceinline__ int crow(int r, int hi) { return (r & 3) + 8 * (r >> 2) + 4 * hi; }
; __device__ __forceinline__ unsigned cvtpk(float lo, float hi) { f32x2_t v = {lo, hi}; bf16x2_t b = __builtin_convertvector(v, bf16x2_t); return __builtin_bit_cast(unsigned, b); }
; __device__ __forceinline__ float bf2f(unsigned short h) { return __uint_as_float(((unsigned)h) << 16); }
; __device__ __forceinline__ float silu(float x) { return x / (1.0f + __expf(-x)); }
; __device__ __forceinline__ void mem_unit(const MemArgs& A, int unit, char* lds, int wv) {
;     ...
;     for (int r = 0; r < 16; ++r) { const int rr_ = crow(r, hi); const float rl = 1.0f / wsl[rr_];
;         const bf16* gp = A.proj + (grow0 + rr_) * INC + C_MG + hm * 128 + r32; bf16* yp = A.y + (grow0 + rr_) * DM + Y_M + hm * 128 + r32;
; #pragma unroll
;         for (int d0 = 0; d0 < 4; ++d0) { const float g = bf2f(gp[d0 * 32]); const float val = o[d0][r] * rl * silu(g);
;             yp[d0 * 32] = (bf16)(cvtpk(val, val) & 0xffffu); } }
	v_mov_b32_e32 v4, v95
	s_nop 0
	v_lshlrev_b32_e32 v4, 16, v4
	v_mul_f32_e32 v5, 0xbfb8aa3b, v4
	v_exp_f32_e32 v5, v5
	s_nop 0
	v_add_f32_e32 v5, 1.0, v5
	v_div_scale_f32 v6, s[0:1], v5, v5, v4
	v_rcp_f32_e32 v7, v6
	s_nop 0
	v_fma_f32 v8, -v6, v7, 1.0
	v_fmac_f32_e32 v7, v8, v7
	v_div_scale_f32 v8, vcc, v4, v5, v4
	v_mul_f32_e32 v9, v8, v7
	v_fma_f32 v10, -v6, v9, v8
	v_fmac_f32_e32 v9, v10, v7
	v_fma_f32 v6, -v6, v9, v8
	v_div_fmas_f32 v6, v6, v7, v9
	v_div_fixup_f32 v4, v6, v5, v4
	v_mul_f32_e32 v2, v2, v4
	v_cvt_pk_bf16_f32 v2, v2, s0
	global_store_short v[0:1], v2, off offset:3264
	v_div_scale_f32 v0, s[0:1], v3, v3, 1.0
	v_rcp_f32_e32 v1, v0
	s_nop 0
	v_fma_f32 v2, -v0, v1, 1.0
	v_fmac_f32_e32 v1, v2, v1
	v_div_scale_f32 v2, vcc, 1.0, v3, 1.0
	v_mul_f32_e32 v4, v2, v1
	v_fma_f32 v5, -v0, v4, v2
	v_fmac_f32_e32 v4, v5, v1
	v_fma_f32 v0, -v0, v4, v2
	v_div_fmas_f32 v0, v0, v1, v4
	v_div_fixup_f32 v6, v0, v3, 1.0
	v_or_b32_e32 v0, 19, v68
	v_mad_u64_u32 v[2:3], s[0:1], v0, s33, v[70:71]
	v_add_u32_e32 v3, s6, v3
	v_lshl_add_u64 v[2:3], v[2:3], 0, s[84:85]
	v_lshl_add_u64 v[2:3], v[2:3], 0, v[176:177]
	v_lshl_add_u64 v[4:5], v[2:3], 0, s[2:3]
	v_add_co_u32_e32 v2, vcc, s63, v2
	v_mov_b32_e32 v1, v69
	s_nop 0
	v_addc_co_u32_e32 v3, vcc, 0, v3, vcc
	s_waitcnt vmcnt(28)
	v_mov_b32_e32 v2, v96
	v_lshlrev_b64 v[0:1], 12, v[0:1]
	v_lshl_add_u64 v[0:1], s[82:83], 0, v[0:1]
	v_mul_f32_e32 v3, v59, v6
	v_lshl_add_u64 v[0:1], v[0:1], 0, s[84:85]
	v_lshl_add_u64 v[0:1], v[0:1], 0, v[176:177]
	s_nop 0
	v_lshlrev_b32_e32 v2, 16, v2
	v_mul_f32_e32 v7, 0xbfb8aa3b, v2
	v_exp_f32_e32 v7, v7
	s_nop 0
	v_add_f32_e32 v7, 1.0, v7
	v_div_scale_f32 v8, s[0:1], v7, v7, v2
	v_rcp_f32_e32 v9, v8
	s_nop 0
	v_fma_f32 v10, -v8, v9, 1.0
	v_fmac_f32_e32 v9, v10, v9
	v_div_scale_f32 v10, vcc, v2, v7, v2
	v_mul_f32_e32 v16, v10, v9
	v_fma_f32 v17, -v8, v16, v10
	v_fmac_f32_e32 v16, v17, v9
	v_fma_f32 v8, -v8, v16, v10
	v_div_fmas_f32 v8, v8, v9, v16
	v_div_fixup_f32 v2, v8, v7, v2
	v_mul_f32_e32 v2, v3, v2
	v_cvt_pk_bf16_f32 v2, v2, s0
	global_store_short v[0:1], v2, off offset:3072
	s_waitcnt vmcnt(28)
	v_mov_b32_e32 v2, v97
	v_mul_f32_e32 v3, v43, v6
	s_nop 0
	v_lshlrev_b32_e32 v2, 16, v2
	v_mul_f32_e32 v7, 0xbfb8aa3b, v2
	v_exp_f32_e32 v7, v7
	s_nop 0
	v_add_f32_e32 v7, 1.0, v7
	v_div_scale_f32 v8, s[0:1], v7, v7, v2
	v_rcp_f32_e32 v9, v8
	s_nop 0
	v_fma_f32 v10, -v8, v9, 1.0
	v_fmac_f32_e32 v9, v10, v9
	v_div_scale_f32 v10, vcc, v2, v7, v2
	v_mul_f32_e32 v16, v10, v9
	v_fma_f32 v17, -v8, v16, v10
	v_fmac_f32_e32 v16, v17, v9
	v_fma_f32 v8, -v8, v16, v10
	v_div_fmas_f32 v8, v8, v9, v16
	v_div_fixup_f32 v2, v8, v7, v2
	v_mul_f32_e32 v2, v3, v2
	v_cvt_pk_bf16_f32 v2, v2, s0
	global_store_short v[0:1], v2, off offset:3136
	s_waitcnt vmcnt(28)
	v_mov_b32_e32 v2, v98
	v_mul_f32_e32 v3, v27, v6
	s_nop 0
	v_lshlrev_b32_e32 v2, 16, v2
	v_mul_f32_e32 v7, 0xbfb8aa3b, v2
	v_exp_f32_e32 v7, v7
	s_nop 0
	v_add_f32_e32 v7, 1.0, v7
	v_div_scale_f32 v8, s[0:1], v7, v7, v2
	v_rcp_f32_e32 v9, v8
	s_nop 0
	v_fma_f32 v10, -v8, v9, 1.0
	v_fmac_f32_e32 v9, v10, v9
	v_div_scale_f32 v10, vcc, v2, v7, v2
	v_mul_f32_e32 v16, v10, v9
	v_fma_f32 v17, -v8, v16, v10
	v_fmac_f32_e32 v16, v17, v9
	v_fma_f32 v8, -v8, v16, v10
	v_div_fmas_f32 v8, v8, v9, v16
	v_div_fixup_f32 v2, v8, v7, v2
	v_mul_f32_e32 v2, v3, v2
	v_cvt_pk_bf16_f32 v2, v2, s0
	global_store_short v[0:1], v2, off offset:3200
	s_waitcnt vmcnt(28)
	v_mov_b32_e32 v2, v99
	v_mul_f32_e32 v3, v11, v6
	s_nop 0
	v_lshlrev_b32_e32 v2, 16, v2
	v_mul_f32_e32 v4, 0xbfb8aa3b, v2
	v_exp_f32_e32 v4, v4
	s_nop 0
	v_add_f32_e32 v4, 1.0, v4
	v_div_scale_f32 v5, s[0:1], v4, v4, v2
	v_rcp_f32_e32 v6, v5
	s_nop 0
	v_fma_f32 v7, -v5, v6, 1.0
	v_fmac_f32_e32 v6, v7, v6
	v_div_scale_f32 v7, vcc, v2, v4, v2
	v_mul_f32_e32 v8, v7, v6
	v_fma_f32 v9, -v5, v8, v7
	v_fmac_f32_e32 v8, v9, v6
	v_fma_f32 v5, -v5, v8, v7
	v_div_fmas_f32 v5, v5, v6, v8
	v_div_fixup_f32 v2, v5, v4, v2
	v_mul_f32_e32 v2, v3, v2
	v_cvt_pk_bf16_f32 v2, v2, s0
	global_store_short v[0:1], v2, off offset:3264
	ds_read_b128 v[0:3], v72 offset:96
	s_waitcnt lgkmcnt(0)
	v_div_scale_f32 v4, s[0:1], v0, v0, 1.0
	v_rcp_f32_e32 v5, v4
	s_nop 0
	v_fma_f32 v6, -v4, v5, 1.0
	v_fmac_f32_e32 v5, v6, v5
	v_div_scale_f32 v6, vcc, 1.0, v0, 1.0
	v_mul_f32_e32 v7, v6, v5
	v_fma_f32 v8, -v4, v7, v6
	v_fmac_f32_e32 v7, v8, v5
	v_fma_f32 v4, -v4, v7, v6
	v_div_fmas_f32 v4, v4, v5, v7
	v_div_fixup_f32 v0, v4, v0, 1.0
	v_or_b32_e32 v4, 24, v68
	v_mad_u64_u32 v[6:7], s[0:1], v4, s33, v[70:71]
	v_add_u32_e32 v7, s6, v7
	v_lshl_add_u64 v[6:7], v[6:7], 0, s[84:85]
	v_lshl_add_u64 v[8:9], v[6:7], 0, v[176:177]
	v_lshl_add_u64 v[6:7], v[8:9], 0, s[2:3]
	v_add_co_u32_e32 v8, vcc, s63, v8
	v_mov_b32_e32 v5, v69
	s_nop 0
	v_addc_co_u32_e32 v9, vcc, 0, v9, vcc
	s_waitcnt vmcnt(28)
	v_mov_b32_e32 v8, v100
	v_lshlrev_b64 v[4:5], 12, v[4:5]
	v_lshl_add_u64 v[4:5], s[82:83], 0, v[4:5]
	v_mul_f32_e32 v9, v60, v0
	v_lshl_add_u64 v[4:5], v[4:5], 0, s[84:85]
	v_lshl_add_u64 v[4:5], v[4:5], 0, v[176:177]
	s_nop 0
	v_lshlrev_b32_e32 v8, 16, v8
	v_mul_f32_e32 v10, 0xbfb8aa3b, v8
	v_exp_f32_e32 v10, v10
	s_nop 0
	v_add_f32_e32 v10, 1.0, v10
	v_div_scale_f32 v11, s[0:1], v10, v10, v8
	v_rcp_f32_e32 v16, v11
	s_nop 0
	v_fma_f32 v17, -v11, v16, 1.0
	v_fmac_f32_e32 v16, v17, v16
	v_div_scale_f32 v17, vcc, v8, v10, v8
	v_mul_f32_e32 v18, v17, v16
	v_fma_f32 v19, -v11, v18, v17
	v_fmac_f32_e32 v18, v19, v16
	v_fma_f32 v11, -v11, v18, v17
	v_div_fmas_f32 v11, v11, v16, v18
	v_div_fixup_f32 v8, v11, v10, v8
	v_mul_f32_e32 v8, v9, v8
	v_cvt_pk_bf16_f32 v8, v8, s0
	global_store_short v[4:5], v8, off offset:3072
	s_waitcnt vmcnt(28)
; __device__ __forceinline__ int crow(int r, int hi) { return (r & 3) + 8 * (r >> 2) + 4 * hi; }
; __device__ __forceinline__ unsigned cvtpk(float lo, float hi) { f32x2_t v = {lo, hi}; bf16x2_t b = __builtin_convertvector(v, bf16x2_t); return __builtin_bit_cast(unsigned, b); }
; __device__ __forceinline__ float bf2f(unsigned short h) { return __uint_as_float(((unsigned)h) << 16); }
; __device__ __forceinline__ float silu(float x) { return x / (1.0f + __expf(-x)); }
; __device__ __forceinline__ void mem_unit(const MemArgs& A, int unit, char* lds, int wv) {
;     ...
;     for (int r = 0; r < 16; ++r) { const int rr_ = crow(r, hi); const float rl = 1.0f / wsl[rr_];
;         const bf16* gp = A.proj + (grow0 + rr_) * INC + C_MG + hm * 128 + r32; bf16* yp = A.y + (grow0 + rr_) * DM + Y_M + hm * 128 + r32;
; #pragma unroll
;         for (int d0 = 0; d0 < 4; ++d0) { const float g = bf2f(gp[d0 * 32]); const float val = o[d0][r] * rl * silu(g);
;             yp[d0 * 32] = (bf16)(cvtpk(val, val) & 0xffffu); } }
	v_mov_b32_e32 v8, v101
	v_mul_f32_e32 v9, v44, v0
	s_nop 0
	v_lshlrev_b32_e32 v8, 16, v8
	v_mul_f32_e32 v10, 0xbfb8aa3b, v8
	v_exp_f32_e32 v10, v10
	s_nop 0
	v_add_f32_e32 v10, 1.0, v10
	v_div_scale_f32 v11, s[0:1], v10, v10, v8
	v_rcp_f32_e32 v16, v11
	s_nop 0
	v_fma_f32 v17, -v11, v16, 1.0
	v_fmac_f32_e32 v16, v17, v16
	v_div_scale_f32 v17, vcc, v8, v10, v8
	v_mul_f32_e32 v18, v17, v16
	v_fma_f32 v19, -v11, v18, v17
	v_fmac_f32_e32 v18, v19, v16
	v_fma_f32 v11, -v11, v18, v17
	v_div_fmas_f32 v11, v11, v16, v18
	v_div_fixup_f32 v8, v11, v10, v8
	v_mul_f32_e32 v8, v9, v8
	v_cvt_pk_bf16_f32 v8, v8, s0
	global_store_short v[4:5], v8, off offset:3136
	s_waitcnt vmcnt(28)
	v_mov_b32_e32 v8, v102
	v_mul_f32_e32 v9, v28, v0
	s_waitcnt vmcnt(28)
	v_mov_b32_e32 v6, v103
	v_mul_f32_e32 v0, v12, v0
	s_nop 0
	v_lshlrev_b32_e32 v8, 16, v8
	v_mul_f32_e32 v10, 0xbfb8aa3b, v8
	v_exp_f32_e32 v10, v10
	s_nop 0
	v_lshlrev_b32_e32 v6, 16, v6
	v_mul_f32_e32 v7, 0xbfb8aa3b, v6
	v_exp_f32_e32 v7, v7
	v_add_f32_e32 v10, 1.0, v10
	v_div_scale_f32 v11, s[0:1], v10, v10, v8
	v_rcp_f32_e32 v16, v11
	v_add_f32_e32 v7, 1.0, v7
	v_fma_f32 v17, -v11, v16, 1.0
	v_fmac_f32_e32 v16, v17, v16
	v_div_scale_f32 v17, vcc, v8, v10, v8
	v_mul_f32_e32 v18, v17, v16
	v_fma_f32 v19, -v11, v18, v17
	v_fmac_f32_e32 v18, v19, v16
	v_fma_f32 v11, -v11, v18, v17
	v_div_fmas_f32 v11, v11, v16, v18
	v_div_fixup_f32 v8, v11, v10, v8
	v_mul_f32_e32 v8, v9, v8
	v_cvt_pk_bf16_f32 v8, v8, s0
	global_store_short v[4:5], v8, off offset:3200
	v_div_scale_f32 v8, s[0:1], v7, v7, v6
	v_rcp_f32_e32 v9, v8
	s_nop 0
	v_fma_f32 v10, -v8, v9, 1.0
	v_fmac_f32_e32 v9, v10, v9
	v_div_scale_f32 v10, vcc, v6, v7, v6
	v_mul_f32_e32 v11, v10, v9
	v_fma_f32 v12, -v8, v11, v10
	v_fmac_f32_e32 v11, v12, v9
	v_fma_f32 v8, -v8, v11, v10
	v_div_fmas_f32 v8, v8, v9, v11
	v_div_fixup_f32 v6, v8, v7, v6
	v_mul_f32_e32 v0, v0, v6
	v_cvt_pk_bf16_f32 v0, v0, s0
	global_store_short v[4:5], v0, off offset:3264
	v_div_scale_f32 v0, s[0:1], v1, v1, 1.0
	v_rcp_f32_e32 v4, v0
	s_nop 0
	v_fma_f32 v5, -v0, v4, 1.0
	v_fmac_f32_e32 v4, v5, v4
	v_div_scale_f32 v5, vcc, 1.0, v1, 1.0
	v_mul_f32_e32 v6, v5, v4
	v_fma_f32 v7, -v0, v6, v5
	v_fmac_f32_e32 v6, v7, v4
	v_fma_f32 v0, -v0, v6, v5
	v_div_fmas_f32 v0, v0, v4, v6
	v_div_fixup_f32 v6, v0, v1, 1.0
	v_or_b32_e32 v0, 25, v68
	v_mad_u64_u32 v[4:5], s[0:1], v0, s33, v[70:71]
	v_add_u32_e32 v5, s6, v5
	v_lshl_add_u64 v[4:5], v[4:5], 0, s[84:85]
	v_lshl_add_u64 v[8:9], v[4:5], 0, v[176:177]
	v_lshl_add_u64 v[4:5], v[8:9], 0, s[2:3]
	v_add_co_u32_e32 v8, vcc, s63, v8
	v_mov_b32_e32 v1, v69
	s_nop 0
	v_addc_co_u32_e32 v9, vcc, 0, v9, vcc
	s_waitcnt vmcnt(28)
	v_mov_b32_e32 v7, v104
	v_lshlrev_b64 v[0:1], 12, v[0:1]
	v_lshl_add_u64 v[0:1], s[82:83], 0, v[0:1]
	v_mul_f32_e32 v8, v61, v6
	v_lshl_add_u64 v[0:1], v[0:1], 0, s[84:85]
	v_lshl_add_u64 v[0:1], v[0:1], 0, v[176:177]
	s_nop 0
	v_lshlrev_b32_e32 v7, 16, v7
	v_mul_f32_e32 v9, 0xbfb8aa3b, v7
	v_exp_f32_e32 v9, v9
	s_nop 0
	v_add_f32_e32 v9, 1.0, v9
	v_div_scale_f32 v10, s[0:1], v9, v9, v7
	v_rcp_f32_e32 v11, v10
	s_nop 0
	v_fma_f32 v12, -v10, v11, 1.0
	v_fmac_f32_e32 v11, v12, v11
	v_div_scale_f32 v12, vcc, v7, v9, v7
	v_mul_f32_e32 v16, v12, v11
	v_fma_f32 v17, -v10, v16, v12
	v_fmac_f32_e32 v16, v17, v11
	v_fma_f32 v10, -v10, v16, v12
	v_div_fmas_f32 v10, v10, v11, v16
	v_div_fixup_f32 v7, v10, v9, v7
	v_mul_f32_e32 v7, v8, v7
	v_cvt_pk_bf16_f32 v7, v7, s0
	global_store_short v[0:1], v7, off offset:3072
	s_waitcnt vmcnt(28)
	v_mov_b32_e32 v7, v105
	v_mul_f32_e32 v8, v45, v6
	s_nop 0
	v_lshlrev_b32_e32 v7, 16, v7
	v_mul_f32_e32 v9, 0xbfb8aa3b, v7
	v_exp_f32_e32 v9, v9
	s_nop 0
	v_add_f32_e32 v9, 1.0, v9
	v_div_scale_f32 v10, s[0:1], v9, v9, v7
	v_rcp_f32_e32 v11, v10
	s_nop 0
	v_fma_f32 v12, -v10, v11, 1.0
	v_fmac_f32_e32 v11, v12, v11
	v_div_scale_f32 v12, vcc, v7, v9, v7
	v_mul_f32_e32 v16, v12, v11
	v_fma_f32 v17, -v10, v16, v12
	v_fmac_f32_e32 v16, v17, v11
	v_fma_f32 v10, -v10, v16, v12
	v_div_fmas_f32 v10, v10, v11, v16
	v_div_fixup_f32 v7, v10, v9, v7
	v_mul_f32_e32 v7, v8, v7
	v_cvt_pk_bf16_f32 v7, v7, s0
	global_store_short v[0:1], v7, off offset:3136
	s_waitcnt vmcnt(28)
	v_mov_b32_e32 v7, v106
	v_mul_f32_e32 v8, v29, v6
	s_waitcnt vmcnt(28)
	v_mov_b32_e32 v4, v107
	v_mul_f32_e32 v5, v13, v6
	s_nop 0
	v_lshlrev_b32_e32 v7, 16, v7
	v_mul_f32_e32 v9, 0xbfb8aa3b, v7
	v_exp_f32_e32 v9, v9
	s_nop 0
	v_lshlrev_b32_e32 v4, 16, v4
	v_mul_f32_e32 v6, 0xbfb8aa3b, v4
	v_exp_f32_e32 v6, v6
	v_add_f32_e32 v9, 1.0, v9
	v_div_scale_f32 v10, s[0:1], v9, v9, v7
	v_rcp_f32_e32 v11, v10
	v_add_f32_e32 v6, 1.0, v6
	v_fma_f32 v12, -v10, v11, 1.0
	v_fmac_f32_e32 v11, v12, v11
	v_div_scale_f32 v12, vcc, v7, v9, v7
	v_mul_f32_e32 v16, v12, v11
	v_fma_f32 v17, -v10, v16, v12
	v_fmac_f32_e32 v16, v17, v11
	v_fma_f32 v10, -v10, v16, v12
	v_div_fmas_f32 v10, v10, v11, v16
	v_div_fixup_f32 v7, v10, v9, v7
	v_mul_f32_e32 v7, v8, v7
	v_cvt_pk_bf16_f32 v7, v7, s0
	global_store_short v[0:1], v7, off offset:3200
	v_div_scale_f32 v7, s[0:1], v6, v6, v4
	v_rcp_f32_e32 v8, v7
	s_nop 0
	v_fma_f32 v9, -v7, v8, 1.0
	v_fmac_f32_e32 v8, v9, v8
	v_div_scale_f32 v9, vcc, v4, v6, v4
	v_mul_f32_e32 v10, v9, v8
	v_fma_f32 v11, -v7, v10, v9
	v_fmac_f32_e32 v10, v11, v8
	v_fma_f32 v7, -v7, v10, v9
	v_div_fmas_f32 v7, v7, v8, v10
	v_div_fixup_f32 v4, v7, v6, v4
	v_mul_f32_e32 v4, v5, v4
	v_cvt_pk_bf16_f32 v4, v4, s0
	global_store_short v[0:1], v4, off offset:3264
	v_div_scale_f32 v0, s[0:1], v2, v2, 1.0
	v_rcp_f32_e32 v1, v0
	s_nop 0
	v_fma_f32 v4, -v0, v1, 1.0
	v_fmac_f32_e32 v1, v4, v1
	v_div_scale_f32 v4, vcc, 1.0, v2, 1.0
	v_mul_f32_e32 v5, v4, v1
	v_fma_f32 v6, -v0, v5, v4
	v_fmac_f32_e32 v5, v6, v1
	v_fma_f32 v0, -v0, v5, v4
	v_div_fmas_f32 v0, v0, v1, v5
	v_div_fixup_f32 v2, v0, v2, 1.0
	v_or_b32_e32 v0, 26, v68
	v_mad_u64_u32 v[4:5], s[0:1], v0, s33, v[70:71]
	v_add_u32_e32 v5, s6, v5
	v_lshl_add_u64 v[4:5], v[4:5], 0, s[84:85]
	v_lshl_add_u64 v[6:7], v[4:5], 0, v[176:177]
	v_lshl_add_u64 v[4:5], v[6:7], 0, s[2:3]
	v_add_co_u32_e32 v6, vcc, s63, v6
	v_mov_b32_e32 v1, v69
	s_nop 0
	v_addc_co_u32_e32 v7, vcc, 0, v7, vcc
	s_waitcnt vmcnt(28)
; __device__ __forceinline__ int crow(int r, int hi) { return (r & 3) + 8 * (r >> 2) + 4 * hi; }
; __device__ __forceinline__ unsigned cvtpk(float lo, float hi) { f32x2_t v = {lo, hi}; bf16x2_t b = __builtin_convertvector(v, bf16x2_t); return __builtin_bit_cast(unsigned, b); }
; __device__ __forceinline__ float bf2f(unsigned short h) { return __uint_as_float(((unsigned)h) << 16); }
; __device__ __forceinline__ float silu(float x) { return x / (1.0f + __expf(-x)); }
; __device__ __forceinline__ void mem_unit(const MemArgs& A, int unit, char* lds, int wv) {
;     ...
;     for (int r = 0; r < 16; ++r) { const int rr_ = crow(r, hi); const float rl = 1.0f / wsl[rr_];
;         const bf16* gp = A.proj + (grow0 + rr_) * INC + C_MG + hm * 128 + r32; bf16* yp = A.y + (grow0 + rr_) * DM + Y_M + hm * 128 + r32;
; #pragma unroll
;         for (int d0 = 0; d0 < 4; ++d0) { const float g = bf2f(gp[d0 * 32]); const float val = o[d0][r] * rl * silu(g);
;             yp[d0 * 32] = (bf16)(cvtpk(val, val) & 0xffffu); } }
;     __syncthreads();
	v_mov_b32_e32 v6, v108
	v_lshlrev_b64 v[0:1], 12, v[0:1]
	v_lshl_add_u64 v[0:1], s[82:83], 0, v[0:1]
	v_mul_f32_e32 v7, v62, v2
	v_lshl_add_u64 v[0:1], v[0:1], 0, s[84:85]
	v_lshl_add_u64 v[0:1], v[0:1], 0, v[176:177]
	v_or_b32_e32 v68, 27, v68
	s_nop 0
	v_lshlrev_b32_e32 v6, 16, v6
	v_mul_f32_e32 v8, 0xbfb8aa3b, v6
	v_exp_f32_e32 v8, v8
	s_nop 0
	v_add_f32_e32 v8, 1.0, v8
	v_div_scale_f32 v9, s[0:1], v8, v8, v6
	v_rcp_f32_e32 v10, v9
	s_nop 0
	v_fma_f32 v11, -v9, v10, 1.0
	v_fmac_f32_e32 v10, v11, v10
	v_div_scale_f32 v11, vcc, v6, v8, v6
	v_mul_f32_e32 v12, v11, v10
	v_fma_f32 v13, -v9, v12, v11
	v_fmac_f32_e32 v12, v13, v10
	v_fma_f32 v9, -v9, v12, v11
	v_div_fmas_f32 v9, v9, v10, v12
	v_div_fixup_f32 v6, v9, v8, v6
	v_mul_f32_e32 v6, v7, v6
	v_cvt_pk_bf16_f32 v6, v6, s0
	global_store_short v[0:1], v6, off offset:3072
	s_waitcnt vmcnt(28)
	v_mov_b32_e32 v6, v109
	v_mul_f32_e32 v7, v46, v2
	s_nop 0
	v_lshlrev_b32_e32 v6, 16, v6
	v_mul_f32_e32 v8, 0xbfb8aa3b, v6
	v_exp_f32_e32 v8, v8
	s_nop 0
	v_add_f32_e32 v8, 1.0, v8
	v_div_scale_f32 v9, s[0:1], v8, v8, v6
	v_rcp_f32_e32 v10, v9
	s_nop 0
	v_fma_f32 v11, -v9, v10, 1.0
	v_fmac_f32_e32 v10, v11, v10
	v_div_scale_f32 v11, vcc, v6, v8, v6
	v_mul_f32_e32 v12, v11, v10
	v_fma_f32 v13, -v9, v12, v11
	v_fmac_f32_e32 v12, v13, v10
	v_fma_f32 v9, -v9, v12, v11
	v_div_fmas_f32 v9, v9, v10, v12
	v_div_fixup_f32 v6, v9, v8, v6
	v_mul_f32_e32 v6, v7, v6
	v_cvt_pk_bf16_f32 v6, v6, s0
	global_store_short v[0:1], v6, off offset:3136
	s_waitcnt vmcnt(28)
	v_mov_b32_e32 v6, v110
	v_mul_f32_e32 v7, v30, v2
	s_waitcnt vmcnt(28)
	v_mov_b32_e32 v4, v111
	v_mul_f32_e32 v2, v14, v2
	s_nop 0
	v_lshlrev_b32_e32 v6, 16, v6
	v_mul_f32_e32 v8, 0xbfb8aa3b, v6
	v_exp_f32_e32 v8, v8
	s_nop 0
	v_lshlrev_b32_e32 v4, 16, v4
	v_mul_f32_e32 v5, 0xbfb8aa3b, v4
	v_exp_f32_e32 v5, v5
	v_add_f32_e32 v8, 1.0, v8
	v_div_scale_f32 v9, s[0:1], v8, v8, v6
	v_rcp_f32_e32 v10, v9
	v_add_f32_e32 v5, 1.0, v5
	v_fma_f32 v11, -v9, v10, 1.0
	v_fmac_f32_e32 v10, v11, v10
	v_div_scale_f32 v11, vcc, v6, v8, v6
	v_mul_f32_e32 v12, v11, v10
	v_fma_f32 v13, -v9, v12, v11
	v_fmac_f32_e32 v12, v13, v10
	v_fma_f32 v9, -v9, v12, v11
	v_div_fmas_f32 v9, v9, v10, v12
	v_div_fixup_f32 v6, v9, v8, v6
	v_mul_f32_e32 v6, v7, v6
	v_cvt_pk_bf16_f32 v6, v6, s0
	global_store_short v[0:1], v6, off offset:3200
	v_div_scale_f32 v6, s[0:1], v5, v5, v4
	v_rcp_f32_e32 v7, v6
	s_nop 0
	v_fma_f32 v8, -v6, v7, 1.0
	v_fmac_f32_e32 v7, v8, v7
	v_div_scale_f32 v8, vcc, v4, v5, v4
	v_mul_f32_e32 v9, v8, v7
	v_fma_f32 v10, -v6, v9, v8
	v_fmac_f32_e32 v9, v10, v7
	v_fma_f32 v6, -v6, v9, v8
	v_div_fmas_f32 v6, v6, v7, v9
	v_div_fixup_f32 v4, v6, v5, v4
	v_mul_f32_e32 v2, v2, v4
	v_cvt_pk_bf16_f32 v2, v2, s0
	global_store_short v[0:1], v2, off offset:3264
	v_div_scale_f32 v0, s[0:1], v3, v3, 1.0
	v_rcp_f32_e32 v1, v0
	s_nop 0
	v_fma_f32 v2, -v0, v1, 1.0
	v_fmac_f32_e32 v1, v2, v1
	v_div_scale_f32 v2, vcc, 1.0, v3, 1.0
	v_mul_f32_e32 v4, v2, v1
	v_fma_f32 v5, -v0, v4, v2
	v_fmac_f32_e32 v4, v5, v1
	v_fma_f32 v0, -v0, v4, v2
	v_div_fmas_f32 v0, v0, v1, v4
	v_div_fixup_f32 v4, v0, v3, 1.0
	v_mad_u64_u32 v[0:1], s[0:1], v68, s33, v[70:71]
	v_add_u32_e32 v1, s6, v1
	v_lshl_add_u64 v[0:1], v[0:1], 0, s[84:85]
	v_lshl_add_u64 v[6:7], v[0:1], 0, v[176:177]
	v_lshl_add_u64 v[2:3], v[6:7], 0, s[2:3]
	v_add_co_u32_e32 v6, vcc, s63, v6
	v_lshlrev_b64 v[0:1], 12, v[68:69]
	s_nop 0
	v_addc_co_u32_e32 v7, vcc, 0, v7, vcc
	s_waitcnt vmcnt(28)
	v_mov_b32_e32 v5, v157
	v_lshl_add_u64 v[0:1], s[82:83], 0, v[0:1]
	v_mul_f32_e32 v6, v63, v4
	v_lshl_add_u64 v[0:1], v[0:1], 0, s[84:85]
	v_lshl_add_u64 v[0:1], v[0:1], 0, v[176:177]
	s_mov_b64 s[6:7], 0
	s_nop 0
	v_lshlrev_b32_e32 v5, 16, v5
	v_mul_f32_e32 v7, 0xbfb8aa3b, v5
	v_exp_f32_e32 v7, v7
	s_nop 0
	v_add_f32_e32 v7, 1.0, v7
	v_div_scale_f32 v8, s[0:1], v7, v7, v5
	v_rcp_f32_e32 v9, v8
	s_nop 0
	v_fma_f32 v10, -v8, v9, 1.0
	v_fmac_f32_e32 v9, v10, v9
	v_div_scale_f32 v10, vcc, v5, v7, v5
	v_mul_f32_e32 v11, v10, v9
	v_fma_f32 v12, -v8, v11, v10
	v_fmac_f32_e32 v11, v12, v9
	v_fma_f32 v8, -v8, v11, v10
	v_div_fmas_f32 v8, v8, v9, v11
	v_div_fixup_f32 v5, v8, v7, v5
	v_mul_f32_e32 v5, v6, v5
	v_cvt_pk_bf16_f32 v5, v5, s0
	global_store_short v[0:1], v5, off offset:3072
	s_waitcnt vmcnt(28)
	v_mov_b32_e32 v5, v158
	v_mul_f32_e32 v6, v47, v4
	s_nop 0
	v_lshlrev_b32_e32 v5, 16, v5
	v_mul_f32_e32 v7, 0xbfb8aa3b, v5
	v_exp_f32_e32 v7, v7
	s_nop 0
	v_add_f32_e32 v7, 1.0, v7
	v_div_scale_f32 v8, s[0:1], v7, v7, v5
	v_rcp_f32_e32 v9, v8
	s_nop 0
	v_fma_f32 v10, -v8, v9, 1.0
	v_fmac_f32_e32 v9, v10, v9
	v_div_scale_f32 v10, vcc, v5, v7, v5
	v_mul_f32_e32 v11, v10, v9
	v_fma_f32 v12, -v8, v11, v10
	v_fmac_f32_e32 v11, v12, v9
	v_fma_f32 v8, -v8, v11, v10
	v_div_fmas_f32 v8, v8, v9, v11
	v_div_fixup_f32 v5, v8, v7, v5
	v_mul_f32_e32 v5, v6, v5
	v_cvt_pk_bf16_f32 v5, v5, s0
	global_store_short v[0:1], v5, off offset:3136
	s_waitcnt vmcnt(28)
	v_mov_b32_e32 v5, v159
	v_mul_f32_e32 v6, v31, v4
	s_waitcnt vmcnt(28)
	v_mov_b32_e32 v2, v160
	v_mul_f32_e32 v3, v15, v4
	s_nop 0
	v_lshlrev_b32_e32 v5, 16, v5
	v_mul_f32_e32 v7, 0xbfb8aa3b, v5
	v_exp_f32_e32 v7, v7
	s_nop 0
	v_lshlrev_b32_e32 v2, 16, v2
	v_mul_f32_e32 v4, 0xbfb8aa3b, v2
	v_exp_f32_e32 v4, v4
	v_add_f32_e32 v7, 1.0, v7
	v_div_scale_f32 v8, s[0:1], v7, v7, v5
	v_rcp_f32_e32 v9, v8
	v_add_f32_e32 v4, 1.0, v4
	v_fma_f32 v10, -v8, v9, 1.0
	v_fmac_f32_e32 v9, v10, v9
	v_div_scale_f32 v10, vcc, v5, v7, v5
	v_mul_f32_e32 v11, v10, v9
	v_fma_f32 v12, -v8, v11, v10
	v_fmac_f32_e32 v11, v12, v9
	v_fma_f32 v8, -v8, v11, v10
	v_div_fmas_f32 v8, v8, v9, v11
	v_div_fixup_f32 v5, v8, v7, v5
	v_mul_f32_e32 v5, v6, v5
	v_cvt_pk_bf16_f32 v5, v5, s0
	global_store_short v[0:1], v5, off offset:3200
	v_div_scale_f32 v5, s[0:1], v4, v4, v2
	v_rcp_f32_e32 v6, v5
	s_nop 0
	v_fma_f32 v7, -v5, v6, 1.0
	v_fmac_f32_e32 v6, v7, v6
	v_div_scale_f32 v7, vcc, v2, v4, v2
	v_mul_f32_e32 v8, v7, v6
	v_fma_f32 v9, -v5, v8, v7
	v_fmac_f32_e32 v8, v9, v6
	v_fma_f32 v5, -v5, v8, v7
	v_div_fmas_f32 v5, v5, v6, v8
	v_div_fixup_f32 v2, v5, v4, v2
	v_mul_f32_e32 v2, v3, v2
	v_cvt_pk_bf16_f32 v2, v2, s0
	global_store_short v[0:1], v2, off offset:3264
	s_barrier

; __device__ __forceinline__ int opaque_tid(int wv) { int lane_; asm volatile("v_mbcnt_lo_u32_b32 %0, -1, 0\n\tv_mbcnt_hi_u32_b32 %0, -1, %0" : "=v"(lane_)); return wv * 64 + lane_; }
; __device__ __forceinline__ int crow(int r, int hi) { return (r & 3) + 8 * (r >> 2) + 4 * hi; }
; __device__ __forceinline__ void diff_unit(const DiffArgs& A, int b, int h, int qb, char* lds, int wv) {
;     ...
;     { auto rr = __builtin_amdgcn_permlane32_swap(__float_as_uint(l_reg), __float_as_uint(l_reg), false, false);
;       l_reg = __uint_as_float(rr[0]) + __uint_as_float(rr[1]); }
;     const int tid_e = opaque_tid(wv), lane_e = tid_e & 63;
;     ...
;     if (hi == 0) wsl[r32] = l_reg;
;     asm volatile("s_waitcnt lgkmcnt(0)" ::: "memory");
;     float rli[16];
; #pragma unroll
;     for (int r = 0; r < 16; ++r) rli[r] = (c ? lam : 1.0f) / wsl[crow(r, hi)];
;     __syncthreads();
;     ...
;       const bf16* gp = (const bf16*)(Pb + (size_t)(qb * 128) * (INC * 2) + C_DG * 2 + (unsigned)((row * INC + cq * 32) * 2));
;       bf16* yp = (bf16*)((char*)A.y + ((size_t)(b * SEQ + qb * 128) * DM + Y_D + h * 128) * 2 + (unsigned)((row * DM + cq * 32) * 2)); const float* gh = A.ghead + cq * 32;
; #pragma unroll
;       for (int i = 0; i < 4; ++i) { const bf16x8 g8 = *reinterpret_cast<const bf16x8*>(gp + 8 * i); const f32x4 h0 = *(const f32x4*)(gh + 8 * i), h1 = *(const f32x4*)(gh + 8 * i + 4);
.LBB0_263:
	s_and_b32 s3, s3, 0x3fffffc0
	s_lshl_b32 s3, s3, 2
	s_add_i32 s3, s3, 0
	s_add_i32 s3, s3, 0x20000
	s_setprio 0
	s_nop 3
	v_mov_b32_e32 v65, v96
	v_mbcnt_lo_u32_b32 v68, -1, 0
	v_mbcnt_hi_u32_b32 v68, -1, v68
	s_mul_i32 s100, s27, 0x1c0000
	s_add_u32 s100, s31, s100
	s_addc_u32 s101, s84, 0
	v_add_u32_e32 v148, s44, v68
	v_lshrrev_b32_e32 v148, 2, v148
	v_mul_u32_u24_e32 v148, 0x1c00, v148
	v_lshlrev_b32_e32 v149, 5, v68
	v_and_b32_e32 v149, 0x60, v149
	v_or_b32_e32 v148, v148, v149
	v_lshlrev_b32_e32 v148, 1, v148
	v_add_u32_e32 v148, 0x2a00, v148
	v_lshlrev_b32_e32 v149, 2, v149
	global_load_dwordx4 v[100:103], v148, s[100:101]
	global_load_dwordx4 v[104:107], v148, s[100:101] offset:16
	global_load_dwordx4 v[108:111], v148, s[100:101] offset:32
	global_load_dwordx4 v[112:115], v148, s[100:101] offset:48
	global_load_dwordx4 v[116:119], v149, s[38:39]
	global_load_dwordx4 v[120:123], v149, s[38:39] offset:16
	global_load_dwordx4 v[124:127], v149, s[38:39] offset:32
	global_load_dwordx4 v[128:131], v149, s[38:39] offset:48
	global_load_dwordx4 v[132:135], v149, s[38:39] offset:64
	global_load_dwordx4 v[136:139], v149, s[38:39] offset:80
	global_load_dwordx4 v[140:143], v149, s[38:39] offset:96
	global_load_dwordx4 v[144:147], v149, s[38:39] offset:112
	s_nop 1
	v_permlane32_swap_b32_e32 v96, v65
	v_and_b32_e32 v64, 63, v68
	v_cmp_gt_u32_e32 vcc, 32, v64
	v_and_b32_e32 v84, 31, v68
	s_and_saveexec_b64 s[6:7], vcc
	v_readlane_b32 s60, v254, 40
	s_movk_i32 s61, 0x4000
	s_movk_i32 s63, 0x3000
	v_add_f32_e32 v65, v96, v65
	v_lshl_add_u32 v66, v84, 2, s3
	ds_write_b32 v66, v65
	s_or_b64 exec, exec, s[6:7]
	v_lshrrev_b32_e32 v78, 5, v64
	s_waitcnt lgkmcnt(0)
	v_mov_b32_e32 v64, s2
	v_lshl_add_u32 v82, v78, 4, s3
	v_cndmask_b32_e64 v85, v64, 1.0, s[36:37]
	ds_read_b128 v[70:73], v82
	ds_read_b128 v[64:67], v82 offset:32
	s_cmp_lg_u32 s0, 1
	s_waitcnt lgkmcnt(0)
	v_div_scale_f32 v69, s[2:3], v70, v70, v85
	v_rcp_f32_e32 v74, v69
	s_nop 0
	v_fma_f32 v75, -v69, v74, 1.0
	v_fmac_f32_e32 v74, v75, v74
	v_div_scale_f32 v75, vcc, v85, v70, v85
	v_mul_f32_e32 v76, v75, v74
	v_fma_f32 v77, -v69, v76, v75
	v_fmac_f32_e32 v76, v77, v74
	v_fma_f32 v69, -v69, v76, v75
	v_div_fmas_f32 v69, v69, v74, v76
	v_div_fixup_f32 v81, v69, v70, v85
	v_div_scale_f32 v69, s[2:3], v71, v71, v85
	v_rcp_f32_e32 v70, v69
	s_nop 0
	v_fma_f32 v74, -v69, v70, 1.0
	v_fmac_f32_e32 v70, v74, v70
	v_div_scale_f32 v74, vcc, v85, v71, v85
	v_mul_f32_e32 v75, v74, v70
	v_fma_f32 v76, -v69, v75, v74
	v_fmac_f32_e32 v75, v76, v70
	v_fma_f32 v69, -v69, v75, v74
	v_div_fmas_f32 v69, v69, v70, v75
	v_div_fixup_f32 v80, v69, v71, v85
	v_div_scale_f32 v69, s[2:3], v72, v72, v85
	v_rcp_f32_e32 v70, v69
	s_nop 0
	v_fma_f32 v71, -v69, v70, 1.0
	v_fmac_f32_e32 v70, v71, v70
	v_div_scale_f32 v71, vcc, v85, v72, v85
	v_mul_f32_e32 v74, v71, v70
	v_fma_f32 v75, -v69, v74, v71
	v_fmac_f32_e32 v74, v75, v70
	v_fma_f32 v69, -v69, v74, v71
	v_div_fmas_f32 v69, v69, v70, v74
	v_div_fixup_f32 v79, v69, v72, v85
	v_div_scale_f32 v69, s[2:3], v73, v73, v85
	v_rcp_f32_e32 v70, v69
	s_nop 0
	v_fma_f32 v71, -v69, v70, 1.0
	v_fmac_f32_e32 v70, v71, v70
	v_div_scale_f32 v71, vcc, v85, v73, v85
	v_mul_f32_e32 v72, v71, v70
	v_fma_f32 v74, -v69, v72, v71
	v_fmac_f32_e32 v72, v74, v70
	v_fma_f32 v69, -v69, v72, v71
	v_div_fmas_f32 v69, v69, v70, v72
	v_div_fixup_f32 v77, v69, v73, v85
	v_div_scale_f32 v69, s[2:3], v64, v64, v85
	v_rcp_f32_e32 v70, v69
	s_nop 0
	v_fma_f32 v71, -v69, v70, 1.0
	v_fmac_f32_e32 v70, v71, v70
	v_div_scale_f32 v71, vcc, v85, v64, v85
	v_mul_f32_e32 v72, v71, v70
	v_fma_f32 v73, -v69, v72, v71
	v_fmac_f32_e32 v72, v73, v70
	v_fma_f32 v69, -v69, v72, v71
	v_div_fmas_f32 v69, v69, v70, v72
	v_div_fixup_f32 v76, v69, v64, v85
	v_div_scale_f32 v64, s[2:3], v65, v65, v85
	v_rcp_f32_e32 v69, v64
	s_nop 0
	v_fma_f32 v70, -v64, v69, 1.0
	v_fmac_f32_e32 v69, v70, v69
	v_div_scale_f32 v70, vcc, v85, v65, v85
	v_mul_f32_e32 v71, v70, v69
	v_fma_f32 v72, -v64, v71, v70
	v_fmac_f32_e32 v71, v72, v69
	v_fma_f32 v64, -v64, v71, v70
	v_div_fmas_f32 v64, v64, v69, v71
	v_div_fixup_f32 v75, v64, v65, v85
	v_div_scale_f32 v64, s[2:3], v66, v66, v85
	v_rcp_f32_e32 v65, v64
	s_nop 0
	v_fma_f32 v69, -v64, v65, 1.0
	v_fmac_f32_e32 v65, v69, v65
	v_div_scale_f32 v69, vcc, v85, v66, v85
	v_mul_f32_e32 v70, v69, v65
	v_fma_f32 v71, -v64, v70, v69
	v_fmac_f32_e32 v70, v71, v65
	v_fma_f32 v64, -v64, v70, v69
	v_div_fmas_f32 v64, v64, v65, v70
	v_div_fixup_f32 v74, v64, v66, v85
	v_div_scale_f32 v64, s[2:3], v67, v67, v85
	v_rcp_f32_e32 v65, v64
	s_nop 0
	v_fma_f32 v66, -v64, v65, 1.0
	v_fmac_f32_e32 v65, v66, v65
	v_div_scale_f32 v66, vcc, v85, v67, v85
	v_mul_f32_e32 v69, v66, v65
	v_fma_f32 v70, -v64, v69, v66
	v_fmac_f32_e32 v69, v70, v65
	v_fma_f32 v64, -v64, v69, v66
	v_div_fmas_f32 v64, v64, v65, v69
	v_div_fixup_f32 v73, v64, v67, v85
	ds_read_b128 v[64:67], v82 offset:64
	s_waitcnt lgkmcnt(0)
	v_div_scale_f32 v69, s[2:3], v64, v64, v85
	v_rcp_f32_e32 v70, v69
	s_nop 0
	v_fma_f32 v71, -v69, v70, 1.0
	v_fmac_f32_e32 v70, v71, v70
	v_div_scale_f32 v71, vcc, v85, v64, v85
	v_mul_f32_e32 v72, v71, v70
	v_fma_f32 v83, -v69, v72, v71
	v_fmac_f32_e32 v72, v83, v70
	v_fma_f32 v69, -v69, v72, v71
	v_div_fmas_f32 v69, v69, v70, v72
	v_div_fixup_f32 v72, v69, v64, v85
	v_div_scale_f32 v64, s[2:3], v65, v65, v85
	v_rcp_f32_e32 v69, v64
	s_nop 0
	v_fma_f32 v70, -v64, v69, 1.0
	v_fmac_f32_e32 v69, v70, v69
	v_div_scale_f32 v70, vcc, v85, v65, v85
	v_mul_f32_e32 v71, v70, v69
	v_fma_f32 v83, -v64, v71, v70
	v_fmac_f32_e32 v71, v83, v69
	v_fma_f32 v64, -v64, v71, v70
	v_div_fmas_f32 v64, v64, v69, v71
	v_div_fixup_f32 v71, v64, v65, v85
	v_div_scale_f32 v64, s[2:3], v66, v66, v85
	v_rcp_f32_e32 v65, v64
	s_nop 0
	v_fma_f32 v69, -v64, v65, 1.0
	v_fmac_f32_e32 v65, v69, v65
	v_div_scale_f32 v69, vcc, v85, v66, v85
	v_mul_f32_e32 v70, v69, v65
	v_fma_f32 v83, -v64, v70, v69
	v_fmac_f32_e32 v70, v83, v65
	v_fma_f32 v64, -v64, v70, v69
	v_div_fmas_f32 v64, v64, v65, v70
	v_div_fixup_f32 v70, v64, v66, v85
	v_div_scale_f32 v64, s[2:3], v67, v67, v85
	v_rcp_f32_e32 v65, v64
	s_nop 0
	v_fma_f32 v66, -v64, v65, 1.0
	v_fmac_f32_e32 v65, v66, v65
	v_div_scale_f32 v66, vcc, v85, v67, v85
	v_mul_f32_e32 v69, v66, v65
	v_fma_f32 v83, -v64, v69, v66
	v_fmac_f32_e32 v69, v83, v65
	v_fma_f32 v64, -v64, v69, v66
	v_div_fmas_f32 v64, v64, v65, v69
	v_div_fixup_f32 v69, v64, v67, v85
	ds_read_b128 v[64:67], v82 offset:96
	s_waitcnt vmcnt(12) lgkmcnt(0)
	s_barrier
; __device__ __forceinline__ int crow(int r, int hi) { return (r & 3) + 8 * (r >> 2) + 4 * hi; }
; __device__ __forceinline__ void diff_unit(const DiffArgs& A, int b, int h, int qb, char* lds, int wv) {
;     ...
;     for (int r = 0; r < 16; ++r) rli[r] = (c ? lam : 1.0f) / wsl[crow(r, hi)];
;     __syncthreads();
;     float* OS = (float*)lds;
;     if (c == 1) {
; #pragma unroll
;         for (int r = 0; r < 16; ++r) { float* orow = OS + (wq * 32 + crow(r, hi)) * 132 + r32;
; #pragma unroll
;             for (int d0 = 0; d0 < 4; ++d0) orow[d0 * 32] = o[d0][r] * rli[r]; }
;     }
	v_div_scale_f32 v82, s[2:3], v64, v64, v85
	v_rcp_f32_e32 v83, v82
	s_nop 0
	v_fma_f32 v86, -v82, v83, 1.0
	v_fmac_f32_e32 v83, v86, v83
	v_div_scale_f32 v86, vcc, v85, v64, v85
	v_mul_f32_e32 v87, v86, v83
	v_fma_f32 v88, -v82, v87, v86
	v_fmac_f32_e32 v87, v88, v83
	v_fma_f32 v82, -v82, v87, v86
	v_div_fmas_f32 v82, v82, v83, v87
	v_div_fixup_f32 v82, v82, v64, v85
	v_div_scale_f32 v64, s[2:3], v65, v65, v85
	v_rcp_f32_e32 v83, v64
	s_nop 0
	v_fma_f32 v86, -v64, v83, 1.0
	v_fmac_f32_e32 v83, v86, v83
	v_div_scale_f32 v86, vcc, v85, v65, v85
	v_mul_f32_e32 v87, v86, v83
	v_fma_f32 v88, -v64, v87, v86
	v_fmac_f32_e32 v87, v88, v83
	v_fma_f32 v64, -v64, v87, v86
	v_div_fmas_f32 v64, v64, v83, v87
	v_div_fixup_f32 v83, v64, v65, v85
	v_div_scale_f32 v64, s[2:3], v66, v66, v85
	v_rcp_f32_e32 v65, v64
	s_nop 0
	v_fma_f32 v86, -v64, v65, 1.0
	v_fmac_f32_e32 v65, v86, v65
	v_div_scale_f32 v86, vcc, v85, v66, v85
	v_mul_f32_e32 v87, v86, v65
	v_fma_f32 v88, -v64, v87, v86
	v_fmac_f32_e32 v87, v88, v65
	v_fma_f32 v64, -v64, v87, v86
	v_div_fmas_f32 v64, v64, v65, v87
	v_div_fixup_f32 v65, v64, v66, v85
	v_div_scale_f32 v64, s[2:3], v67, v67, v85
	v_rcp_f32_e32 v66, v64
	s_nop 0
	v_fma_f32 v86, -v64, v66, 1.0
	v_fmac_f32_e32 v66, v86, v66
	v_div_scale_f32 v86, vcc, v85, v67, v85
	v_mul_f32_e32 v87, v86, v66
	v_fma_f32 v88, -v64, v87, v86
	v_fmac_f32_e32 v87, v88, v66
	v_fma_f32 v64, -v64, v87, v86
	v_div_fmas_f32 v64, v64, v66, v87
	v_div_fixup_f32 v64, v64, v67, v85
	v_lshlrev_b32_e32 v66, 2, v84
	s_cbranch_scc1 .LBB0_267
	v_lshl_or_b32 v67, v78, 2, s1
	v_mul_u32_u24_e32 v67, 0x210, v67
	v_add3_u32 v67, 0, v66, v67
	v_mul_f32_e32 v84, v48, v81
	v_mul_f32_e32 v85, v32, v81
	ds_write2_b32 v67, v84, v85 offset1:32
	v_mul_f32_e32 v84, v16, v81
	v_mul_f32_e32 v85, v0, v81
	ds_write2_b32 v67, v84, v85 offset0:64 offset1:96
	v_mul_f32_e32 v84, v49, v80
	v_mul_f32_e32 v85, v33, v80
	ds_write2_b32 v67, v84, v85 offset0:132 offset1:164
	v_mul_f32_e32 v84, v17, v80
	v_mul_f32_e32 v85, v1, v80
	ds_write2_b32 v67, v84, v85 offset0:196 offset1:228
	v_mul_f32_e32 v84, v50, v79
	v_mul_f32_e32 v85, v34, v79
	v_add_u32_e32 v86, 0x400, v67
	ds_write2_b32 v86, v84, v85 offset0:8 offset1:40
	v_mul_f32_e32 v84, v18, v79
	v_mul_f32_e32 v85, v2, v79
	ds_write2_b32 v86, v84, v85 offset0:72 offset1:104
	v_mul_f32_e32 v84, v51, v77
	v_mul_f32_e32 v85, v35, v77
	ds_write2_b32 v86, v84, v85 offset0:140 offset1:172
	v_mul_f32_e32 v84, v19, v77
	v_mul_f32_e32 v85, v3, v77
	ds_write2_b32 v86, v84, v85 offset0:204 offset1:236
	v_mul_f32_e32 v84, v52, v76
	v_mul_f32_e32 v85, v36, v76
	v_add_u32_e32 v86, 0x1000, v67
	ds_write2_b32 v86, v84, v85 offset0:32 offset1:64
	v_mul_f32_e32 v84, v20, v76
	v_mul_f32_e32 v85, v4, v76
	ds_write2_b32 v86, v84, v85 offset0:96 offset1:128
	v_mul_f32_e32 v84, v53, v75
	v_mul_f32_e32 v85, v37, v75
	ds_write2_b32 v86, v84, v85 offset0:164 offset1:196
	v_mul_f32_e32 v84, v21, v75
	v_mul_f32_e32 v85, v5, v75
	v_add_u32_e32 v86, 0x1200, v67
	ds_write2_b32 v86, v84, v85 offset0:100 offset1:132
	v_mul_f32_e32 v84, v54, v74
	v_mul_f32_e32 v85, v38, v74
	v_add_u32_e32 v86, 0x1400, v67
	ds_write2_b32 v86, v84, v85 offset0:40 offset1:72
	v_mul_f32_e32 v84, v22, v74
	v_mul_f32_e32 v85, v6, v74
	ds_write2_b32 v86, v84, v85 offset0:104 offset1:136
	v_mul_f32_e32 v84, v55, v73
	v_mul_f32_e32 v85, v39, v73
	ds_write2_b32 v86, v84, v85 offset0:172 offset1:204
	v_mul_f32_e32 v84, v23, v73
	v_mul_f32_e32 v85, v7, v73
	v_add_u32_e32 v86, 0x1600, v67
	ds_write2_b32 v86, v84, v85 offset0:108 offset1:140
	v_mul_f32_e32 v84, v56, v72
	v_mul_f32_e32 v85, v40, v72
	v_add_u32_e32 v86, 0x2000, v67
	ds_write2_b32 v86, v84, v85 offset0:64 offset1:96
	v_mul_f32_e32 v84, v24, v72
	v_mul_f32_e32 v85, v8, v72
	ds_write2_b32 v86, v84, v85 offset0:128 offset1:160
	v_mul_f32_e32 v84, v57, v71
	v_mul_f32_e32 v85, v41, v71
	ds_write2_b32 v86, v84, v85 offset0:196 offset1:228
	v_mul_f32_e32 v84, v25, v71
	v_mul_f32_e32 v85, v9, v71
	v_add_u32_e32 v86, 0x2400, v67
	ds_write2_b32 v86, v84, v85 offset0:4 offset1:36
	v_mul_f32_e32 v84, v58, v70
	v_mul_f32_e32 v85, v42, v70
	ds_write2_b32 v86, v84, v85 offset0:72 offset1:104
	v_mul_f32_e32 v84, v26, v70
	v_mul_f32_e32 v85, v10, v70
	ds_write2_b32 v86, v84, v85 offset0:136 offset1:168
	v_mul_f32_e32 v84, v59, v69
	v_mul_f32_e32 v85, v43, v69
	ds_write2_b32 v86, v84, v85 offset0:204 offset1:236
	v_mul_f32_e32 v84, v27, v69
	v_mul_f32_e32 v85, v11, v69
	v_add_u32_e32 v86, 0x2800, v67
	ds_write2_b32 v86, v84, v85 offset0:12 offset1:44
	v_mul_f32_e32 v84, v60, v82
	v_mul_f32_e32 v85, v44, v82
	v_add_u32_e32 v86, 0x3000, v67
	ds_write2_b32 v86, v84, v85 offset0:96 offset1:128
	v_mul_f32_e32 v84, v28, v82
	v_mul_f32_e32 v85, v12, v82
	ds_write2_b32 v86, v84, v85 offset0:160 offset1:192
	v_mul_f32_e32 v84, v61, v83
	v_mul_f32_e32 v85, v45, v83
	v_add_u32_e32 v86, 0x3200, v67
	ds_write2_b32 v86, v84, v85 offset0:100 offset1:132
	v_mul_f32_e32 v84, v29, v83
	v_mul_f32_e32 v85, v13, v83
	v_add_u32_e32 v86, 0x3400, v67
	ds_write2_b32 v86, v84, v85 offset0:36 offset1:68
	v_mul_f32_e32 v84, v62, v65
	v_mul_f32_e32 v85, v46, v65
	ds_write2_b32 v86, v84, v85 offset0:104 offset1:136
	v_mul_f32_e32 v84, v30, v65
	v_mul_f32_e32 v85, v14, v65
	ds_write2_b32 v86, v84, v85 offset0:168 offset1:200
	v_mul_f32_e32 v84, v63, v64
	v_mul_f32_e32 v85, v47, v64
	v_add_u32_e32 v86, 0x3600, v67
	ds_write2_b32 v86, v84, v85 offset0:108 offset1:140
	v_mul_f32_e32 v84, v31, v64
	v_mul_f32_e32 v85, v15, v64
	v_add_u32_e32 v67, 0x3800, v67
	ds_write2_b32 v67, v84, v85 offset0:44 offset1:76

; template <int X> __device__ __forceinline__ float swz_xor(float v) { return __int_as_float(__builtin_amdgcn_ds_swizzle(__float_as_int(v), (X << 10) | 0x1f)); }
; __device__ __forceinline__ void diff_unit(const DiffArgs& A, int b, int h, int qb, char* lds, int wv) {
;     ...
;     __syncthreads();
;     { const int row = tid >> 2, cq = tid & 3; const float* src = OS + row * 132 + cq * 32;
;       f32x4 v[8]; float ss = 0.f;
; #pragma unroll
;       for (int i = 0; i < 8; ++i) { v[i] = *(const f32x4*)(src + 4 * i); const f32x4 q = v[i] * v[i]; ss += (q.x + q.y) + (q.z + q.w); }
;       ss += swz_xor<1>(ss); ss += swz_xor<2>(ss);
;       const float rn = (1.0f - lam_init) / sqrtf(ss * (1.0f / 128.0f) + EPS);
;       const bf16* gp = (const bf16*)(Pb + (size_t)(qb * 128) * (INC * 2) + C_DG * 2 + (unsigned)((row * INC + cq * 32) * 2));
;       bf16* yp = (bf16*)((char*)A.y + ((size_t)(b * SEQ + qb * 128) * DM + Y_D + h * 128) * 2 + (unsigned)((row * DM + cq * 32) * 2)); const float* gh = A.ghead + cq * 32;
; #pragma unroll
;       for (int i = 0; i < 4; ++i) { const bf16x8 g8 = *reinterpret_cast<const bf16x8*>(gp + 8 * i); const f32x4 h0 = *(const f32x4*)(gh + 8 * i), h1 = *(const f32x4*)(gh + 8 * i + 4);
.LBB0_269:
	v_add_u32_e32 v0, s44, v68
	v_lshlrev_b32_e32 v1, 5, v68
	v_ashrrev_i32_e32 v45, 2, v0
	s_movk_i32 s0, 0x210
	v_and_b32_e32 v49, 0x60, v1
	v_mul_lo_u32 v0, v45, s0
	v_lshlrev_b32_e32 v48, 2, v49
	v_add3_u32 v37, 0, v0, v48
	s_waitcnt lgkmcnt(0)
	s_barrier
	ds_read_b128 v[28:31], v37
	ds_read_b128 v[24:27], v37 offset:16
	ds_read_b128 v[20:23], v37 offset:32
	ds_read_b128 v[16:19], v37 offset:48
	s_mov_b32 s0, 0xf800000
	s_waitcnt lgkmcnt(3)
	v_pk_mul_f32 v[2:3], v[28:29], v[28:29]
	s_waitcnt lgkmcnt(2)
	v_pk_mul_f32 v[6:7], v[24:25], v[24:25]
	v_pk_mul_f32 v[0:1], v[30:31], v[30:31]
	v_pk_mul_f32 v[4:5], v[26:27], v[26:27]
	v_mov_b32_e32 v8, v2
	v_mov_b32_e32 v9, v6
	v_mov_b32_e32 v6, v3
	v_pk_add_f32 v[2:3], v[8:9], v[6:7]
	v_mov_b32_e32 v6, v0
	v_mov_b32_e32 v7, v4
	v_mov_b32_e32 v4, v1
	ds_read_b128 v[8:11], v37 offset:64
	v_pk_add_f32 v[0:1], v[6:7], v[4:5]
	s_waitcnt lgkmcnt(2)
	v_pk_mul_f32 v[4:5], v[20:21], v[20:21]
	v_pk_add_f32 v[0:1], v[2:3], v[0:1]
	v_pk_mul_f32 v[2:3], v[22:23], v[22:23]
	v_pk_add_f32 v[0:1], v[0:1], v[0:1] op_sel:[0,1] op_sel_hi:[1,0]
	v_pk_mov_b32 v[6:7], v[4:5], v[2:3] op_sel:[1,0]
	v_mov_b32_e32 v5, v3
	v_pk_add_f32 v[2:3], v[6:7], v[4:5]
	s_waitcnt lgkmcnt(1)
	v_pk_mul_f32 v[4:5], v[18:19], v[18:19]
	v_pk_add_f32 v[2:3], v[2:3], v[2:3] op_sel:[0,1] op_sel_hi:[1,0]
	v_pk_mul_f32 v[6:7], v[16:17], v[16:17]
	s_waitcnt lgkmcnt(0)
	v_pk_mul_f32 v[12:13], v[10:11], v[10:11]
	v_pk_mul_f32 v[14:15], v[8:9], v[8:9]
	v_add_f32_e32 v6, v6, v7
	v_add_f32_e32 v4, v4, v5
	v_mov_b32_e32 v1, v14
	v_mov_b32_e32 v3, v15
	v_mov_b32_e32 v7, v12
	v_mov_b32_e32 v5, v13
	ds_read_b128 v[12:15], v37 offset:80
	v_pk_add_f32 v[0:1], v[0:1], v[2:3]
	v_pk_add_f32 v[2:3], v[6:7], v[4:5]
	s_movk_i32 s2, 0x1c00
	v_pk_add_f32 v[0:1], v[0:1], v[2:3]
	s_waitcnt lgkmcnt(0)
	v_pk_mul_f32 v[2:3], v[12:13], v[12:13]
	v_pk_add_f32 v[32:33], v[0:1], v[0:1] op_sel:[0,1] op_sel_hi:[1,0]
	v_pk_mul_f32 v[0:1], v[14:15], v[14:15]
	s_nop 0
	v_pk_mov_b32 v[4:5], v[2:3], v[0:1] op_sel:[1,0]
	v_mov_b32_e32 v3, v1
	v_pk_add_f32 v[0:1], v[4:5], v[2:3]
	s_nop 0
	v_pk_add_f32 v[34:35], v[0:1], v[0:1] op_sel:[0,1] op_sel_hi:[1,0]
	ds_read_b128 v[0:3], v37 offset:96
	s_waitcnt lgkmcnt(0)
	v_pk_mul_f32 v[4:5], v[2:3], v[2:3]
	v_pk_mul_f32 v[6:7], v[0:1], v[0:1]
	v_add_f32_e32 v38, v4, v5
	v_add_f32_e32 v36, v6, v7
	ds_read_b128 v[4:7], v37 offset:112
	s_waitcnt lgkmcnt(0)
	v_pk_mul_f32 v[40:41], v[6:7], v[6:7]
	v_pk_mul_f32 v[42:43], v[4:5], v[4:5]
	v_mov_b32_e32 v37, v40
	v_mov_b32_e32 v33, v42
	v_mov_b32_e32 v35, v43
	v_mov_b32_e32 v39, v41
	v_pk_add_f32 v[32:33], v[32:33], v[34:35]
	v_pk_add_f32 v[34:35], v[36:37], v[38:39]
	s_nop 0
	v_pk_add_f32 v[32:33], v[32:33], v[34:35]
	s_nop 0
	v_add_f32_e32 v32, v32, v33
	ds_swizzle_b32 v33, v32 offset:swizzle(SWAP,1)
	s_waitcnt lgkmcnt(0)
	v_add_f32_e32 v32, v32, v33
	ds_swizzle_b32 v33, v32 offset:swizzle(SWAP,2)
	s_waitcnt lgkmcnt(0)
	v_add_f32_e32 v32, v32, v33
	v_fmamk_f32 v32, v32, 0x3c000000, v224
	v_cmp_gt_f32_e32 vcc, s0, v32
	v_mul_f32_e32 v34, 0x4f800000, v32
	v_sub_f32_e64 v33, 1.0, s22
	v_cndmask_b32_e32 v32, v32, v34, vcc
	v_sqrt_f32_e32 v34, v32
	s_nop 0
	v_add_u32_e32 v35, -1, v34
	v_fma_f32 v36, -v35, v34, v32
	v_cmp_ge_f32_e64 s[36:37], 0, v36
	v_add_u32_e32 v36, 1, v34
	s_nop 0
	v_cndmask_b32_e64 v35, v34, v35, s[36:37]
	v_fma_f32 v34, -v36, v34, v32
	v_cmp_lt_f32_e64 s[36:37], 0, v34
	s_nop 1
	v_cndmask_b32_e64 v34, v35, v36, s[36:37]
	v_mul_f32_e32 v35, 0x37800000, v34
	v_cndmask_b32_e32 v34, v34, v35, vcc
	v_cmp_class_f32_e32 vcc, v32, v250
	s_nop 1
	v_cndmask_b32_e32 v32, v34, v32, vcc
	v_div_scale_f32 v34, s[0:1], v32, v32, v33
	v_rcp_f32_e32 v35, v34
	s_mul_i32 s0, s27, 0x1c0000
	s_add_u32 s0, s31, s0
	s_addc_u32 s1, s84, 0
	v_fma_f32 v36, -v34, v35, 1.0
	v_fmac_f32_e32 v35, v36, v35
	v_div_scale_f32 v36, vcc, v33, v32, v33
	v_mul_f32_e32 v37, v36, v35
	v_fma_f32 v38, -v34, v37, v36
	v_fmac_f32_e32 v37, v38, v35
	v_fma_f32 v34, -v34, v37, v36
	v_div_fmas_f32 v34, v34, v35, v37
	v_div_fixup_f32 v44, v34, v32, v33
	v_mul_lo_u32 v32, v45, s2
	v_or_b32_e32 v32, v32, v49
	v_lshlrev_b32_e32 v176, 1, v32
	v_lshl_add_u64 v[32:33], s[0:1], 0, v[176:177]
	s_mov_b64 s[0:1], 0x2a00
	v_lshl_add_u64 v[46:47], v[32:33], 0, s[0:1]
	s_lshl_b32 s1, s27, 18
	s_lshl_b32 s0, s79, 24
	s_sub_i32 s1, s1, s30
	s_add_i32 s0, s1, s0
	s_add_i32 s84, s0, 0x580
	s_lshl_b64 s[0:1], s[84:85], 1
	s_add_u32 s6, s82, s0
	s_movk_i32 s0, 0x2000
	v_add_co_u32_e32 v32, vcc, s0, v32
	v_lshlrev_b32_e32 v34, 1, v49
	s_nop 0
	v_addc_co_u32_e32 v33, vcc, 0, v33, vcc
	v_lshl_or_b32 v45, v45, 12, v34
	s_waitcnt vmcnt(0)
; __device__ __forceinline__ unsigned cvtpk(float lo, float hi) { f32x2_t v = {lo, hi}; bf16x2_t b = __builtin_convertvector(v, bf16x2_t); return __builtin_bit_cast(unsigned, b); }
; __device__ __forceinline__ float bf2f(unsigned short h) { return __uint_as_float(((unsigned)h) << 16); }
; __device__ __forceinline__ float silu(float x) { return x / (1.0f + __expf(-x)); }
; __device__ __forceinline__ void diff_unit(const DiffArgs& A, int b, int h, int qb, char* lds, int wv) {
;     ...
;       const bf16* gp = (const bf16*)(Pb + (size_t)(qb * 128) * (INC * 2) + C_DG * 2 + (unsigned)((row * INC + cq * 32) * 2));
;       bf16* yp = (bf16*)((char*)A.y + ((size_t)(b * SEQ + qb * 128) * DM + Y_D + h * 128) * 2 + (unsigned)((row * DM + cq * 32) * 2)); const float* gh = A.ghead + cq * 32;
; #pragma unroll
;       for (int i = 0; i < 4; ++i) { const bf16x8 g8 = *reinterpret_cast<const bf16x8*>(gp + 8 * i); const f32x4 h0 = *(const f32x4*)(gh + 8 * i), h1 = *(const f32x4*)(gh + 8 * i + 4);
;           const f32x4 a = v[2 * i] * h0 * rn, bq = v[2 * i + 1] * h1 * rn;
;           u32x4 w; w.x = cvtpk(a.x * silu(bf2f(g8[0])), a.y * silu(bf2f(g8[1]))); w.y = cvtpk(a.z * silu(bf2f(g8[2])), a.w * silu(bf2f(g8[3])));
;           w.z = cvtpk(bq.x * silu(bf2f(g8[4])), bq.y * silu(bf2f(g8[5]))); w.w = cvtpk(bq.z * silu(bf2f(g8[6])), bq.w * silu(bf2f(g8[7])));
;           *(u32x4*)(yp + 8 * i) = w; } }
	v_mov_b32_e32 v32, v100
	v_mov_b32_e32 v33, v101
	v_mov_b32_e32 v34, v102
	v_mov_b32_e32 v35, v103
	s_nop 0
	v_mov_b32_e32 v36, v120
	v_mov_b32_e32 v37, v121
	v_mov_b32_e32 v38, v122
	v_mov_b32_e32 v39, v123
	v_mov_b32_e32 v40, v116
	v_mov_b32_e32 v41, v117
	v_mov_b32_e32 v42, v118
	v_mov_b32_e32 v43, v119
	s_addc_u32 s7, s83, s1
	v_readlane_b32 s79, v254, 59
	s_nop 0
	v_pk_mul_f32 v[26:27], v[26:27], v[38:39]
	s_nop 0
	v_pk_mul_f32 v[28:29], v[28:29], v[40:41]
	v_pk_mul_f32 v[24:25], v[24:25], v[36:37]
	v_and_b32_e32 v36, 0xffff0000, v32
	v_lshlrev_b32_e32 v32, 16, v32
	v_pk_mul_f32 v[40:41], v[28:29], v[44:45] op_sel_hi:[1,0]
	v_pk_mul_f32 v[28:29], v[26:27], v[44:45] op_sel_hi:[1,0]
	v_pk_mul_f32 v[26:27], v[24:25], v[44:45] op_sel_hi:[1,0]
	v_mul_f32_e32 v24, 0xbfb8aa3b, v32
	v_mul_f32_e32 v25, 0xbfb8aa3b, v36
	v_exp_f32_e32 v24, v24
	v_exp_f32_e32 v25, v25
	v_pk_mul_f32 v[30:31], v[30:31], v[42:43]
	v_pk_add_f32 v[24:25], v[24:25], 1.0 op_sel_hi:[1,0]
	s_nop 0
	v_div_scale_f32 v37, s[0:1], v25, v25, v36
	v_rcp_f32_e32 v38, v37
	v_pk_mul_f32 v[30:31], v[30:31], v[44:45] op_sel_hi:[1,0]
	v_fma_f32 v39, -v37, v38, 1.0
	v_fmac_f32_e32 v38, v39, v38
	v_div_scale_f32 v39, vcc, v36, v25, v36
	v_mul_f32_e32 v42, v39, v38
	v_fma_f32 v43, -v37, v42, v39
	v_fmac_f32_e32 v42, v43, v38
	v_fma_f32 v37, -v37, v42, v39
	v_div_fmas_f32 v37, v37, v38, v42
	v_div_fixup_f32 v25, v37, v25, v36
	v_div_scale_f32 v36, s[0:1], v24, v24, v32
	v_rcp_f32_e32 v37, v36
	s_nop 0
	v_fma_f32 v38, -v36, v37, 1.0
	v_fmac_f32_e32 v37, v38, v37
	v_div_scale_f32 v38, vcc, v32, v24, v32
	v_mul_f32_e32 v39, v38, v37
	v_fma_f32 v42, -v36, v39, v38
	v_fmac_f32_e32 v39, v42, v37
	v_fma_f32 v36, -v36, v39, v38
	v_div_fmas_f32 v36, v36, v37, v39
	v_div_fixup_f32 v24, v36, v24, v32
	v_pk_mul_f32 v[24:25], v[24:25], v[40:41]
	v_lshlrev_b32_e32 v36, 16, v33
	v_cvt_pk_bf16_f32 v24, v24, v25
	v_and_b32_e32 v25, 0xffff0000, v33
	v_mul_f32_e32 v32, 0xbfb8aa3b, v36
	v_mul_f32_e32 v33, 0xbfb8aa3b, v25
	v_exp_f32_e32 v32, v32
	v_exp_f32_e32 v33, v33
	s_nop 0
	v_pk_add_f32 v[32:33], v[32:33], 1.0 op_sel_hi:[1,0]
	s_nop 0
	v_div_scale_f32 v37, s[0:1], v33, v33, v25
	v_rcp_f32_e32 v38, v37
	s_nop 0
	v_fma_f32 v39, -v37, v38, 1.0
	v_fmac_f32_e32 v38, v39, v38
	v_div_scale_f32 v39, vcc, v25, v33, v25
	v_mul_f32_e32 v40, v39, v38
	v_fma_f32 v41, -v37, v40, v39
	v_fmac_f32_e32 v40, v41, v38
	v_fma_f32 v37, -v37, v40, v39
	v_div_fmas_f32 v37, v37, v38, v40
	v_div_fixup_f32 v33, v37, v33, v25
	v_div_scale_f32 v25, s[0:1], v32, v32, v36
	v_rcp_f32_e32 v37, v25
	s_nop 0
	v_fma_f32 v38, -v25, v37, 1.0
	v_fmac_f32_e32 v37, v38, v37
	v_div_scale_f32 v38, vcc, v36, v32, v36
	v_mul_f32_e32 v39, v38, v37
	v_fma_f32 v40, -v25, v39, v38
	v_fmac_f32_e32 v39, v40, v37
	v_fma_f32 v25, -v25, v39, v38
	v_div_fmas_f32 v25, v25, v37, v39
	v_div_fixup_f32 v32, v25, v32, v36
	v_pk_mul_f32 v[30:31], v[32:33], v[30:31]
	v_and_b32_e32 v32, 0xffff0000, v34
	v_lshlrev_b32_e32 v33, 16, v34
	v_cvt_pk_bf16_f32 v25, v30, v31
	v_mul_f32_e32 v30, 0xbfb8aa3b, v33
	v_mul_f32_e32 v31, 0xbfb8aa3b, v32
	v_exp_f32_e32 v30, v30
	v_exp_f32_e32 v31, v31
	s_nop 0
	v_pk_add_f32 v[30:31], v[30:31], 1.0 op_sel_hi:[1,0]
	s_nop 0
	v_div_scale_f32 v34, s[0:1], v31, v31, v32
	v_rcp_f32_e32 v36, v34
	s_nop 0
	v_fma_f32 v37, -v34, v36, 1.0
	v_fmac_f32_e32 v36, v37, v36
	v_div_scale_f32 v37, vcc, v32, v31, v32
	v_mul_f32_e32 v38, v37, v36
	v_fma_f32 v39, -v34, v38, v37
	v_fmac_f32_e32 v38, v39, v36
	v_fma_f32 v34, -v34, v38, v37
	v_div_fmas_f32 v34, v34, v36, v38
	v_div_fixup_f32 v31, v34, v31, v32
	v_div_scale_f32 v32, s[0:1], v30, v30, v33
	v_rcp_f32_e32 v34, v32
	s_nop 0
	v_fma_f32 v36, -v32, v34, 1.0
	v_fmac_f32_e32 v34, v36, v34
	v_div_scale_f32 v36, vcc, v33, v30, v33
	v_mul_f32_e32 v37, v36, v34
	v_fma_f32 v38, -v32, v37, v36
	v_fmac_f32_e32 v37, v38, v34
	v_fma_f32 v32, -v32, v37, v36
	v_div_fmas_f32 v32, v32, v34, v37
	v_div_fixup_f32 v30, v32, v30, v33
	v_pk_mul_f32 v[26:27], v[30:31], v[26:27]
	v_lshlrev_b32_e32 v32, 16, v35
	v_cvt_pk_bf16_f32 v26, v26, v27
	v_and_b32_e32 v27, 0xffff0000, v35
	v_mul_f32_e32 v30, 0xbfb8aa3b, v32
	v_mul_f32_e32 v31, 0xbfb8aa3b, v27
	v_exp_f32_e32 v30, v30
	v_exp_f32_e32 v31, v31
	s_nop 0
	v_pk_add_f32 v[30:31], v[30:31], 1.0 op_sel_hi:[1,0]
	s_nop 0
	v_div_scale_f32 v33, s[0:1], v31, v31, v27
	v_rcp_f32_e32 v34, v33
	s_nop 0
	v_fma_f32 v35, -v33, v34, 1.0
	v_fmac_f32_e32 v34, v35, v34
	v_div_scale_f32 v35, vcc, v27, v31, v27
	v_mul_f32_e32 v36, v35, v34
	v_fma_f32 v37, -v33, v36, v35
	v_fmac_f32_e32 v36, v37, v34
	v_fma_f32 v33, -v33, v36, v35
	v_div_fmas_f32 v33, v33, v34, v36
	v_div_fixup_f32 v31, v33, v31, v27
	v_div_scale_f32 v27, s[0:1], v30, v30, v32
	v_rcp_f32_e32 v33, v27
	s_nop 0
	v_fma_f32 v34, -v27, v33, 1.0
	v_fmac_f32_e32 v33, v34, v33
	v_div_scale_f32 v34, vcc, v32, v30, v32
	v_mul_f32_e32 v35, v34, v33
	v_fma_f32 v36, -v27, v35, v34
	v_fmac_f32_e32 v35, v36, v33
	v_fma_f32 v27, -v27, v35, v34
	v_div_fmas_f32 v27, v27, v33, v35
	v_div_fixup_f32 v30, v27, v30, v32
	v_pk_mul_f32 v[28:29], v[30:31], v[28:29]
	s_nop 0
	v_cvt_pk_bf16_f32 v27, v28, v29
	global_store_dwordx4 v45, v[24:27], s[6:7]
	s_nop 1
	v_mov_b32_e32 v24, v104
	v_mov_b32_e32 v25, v105
	v_mov_b32_e32 v26, v106
	v_mov_b32_e32 v27, v107
	s_nop 0
	v_mov_b32_e32 v28, v128
	v_mov_b32_e32 v29, v129
	v_mov_b32_e32 v30, v130
	v_mov_b32_e32 v31, v131
	v_mov_b32_e32 v32, v124
	v_mov_b32_e32 v33, v125
	v_mov_b32_e32 v34, v126
	v_mov_b32_e32 v35, v127
	s_nop 0
	v_pk_mul_f32 v[18:19], v[18:19], v[30:31]
	s_nop 0
	v_pk_mul_f32 v[20:21], v[20:21], v[32:33]
	v_pk_mul_f32 v[16:17], v[16:17], v[28:29]
	v_and_b32_e32 v28, 0xffff0000, v24
; __device__ __forceinline__ unsigned cvtpk(float lo, float hi) { f32x2_t v = {lo, hi}; bf16x2_t b = __builtin_convertvector(v, bf16x2_t); return __builtin_bit_cast(unsigned, b); }
; __device__ __forceinline__ float bf2f(unsigned short h) { return __uint_as_float(((unsigned)h) << 16); }
; __device__ __forceinline__ float silu(float x) { return x / (1.0f + __expf(-x)); }
; __device__ __forceinline__ void diff_unit(const DiffArgs& A, int b, int h, int qb, char* lds, int wv) {
;     ...
;       const bf16* gp = (const bf16*)(Pb + (size_t)(qb * 128) * (INC * 2) + C_DG * 2 + (unsigned)((row * INC + cq * 32) * 2));
;       bf16* yp = (bf16*)((char*)A.y + ((size_t)(b * SEQ + qb * 128) * DM + Y_D + h * 128) * 2 + (unsigned)((row * DM + cq * 32) * 2)); const float* gh = A.ghead + cq * 32;
; #pragma unroll
;       for (int i = 0; i < 4; ++i) { const bf16x8 g8 = *reinterpret_cast<const bf16x8*>(gp + 8 * i); const f32x4 h0 = *(const f32x4*)(gh + 8 * i), h1 = *(const f32x4*)(gh + 8 * i + 4);
;           const f32x4 a = v[2 * i] * h0 * rn, bq = v[2 * i + 1] * h1 * rn;
;           u32x4 w; w.x = cvtpk(a.x * silu(bf2f(g8[0])), a.y * silu(bf2f(g8[1]))); w.y = cvtpk(a.z * silu(bf2f(g8[2])), a.w * silu(bf2f(g8[3])));
;           w.z = cvtpk(bq.x * silu(bf2f(g8[4])), bq.y * silu(bf2f(g8[5]))); w.w = cvtpk(bq.z * silu(bf2f(g8[6])), bq.w * silu(bf2f(g8[7])));
;           *(u32x4*)(yp + 8 * i) = w; } }
	v_lshlrev_b32_e32 v24, 16, v24
	v_pk_mul_f32 v[32:33], v[20:21], v[44:45] op_sel_hi:[1,0]
	v_pk_mul_f32 v[20:21], v[18:19], v[44:45] op_sel_hi:[1,0]
	v_pk_mul_f32 v[18:19], v[16:17], v[44:45] op_sel_hi:[1,0]
	v_mul_f32_e32 v16, 0xbfb8aa3b, v24
	v_mul_f32_e32 v17, 0xbfb8aa3b, v28
	v_exp_f32_e32 v16, v16
	v_exp_f32_e32 v17, v17
	v_pk_mul_f32 v[22:23], v[22:23], v[34:35]
	v_pk_add_f32 v[16:17], v[16:17], 1.0 op_sel_hi:[1,0]
	s_nop 0
	v_div_scale_f32 v29, s[0:1], v17, v17, v28
	v_rcp_f32_e32 v30, v29
	v_pk_mul_f32 v[22:23], v[22:23], v[44:45] op_sel_hi:[1,0]
	v_fma_f32 v31, -v29, v30, 1.0
	v_fmac_f32_e32 v30, v31, v30
	v_div_scale_f32 v31, vcc, v28, v17, v28
	v_mul_f32_e32 v34, v31, v30
	v_fma_f32 v35, -v29, v34, v31
	v_fmac_f32_e32 v34, v35, v30
	v_fma_f32 v29, -v29, v34, v31
	v_div_fmas_f32 v29, v29, v30, v34
	v_div_fixup_f32 v17, v29, v17, v28
	v_div_scale_f32 v28, s[0:1], v16, v16, v24
	v_rcp_f32_e32 v29, v28
	s_nop 0
	v_fma_f32 v30, -v28, v29, 1.0
	v_fmac_f32_e32 v29, v30, v29
	v_div_scale_f32 v30, vcc, v24, v16, v24
	v_mul_f32_e32 v31, v30, v29
	v_fma_f32 v34, -v28, v31, v30
	v_fmac_f32_e32 v31, v34, v29
	v_fma_f32 v28, -v28, v31, v30
	v_div_fmas_f32 v28, v28, v29, v31
	v_div_fixup_f32 v16, v28, v16, v24
	v_pk_mul_f32 v[16:17], v[32:33], v[16:17]
	v_lshlrev_b32_e32 v28, 16, v25
	v_cvt_pk_bf16_f32 v16, v16, v17
	v_and_b32_e32 v17, 0xffff0000, v25
	v_mul_f32_e32 v24, 0xbfb8aa3b, v28
	v_mul_f32_e32 v25, 0xbfb8aa3b, v17
	v_exp_f32_e32 v24, v24
	v_exp_f32_e32 v25, v25
	s_nop 0
	v_pk_add_f32 v[24:25], v[24:25], 1.0 op_sel_hi:[1,0]
	s_nop 0
	v_div_scale_f32 v29, s[0:1], v25, v25, v17
	v_rcp_f32_e32 v30, v29
	s_nop 0
	v_fma_f32 v31, -v29, v30, 1.0
	v_fmac_f32_e32 v30, v31, v30
	v_div_scale_f32 v31, vcc, v17, v25, v17
	v_mul_f32_e32 v32, v31, v30
	v_fma_f32 v33, -v29, v32, v31
	v_fmac_f32_e32 v32, v33, v30
	v_fma_f32 v29, -v29, v32, v31
	v_div_fmas_f32 v29, v29, v30, v32
	v_div_fixup_f32 v25, v29, v25, v17
	v_div_scale_f32 v17, s[0:1], v24, v24, v28
	v_rcp_f32_e32 v29, v17
	s_nop 0
	v_fma_f32 v30, -v17, v29, 1.0
	v_fmac_f32_e32 v29, v30, v29
	v_div_scale_f32 v30, vcc, v28, v24, v28
	v_mul_f32_e32 v31, v30, v29
	v_fma_f32 v32, -v17, v31, v30
	v_fmac_f32_e32 v31, v32, v29
	v_fma_f32 v17, -v17, v31, v30
	v_div_fmas_f32 v17, v17, v29, v31
	v_div_fixup_f32 v24, v17, v24, v28
	v_pk_mul_f32 v[22:23], v[22:23], v[24:25]
	v_and_b32_e32 v24, 0xffff0000, v26
	v_lshlrev_b32_e32 v25, 16, v26
	v_cvt_pk_bf16_f32 v17, v22, v23
	v_mul_f32_e32 v22, 0xbfb8aa3b, v25
	v_mul_f32_e32 v23, 0xbfb8aa3b, v24
	v_exp_f32_e32 v22, v22
	v_exp_f32_e32 v23, v23
	s_nop 0
	v_pk_add_f32 v[22:23], v[22:23], 1.0 op_sel_hi:[1,0]
	s_nop 0
	v_div_scale_f32 v26, s[0:1], v23, v23, v24
	v_rcp_f32_e32 v28, v26
	s_nop 0
	v_fma_f32 v29, -v26, v28, 1.0
	v_fmac_f32_e32 v28, v29, v28
	v_div_scale_f32 v29, vcc, v24, v23, v24
	v_mul_f32_e32 v30, v29, v28
	v_fma_f32 v31, -v26, v30, v29
	v_fmac_f32_e32 v30, v31, v28
	v_fma_f32 v26, -v26, v30, v29
	v_div_fmas_f32 v26, v26, v28, v30
	v_div_fixup_f32 v23, v26, v23, v24
	v_div_scale_f32 v24, s[0:1], v22, v22, v25
	v_rcp_f32_e32 v26, v24
	s_nop 0
	v_fma_f32 v28, -v24, v26, 1.0
	v_fmac_f32_e32 v26, v28, v26
	v_div_scale_f32 v28, vcc, v25, v22, v25
	v_mul_f32_e32 v29, v28, v26
	v_fma_f32 v30, -v24, v29, v28
	v_fmac_f32_e32 v29, v30, v26
	v_fma_f32 v24, -v24, v29, v28
	v_div_fmas_f32 v24, v24, v26, v29
	v_div_fixup_f32 v22, v24, v22, v25
	v_pk_mul_f32 v[18:19], v[18:19], v[22:23]
	v_lshlrev_b32_e32 v24, 16, v27
	v_cvt_pk_bf16_f32 v18, v18, v19
	v_and_b32_e32 v19, 0xffff0000, v27
	v_mul_f32_e32 v22, 0xbfb8aa3b, v24
	v_mul_f32_e32 v23, 0xbfb8aa3b, v19
	v_exp_f32_e32 v22, v22
	v_exp_f32_e32 v23, v23
	s_nop 0
	v_pk_add_f32 v[22:23], v[22:23], 1.0 op_sel_hi:[1,0]
	s_nop 0
	v_div_scale_f32 v25, s[0:1], v23, v23, v19
	v_rcp_f32_e32 v26, v25
	s_nop 0
	v_fma_f32 v27, -v25, v26, 1.0
	v_fmac_f32_e32 v26, v27, v26
	v_div_scale_f32 v27, vcc, v19, v23, v19
	v_mul_f32_e32 v28, v27, v26
	v_fma_f32 v29, -v25, v28, v27
	v_fmac_f32_e32 v28, v29, v26
	v_fma_f32 v25, -v25, v28, v27
	v_div_fmas_f32 v25, v25, v26, v28
	v_div_fixup_f32 v23, v25, v23, v19
	v_div_scale_f32 v19, s[0:1], v22, v22, v24
	v_rcp_f32_e32 v25, v19
	s_nop 0
	v_fma_f32 v26, -v19, v25, 1.0
	v_fmac_f32_e32 v25, v26, v25
	v_div_scale_f32 v26, vcc, v24, v22, v24
	v_mul_f32_e32 v27, v26, v25
	v_fma_f32 v28, -v19, v27, v26
	v_fmac_f32_e32 v27, v28, v25
	v_fma_f32 v19, -v19, v27, v26
	v_div_fmas_f32 v19, v19, v25, v27
	v_div_fixup_f32 v22, v19, v22, v24
	v_pk_mul_f32 v[20:21], v[20:21], v[22:23]
	s_nop 0
	v_cvt_pk_bf16_f32 v19, v20, v21
	global_store_dwordx4 v45, v[16:19], s[6:7] offset:16
	s_nop 1
	v_mov_b32_e32 v16, v108
	v_mov_b32_e32 v17, v109
	v_mov_b32_e32 v18, v110
	v_mov_b32_e32 v19, v111
	s_nop 0
	v_mov_b32_e32 v20, v136
	v_mov_b32_e32 v21, v137
	v_mov_b32_e32 v22, v138
	v_mov_b32_e32 v23, v139
	v_mov_b32_e32 v24, v132
	v_mov_b32_e32 v25, v133
	v_mov_b32_e32 v26, v134
	v_mov_b32_e32 v27, v135
	s_nop 0
	v_pk_mul_f32 v[10:11], v[10:11], v[26:27]
	v_pk_mul_f32 v[8:9], v[8:9], v[24:25]
	v_pk_mul_f32 v[24:25], v[44:45], v[10:11] op_sel_hi:[0,1]
	v_pk_mul_f32 v[10:11], v[14:15], v[22:23]
	v_pk_mul_f32 v[14:15], v[12:13], v[20:21]
	v_and_b32_e32 v20, 0xffff0000, v16
	v_lshlrev_b32_e32 v16, 16, v16
	v_pk_mul_f32 v[12:13], v[44:45], v[10:11] op_sel_hi:[0,1]
	v_pk_mul_f32 v[10:11], v[44:45], v[14:15] op_sel_hi:[0,1]
	v_mul_f32_e32 v14, 0xbfb8aa3b, v16
	v_mul_f32_e32 v15, 0xbfb8aa3b, v20
	v_exp_f32_e32 v14, v14
	v_exp_f32_e32 v15, v15
	v_pk_mul_f32 v[8:9], v[44:45], v[8:9] op_sel_hi:[0,1]
	v_pk_add_f32 v[14:15], v[14:15], 1.0 op_sel_hi:[1,0]
	s_nop 0
	v_div_scale_f32 v21, s[0:1], v15, v15, v20
	v_rcp_f32_e32 v22, v21
; __device__ __forceinline__ unsigned cvtpk(float lo, float hi) { f32x2_t v = {lo, hi}; bf16x2_t b = __builtin_convertvector(v, bf16x2_t); return __builtin_bit_cast(unsigned, b); }
; __device__ __forceinline__ float bf2f(unsigned short h) { return __uint_as_float(((unsigned)h) << 16); }
; __device__ __forceinline__ float silu(float x) { return x / (1.0f + __expf(-x)); }
; __device__ __forceinline__ void diff_unit(const DiffArgs& A, int b, int h, int qb, char* lds, int wv) {
;     ...
;       const bf16* gp = (const bf16*)(Pb + (size_t)(qb * 128) * (INC * 2) + C_DG * 2 + (unsigned)((row * INC + cq * 32) * 2));
;       bf16* yp = (bf16*)((char*)A.y + ((size_t)(b * SEQ + qb * 128) * DM + Y_D + h * 128) * 2 + (unsigned)((row * DM + cq * 32) * 2)); const float* gh = A.ghead + cq * 32;
; #pragma unroll
;       for (int i = 0; i < 4; ++i) { const bf16x8 g8 = *reinterpret_cast<const bf16x8*>(gp + 8 * i); const f32x4 h0 = *(const f32x4*)(gh + 8 * i), h1 = *(const f32x4*)(gh + 8 * i + 4);
;           const f32x4 a = v[2 * i] * h0 * rn, bq = v[2 * i + 1] * h1 * rn;
;           u32x4 w; w.x = cvtpk(a.x * silu(bf2f(g8[0])), a.y * silu(bf2f(g8[1]))); w.y = cvtpk(a.z * silu(bf2f(g8[2])), a.w * silu(bf2f(g8[3])));
;           w.z = cvtpk(bq.x * silu(bf2f(g8[4])), bq.y * silu(bf2f(g8[5]))); w.w = cvtpk(bq.z * silu(bf2f(g8[6])), bq.w * silu(bf2f(g8[7])));
;           *(u32x4*)(yp + 8 * i) = w; } }
	s_nop 0
	v_fma_f32 v23, -v21, v22, 1.0
	v_fmac_f32_e32 v22, v23, v22
	v_div_scale_f32 v23, vcc, v20, v15, v20
	v_mul_f32_e32 v26, v23, v22
	v_fma_f32 v27, -v21, v26, v23
	v_fmac_f32_e32 v26, v27, v22
	v_fma_f32 v21, -v21, v26, v23
	v_div_fmas_f32 v21, v21, v22, v26
	v_div_fixup_f32 v15, v21, v15, v20
	v_div_scale_f32 v20, s[0:1], v14, v14, v16
	v_rcp_f32_e32 v21, v20
	s_nop 0
	v_fma_f32 v22, -v20, v21, 1.0
	v_fmac_f32_e32 v21, v22, v21
	v_div_scale_f32 v22, vcc, v16, v14, v16
	v_mul_f32_e32 v23, v22, v21
	v_fma_f32 v26, -v20, v23, v22
	v_fmac_f32_e32 v23, v26, v21
	v_fma_f32 v20, -v20, v23, v22
	v_div_fmas_f32 v20, v20, v21, v23
	v_div_fixup_f32 v14, v20, v14, v16
	v_pk_mul_f32 v[8:9], v[8:9], v[14:15]
	v_lshlrev_b32_e32 v16, 16, v17
	v_cvt_pk_bf16_f32 v8, v8, v9
	v_and_b32_e32 v9, 0xffff0000, v17
	v_mul_f32_e32 v14, 0xbfb8aa3b, v16
	v_mul_f32_e32 v15, 0xbfb8aa3b, v9
	v_exp_f32_e32 v14, v14
	v_exp_f32_e32 v15, v15
	s_nop 0
	v_pk_add_f32 v[14:15], v[14:15], 1.0 op_sel_hi:[1,0]
	s_nop 0
	v_div_scale_f32 v17, s[0:1], v15, v15, v9
	v_rcp_f32_e32 v20, v17
	s_nop 0
	v_fma_f32 v21, -v17, v20, 1.0
	v_fmac_f32_e32 v20, v21, v20
	v_div_scale_f32 v21, vcc, v9, v15, v9
	v_mul_f32_e32 v22, v21, v20
	v_fma_f32 v23, -v17, v22, v21
	v_fmac_f32_e32 v22, v23, v20
	v_fma_f32 v17, -v17, v22, v21
	v_div_fmas_f32 v17, v17, v20, v22
	v_div_fixup_f32 v15, v17, v15, v9
	v_div_scale_f32 v9, s[0:1], v14, v14, v16
	v_rcp_f32_e32 v17, v9
	s_nop 0
	v_fma_f32 v20, -v9, v17, 1.0
	v_fmac_f32_e32 v17, v20, v17
	v_div_scale_f32 v20, vcc, v16, v14, v16
	v_mul_f32_e32 v21, v20, v17
	v_fma_f32 v22, -v9, v21, v20
	v_fmac_f32_e32 v21, v22, v17
	v_fma_f32 v9, -v9, v21, v20
	v_div_fmas_f32 v9, v9, v17, v21
	v_div_fixup_f32 v14, v9, v14, v16
	v_pk_mul_f32 v[14:15], v[24:25], v[14:15]
	v_and_b32_e32 v16, 0xffff0000, v18
	v_lshlrev_b32_e32 v17, 16, v18
	v_cvt_pk_bf16_f32 v9, v14, v15
	v_mul_f32_e32 v14, 0xbfb8aa3b, v17
	v_mul_f32_e32 v15, 0xbfb8aa3b, v16
	v_exp_f32_e32 v14, v14
	v_exp_f32_e32 v15, v15
	s_nop 0
	v_pk_add_f32 v[14:15], v[14:15], 1.0 op_sel_hi:[1,0]
	s_nop 0
	v_div_scale_f32 v18, s[0:1], v15, v15, v16
	v_rcp_f32_e32 v20, v18
	s_nop 0
	v_fma_f32 v21, -v18, v20, 1.0
	v_fmac_f32_e32 v20, v21, v20
	v_div_scale_f32 v21, vcc, v16, v15, v16
	v_mul_f32_e32 v22, v21, v20
	v_fma_f32 v23, -v18, v22, v21
	v_fmac_f32_e32 v22, v23, v20
	v_fma_f32 v18, -v18, v22, v21
	v_div_fmas_f32 v18, v18, v20, v22
	v_div_fixup_f32 v15, v18, v15, v16
	v_div_scale_f32 v16, s[0:1], v14, v14, v17
	v_rcp_f32_e32 v18, v16
	s_nop 0
	v_fma_f32 v20, -v16, v18, 1.0
	v_fmac_f32_e32 v18, v20, v18
	v_div_scale_f32 v20, vcc, v17, v14, v17
	v_mul_f32_e32 v21, v20, v18
	v_fma_f32 v22, -v16, v21, v20
	v_fmac_f32_e32 v21, v22, v18
	v_fma_f32 v16, -v16, v21, v20
	v_div_fmas_f32 v16, v16, v18, v21
	v_div_fixup_f32 v14, v16, v14, v17
	v_pk_mul_f32 v[10:11], v[10:11], v[14:15]
	v_lshlrev_b32_e32 v16, 16, v19
	v_cvt_pk_bf16_f32 v10, v10, v11
	v_and_b32_e32 v11, 0xffff0000, v19
	v_mul_f32_e32 v14, 0xbfb8aa3b, v16
	v_mul_f32_e32 v15, 0xbfb8aa3b, v11
	v_exp_f32_e32 v14, v14
	v_exp_f32_e32 v15, v15
	s_nop 0
	v_pk_add_f32 v[14:15], v[14:15], 1.0 op_sel_hi:[1,0]
	s_nop 0
	v_div_scale_f32 v17, s[0:1], v15, v15, v11
	v_rcp_f32_e32 v18, v17
	s_nop 0
	v_fma_f32 v19, -v17, v18, 1.0
	v_fmac_f32_e32 v18, v19, v18
	v_div_scale_f32 v19, vcc, v11, v15, v11
	v_mul_f32_e32 v20, v19, v18
	v_fma_f32 v21, -v17, v20, v19
	v_fmac_f32_e32 v20, v21, v18
	v_fma_f32 v17, -v17, v20, v19
	v_div_fmas_f32 v17, v17, v18, v20
	v_div_fixup_f32 v15, v17, v15, v11
	v_div_scale_f32 v11, s[0:1], v14, v14, v16
	v_rcp_f32_e32 v17, v11
	s_nop 0
	v_fma_f32 v18, -v11, v17, 1.0
	v_fmac_f32_e32 v17, v18, v17
	v_div_scale_f32 v18, vcc, v16, v14, v16
	v_mul_f32_e32 v19, v18, v17
	v_fma_f32 v20, -v11, v19, v18
	v_fmac_f32_e32 v19, v20, v17
	v_fma_f32 v11, -v11, v19, v18
	v_div_fmas_f32 v11, v11, v17, v19
	v_div_fixup_f32 v14, v11, v14, v16
	v_pk_mul_f32 v[12:13], v[12:13], v[14:15]
	s_nop 0
	v_cvt_pk_bf16_f32 v11, v12, v13
	global_store_dwordx4 v45, v[8:11], s[6:7] offset:32
	s_nop 1
	v_mov_b32_e32 v8, v112
	v_mov_b32_e32 v9, v113
	v_mov_b32_e32 v10, v114
	v_mov_b32_e32 v11, v115
	s_nop 0
	v_mov_b32_e32 v12, v144
	v_mov_b32_e32 v13, v145
	v_mov_b32_e32 v14, v146
	v_mov_b32_e32 v15, v147
	v_mov_b32_e32 v16, v140
	v_mov_b32_e32 v17, v141
	v_mov_b32_e32 v18, v142
	v_mov_b32_e32 v19, v143
	s_nop 0
	v_pk_mul_f32 v[2:3], v[2:3], v[18:19]
	v_pk_mul_f32 v[0:1], v[0:1], v[16:17]
; __device__ __forceinline__ unsigned cvtpk(float lo, float hi) { f32x2_t v = {lo, hi}; bf16x2_t b = __builtin_convertvector(v, bf16x2_t); return __builtin_bit_cast(unsigned, b); }
; __device__ __forceinline__ float bf2f(unsigned short h) { return __uint_as_float(((unsigned)h) << 16); }
; __device__ __forceinline__ float silu(float x) { return x / (1.0f + __expf(-x)); }
; __device__ __forceinline__ void diff_unit(const DiffArgs& A, int b, int h, int qb, char* lds, int wv) {
;     ...
;       for (int i = 0; i < 4; ++i) { const bf16x8 g8 = *reinterpret_cast<const bf16x8*>(gp + 8 * i); const f32x4 h0 = *(const f32x4*)(gh + 8 * i), h1 = *(const f32x4*)(gh + 8 * i + 4);
;           const f32x4 a = v[2 * i] * h0 * rn, bq = v[2 * i + 1] * h1 * rn;
;           u32x4 w; w.x = cvtpk(a.x * silu(bf2f(g8[0])), a.y * silu(bf2f(g8[1]))); w.y = cvtpk(a.z * silu(bf2f(g8[2])), a.w * silu(bf2f(g8[3])));
;           w.z = cvtpk(bq.x * silu(bf2f(g8[4])), bq.y * silu(bf2f(g8[5]))); w.w = cvtpk(bq.z * silu(bf2f(g8[6])), bq.w * silu(bf2f(g8[7])));
;           *(u32x4*)(yp + 8 * i) = w; } }
;     __syncthreads();
	v_pk_mul_f32 v[16:17], v[44:45], v[2:3] op_sel_hi:[0,1]
	v_pk_mul_f32 v[2:3], v[6:7], v[14:15]
	v_pk_mul_f32 v[6:7], v[4:5], v[12:13]
	v_and_b32_e32 v12, 0xffff0000, v8
	v_lshlrev_b32_e32 v8, 16, v8
	v_pk_mul_f32 v[4:5], v[44:45], v[2:3] op_sel_hi:[0,1]
	v_pk_mul_f32 v[2:3], v[44:45], v[6:7] op_sel_hi:[0,1]
	v_mul_f32_e32 v6, 0xbfb8aa3b, v8
	v_mul_f32_e32 v7, 0xbfb8aa3b, v12
	v_exp_f32_e32 v6, v6
	v_exp_f32_e32 v7, v7
	v_pk_mul_f32 v[0:1], v[44:45], v[0:1] op_sel_hi:[0,1]
	v_pk_add_f32 v[6:7], v[6:7], 1.0 op_sel_hi:[1,0]
	s_nop 0
	v_div_scale_f32 v13, s[0:1], v7, v7, v12
	v_rcp_f32_e32 v14, v13
	s_nop 0
	v_fma_f32 v15, -v13, v14, 1.0
	v_fmac_f32_e32 v14, v15, v14
	v_div_scale_f32 v15, vcc, v12, v7, v12
	v_mul_f32_e32 v18, v15, v14
	v_fma_f32 v19, -v13, v18, v15
	v_fmac_f32_e32 v18, v19, v14
	v_fma_f32 v13, -v13, v18, v15
	v_div_fmas_f32 v13, v13, v14, v18
	v_div_fixup_f32 v7, v13, v7, v12
	v_div_scale_f32 v12, s[0:1], v6, v6, v8
	v_rcp_f32_e32 v13, v12
	s_nop 0
	v_fma_f32 v14, -v12, v13, 1.0
	v_fmac_f32_e32 v13, v14, v13
	v_div_scale_f32 v14, vcc, v8, v6, v8
	v_mul_f32_e32 v15, v14, v13
	v_fma_f32 v18, -v12, v15, v14
	v_fmac_f32_e32 v15, v18, v13
	v_fma_f32 v12, -v12, v15, v14
	v_div_fmas_f32 v12, v12, v13, v15
	v_div_fixup_f32 v6, v12, v6, v8
	v_pk_mul_f32 v[0:1], v[0:1], v[6:7]
	v_lshlrev_b32_e32 v8, 16, v9
	v_cvt_pk_bf16_f32 v0, v0, v1
	v_and_b32_e32 v1, 0xffff0000, v9
	v_mul_f32_e32 v6, 0xbfb8aa3b, v8
	v_mul_f32_e32 v7, 0xbfb8aa3b, v1
	v_exp_f32_e32 v6, v6
	v_exp_f32_e32 v7, v7
	s_nop 0
	v_pk_add_f32 v[6:7], v[6:7], 1.0 op_sel_hi:[1,0]
	s_nop 0
	v_div_scale_f32 v9, s[0:1], v7, v7, v1
	v_rcp_f32_e32 v12, v9
	s_nop 0
	v_fma_f32 v13, -v9, v12, 1.0
	v_fmac_f32_e32 v12, v13, v12
	v_div_scale_f32 v13, vcc, v1, v7, v1
	v_mul_f32_e32 v14, v13, v12
	v_fma_f32 v15, -v9, v14, v13
	v_fmac_f32_e32 v14, v15, v12
	v_fma_f32 v9, -v9, v14, v13
	v_div_fmas_f32 v9, v9, v12, v14
	v_div_fixup_f32 v7, v9, v7, v1
	v_div_scale_f32 v1, s[0:1], v6, v6, v8
	v_rcp_f32_e32 v9, v1
	s_nop 0
	v_fma_f32 v12, -v1, v9, 1.0
	v_fmac_f32_e32 v9, v12, v9
	v_div_scale_f32 v12, vcc, v8, v6, v8
	v_mul_f32_e32 v13, v12, v9
	v_fma_f32 v14, -v1, v13, v12
	v_fmac_f32_e32 v13, v14, v9
	v_fma_f32 v1, -v1, v13, v12
	v_div_fmas_f32 v1, v1, v9, v13
	v_div_fixup_f32 v6, v1, v6, v8
	v_pk_mul_f32 v[6:7], v[16:17], v[6:7]
	v_and_b32_e32 v8, 0xffff0000, v10
	v_lshlrev_b32_e32 v9, 16, v10
	v_cvt_pk_bf16_f32 v1, v6, v7
	v_mul_f32_e32 v6, 0xbfb8aa3b, v9
	v_mul_f32_e32 v7, 0xbfb8aa3b, v8
	v_exp_f32_e32 v6, v6
	v_exp_f32_e32 v7, v7
	s_nop 0
	v_pk_add_f32 v[6:7], v[6:7], 1.0 op_sel_hi:[1,0]
	s_nop 0
	v_div_scale_f32 v10, s[0:1], v7, v7, v8
	v_rcp_f32_e32 v12, v10
	s_nop 0
	v_fma_f32 v13, -v10, v12, 1.0
	v_fmac_f32_e32 v12, v13, v12
	v_div_scale_f32 v13, vcc, v8, v7, v8
	v_mul_f32_e32 v14, v13, v12
	v_fma_f32 v15, -v10, v14, v13
	v_fmac_f32_e32 v14, v15, v12
	v_fma_f32 v10, -v10, v14, v13
	v_div_fmas_f32 v10, v10, v12, v14
	v_div_fixup_f32 v7, v10, v7, v8
	v_div_scale_f32 v8, s[0:1], v6, v6, v9
	v_rcp_f32_e32 v10, v8
	s_nop 0
	v_fma_f32 v12, -v8, v10, 1.0
	v_fmac_f32_e32 v10, v12, v10
	v_div_scale_f32 v12, vcc, v9, v6, v9
	v_mul_f32_e32 v13, v12, v10
	v_fma_f32 v14, -v8, v13, v12
	v_fmac_f32_e32 v13, v14, v10
	v_fma_f32 v8, -v8, v13, v12
	v_div_fmas_f32 v8, v8, v10, v13
	v_div_fixup_f32 v6, v8, v6, v9
	v_pk_mul_f32 v[2:3], v[2:3], v[6:7]
	v_lshlrev_b32_e32 v8, 16, v11
	v_cvt_pk_bf16_f32 v2, v2, v3
	v_and_b32_e32 v3, 0xffff0000, v11
	v_mul_f32_e32 v6, 0xbfb8aa3b, v8
	v_mul_f32_e32 v7, 0xbfb8aa3b, v3
	v_exp_f32_e32 v6, v6
	v_exp_f32_e32 v7, v7
	s_nop 0
	v_pk_add_f32 v[6:7], v[6:7], 1.0 op_sel_hi:[1,0]
	s_nop 0
	v_div_scale_f32 v9, s[0:1], v7, v7, v3
	v_rcp_f32_e32 v10, v9
	s_nop 0
	v_fma_f32 v11, -v9, v10, 1.0
	v_fmac_f32_e32 v10, v11, v10
	v_div_scale_f32 v11, vcc, v3, v7, v3
	v_mul_f32_e32 v12, v11, v10
	v_fma_f32 v13, -v9, v12, v11
	v_fmac_f32_e32 v12, v13, v10
	v_fma_f32 v9, -v9, v12, v11
	v_div_fmas_f32 v9, v9, v10, v12
	v_div_fixup_f32 v7, v9, v7, v3
	v_div_scale_f32 v3, s[0:1], v6, v6, v8
	v_rcp_f32_e32 v9, v3
	s_nop 0
	v_fma_f32 v10, -v3, v9, 1.0
	v_fmac_f32_e32 v9, v10, v9
	v_div_scale_f32 v10, vcc, v8, v6, v8
	v_mul_f32_e32 v11, v10, v9
	v_fma_f32 v12, -v3, v11, v10
	v_fmac_f32_e32 v11, v12, v9
	v_fma_f32 v3, -v3, v11, v10
	v_div_fmas_f32 v3, v3, v9, v11
	v_div_fixup_f32 v6, v3, v6, v8
	v_pk_mul_f32 v[4:5], v[4:5], v[6:7]
	s_nop 0
	v_cvt_pk_bf16_f32 v3, v4, v5
	global_store_dwordx4 v45, v[0:3], s[6:7] offset:48
	s_barrier

; __global__ void __launch_bounds__(512) fwd_megakernel(Args args) {
;     extern __shared__ __attribute__((aligned(16))) unsigned char lds[];
	.amdhsa_kernel _Z14fwd_megakernel4Args
		.amdhsa_group_segment_fixed_size 0
		.amdhsa_private_segment_fixed_size 0
		.amdhsa_kernarg_size 424
		.amdhsa_user_sgpr_count 2
		.amdhsa_user_sgpr_dispatch_ptr 0
		.amdhsa_user_sgpr_queue_ptr 0
		.amdhsa_user_sgpr_kernarg_segment_ptr 1
		.amdhsa_user_sgpr_dispatch_id 0
		.amdhsa_user_sgpr_kernarg_preload_length 0
		.amdhsa_user_sgpr_kernarg_preload_offset 0
		.amdhsa_user_sgpr_private_segment_size 0
		.amdhsa_uses_dynamic_stack 0
		.amdhsa_enable_private_segment 0
		.amdhsa_system_sgpr_workgroup_id_x 1
		.amdhsa_system_sgpr_workgroup_id_y 0
		.amdhsa_system_sgpr_workgroup_id_z 0
		.amdhsa_system_sgpr_workgroup_info 0
		.amdhsa_system_vgpr_workitem_id 2
		.amdhsa_next_free_vgpr 256
		.amdhsa_next_free_sgpr 102
		.amdhsa_accum_offset 256
		.amdhsa_reserve_vcc 1
		.amdhsa_float_round_mode_32 0
		.amdhsa_float_round_mode_16_64 0
		.amdhsa_float_denorm_mode_32 3
		.amdhsa_float_denorm_mode_16_64 3
		.amdhsa_dx10_clamp 1
		.amdhsa_ieee_mode 1
		.amdhsa_fp16_overflow 0
		.amdhsa_tg_split 0
		.amdhsa_exception_fp_ieee_invalid_op 0
		.amdhsa_exception_fp_denorm_src 0
		.amdhsa_exception_fp_ieee_div_zero 0
		.amdhsa_exception_fp_ieee_overflow 0
		.amdhsa_exception_fp_ieee_underflow 0
		.amdhsa_exception_fp_ieee_inexact 0
		.amdhsa_exception_int_div_zero 0
	.end_amdhsa_kernel

; __global__ void __launch_bounds__(512) fwd_megakernel(Args args) {
;     extern __shared__ __attribute__((aligned(16))) unsigned char lds[];
amdhsa.kernels:
  - .agpr_count:     0
    .args:
      - .offset:         0
        .size:           168
        .value_kind:     by_value
      - .offset:         168
        .size:           4
        .value_kind:     hidden_block_count_x
      - .offset:         172
        .size:           4
        .value_kind:     hidden_block_count_y
      - .offset:         176
        .size:           4
        .value_kind:     hidden_block_count_z
      - .offset:         180
        .size:           2
        .value_kind:     hidden_group_size_x
      - .offset:         182
        .size:           2
        .value_kind:     hidden_group_size_y
      - .offset:         184
        .size:           2
        .value_kind:     hidden_group_size_z
      - .offset:         186
        .size:           2
        .value_kind:     hidden_remainder_x
      - .offset:         188
        .size:           2
        .value_kind:     hidden_remainder_y
      - .offset:         190
        .size:           2
        .value_kind:     hidden_remainder_z
      - .offset:         208
        .size:           8
        .value_kind:     hidden_global_offset_x
      - .offset:         216
        .size:           8
        .value_kind:     hidden_global_offset_y
      - .offset:         224
        .size:           8
        .value_kind:     hidden_global_offset_z
      - .offset:         232
        .size:           2
        .value_kind:     hidden_grid_dims
      - .offset:         256
        .size:           8
        .value_kind:     hidden_multigrid_sync_arg
      - .offset:         288
        .size:           4
        .value_kind:     hidden_dynamic_lds_size
    .group_segment_fixed_size: 0
    .kernarg_segment_align: 8
    .kernarg_segment_size: 424
    .language:       OpenCL C
    .language_version:
      - 2
      - 0
    .max_flat_workgroup_size: 512
    .name:           _Z14fwd_megakernel4Args
    .private_segment_fixed_size: 0
    .sgpr_count:     108
    .sgpr_spill_count: 141
    .symbol:         _Z14fwd_megakernel4Args.kd
    .uniform_work_group_size: 1
    .uses_dynamic_stack: false
    .vgpr_count:     256
    .vgpr_spill_count: 0
    .wavefront_size: 64
